# GEMM K-loops hand-rescheduled: B frags double-buffered, LDS-DMA issue interleaved with MFMAs, SGPR-base DMA addressing
# speedup vs baseline: 1.1157x; 1.0446x over previous
; __device__ __forceinline__ f32x4 mfma16(bf16x8 a, bf16x8 b, f32x4 c) { return __builtin_amdgcn_mfma_f32_16x16x32_bf16(a, b, c, 0, 0, 0); }
; template <class Epi>
; __device__ __forceinline__ void gemm_tile(const bf16_t* __restrict__ A, const bf16_t* __restrict__ Bt, int K, int row0, int col0, const Epi& epi, char* smem,
;                                           bool prefetched, bool nvalid, int nrow0, int ncol0) {
;     ...
;     for (int kt = 0; kt < nk; ++kt) {
;         const int cur = kt & 1;
;         if (kt + 1 < nk) GLDS_STAGE(cur ^ 1, pA, pB, kt + 1);
;         const char* cb = smem + cur * 2 * TILE_B;
; #pragma unroll
;         for (int ks = 0; ks < 2; ++ks) {
;             bf16x8 a[4], b[4];
; #pragma unroll
;             for (int m = 0; m < 4; ++m) a[m] = *(const bf16x8*)(cb + offA[m][ks]);
; #pragma unroll
;             for (int n = 0; n < 4; ++n) b[n] = *(const bf16x8*)(cb + offB[n][ks]);
; #pragma unroll
;             for (int m = 0; m < 4; ++m)
; #pragma unroll
;                 for (int n = 0; n < 4; ++n) acc[m][n] = mfma16(b[n], a[m], acc[m][n]);
;         }
;         asm volatile("s_waitcnt vmcnt(0)" ::: "memory");
;         __syncthreads();
;     }
.LBB0_154:
	v_readfirstlane_b32 s98, v64
	v_readfirstlane_b32 s99, v65
	v_readfirstlane_b32 s10, v66
	v_readfirstlane_b32 s100, v72
	v_readfirstlane_b32 s101, v73
	v_readfirstlane_b32 s13, v149
	s_nop 3
	s_sub_u32 s14, s10, s98
	s_and_b32 s98, s98, 0xffffff80
	s_and_b32 s100, s100, 0xffffff80
	s_nop 1
	v_subrev_u32_e32 v254, s98, v64
	v_subrev_u32_e32 v255, s100, v72
	s_add_i32 s12, s13, 0x8000
	s_mov_b32 m0, s12
	s_nop 1
	global_load_lds_dwordx4 v254, s[98:99]
	s_add_i32 m0, s12, 0x1000
	s_add_u32 s10, s98, s14
	s_addc_u32 s11, s99, 0
	global_load_lds_dwordx4 v254, s[10:11]
	s_add_i32 m0, s12, 0x2000
	s_add_u32 s10, s10, s14
	s_addc_u32 s11, s11, 0
	global_load_lds_dwordx4 v254, s[10:11]
	s_add_i32 m0, s12, 0x3000
	s_add_u32 s10, s10, s14
	s_addc_u32 s11, s11, 0
	global_load_lds_dwordx4 v254, s[10:11]
	s_add_u32 s98, s98, 0x80
	s_addc_u32 s99, s99, 0
	ds_read_b128 v[182:185], v139
	ds_read_b128 v[64:67], v142 offset:16384
	ds_read_b128 v[68:71], v142 offset:16896
	ds_read_b128 v[72:75], v142 offset:20480
	ds_read_b128 v[76:79], v142 offset:20992
	ds_read_b128 v[186:189], v139 offset:2048
	ds_read_b128 v[246:249], v139 offset:4096
	ds_read_b128 v[250:253], v139 offset:6144
.Lgk_loop_154:
	s_and_b32 s8, s5, 0x8000
	s_xor_b32 s9, s8, 0x8000
	s_add_i32 s12, s9, s13
	v_or_b32_e32 v173, s8, v141
	v_add_u32_e32 v190, s8, v140
	s_add_i32 m0, s12, 0x4000
	s_waitcnt lgkmcnt(6)
	v_mfma_f32_16x16x32_bf16 v[0:3], v[64:67], v[182:185], v[0:3]
	global_load_lds_dwordx4 v255, s[100:101]
	ds_read_b128 v[80:83], v173 offset:16384
	s_add_i32 m0, s12, 0x5000
	s_add_u32 s10, s100, s14
	s_addc_u32 s11, s101, 0
	s_waitcnt lgkmcnt(6)
	v_mfma_f32_16x16x32_bf16 v[4:7], v[68:71], v[182:185], v[4:7]
	global_load_lds_dwordx4 v255, s[10:11]
	ds_read_b128 v[128:131], v173 offset:16896
	s_add_i32 m0, s12, 0x6000
	s_add_u32 s10, s10, s14
	s_addc_u32 s11, s11, 0
	s_waitcnt lgkmcnt(6)
	v_mfma_f32_16x16x32_bf16 v[8:11], v[72:75], v[182:185], v[8:11]
	global_load_lds_dwordx4 v255, s[10:11]
	ds_read_b128 v[174:177], v173 offset:20480
	s_add_i32 m0, s12, 0x7000
	s_add_u32 s10, s10, s14
	s_addc_u32 s11, s11, 0
	s_waitcnt lgkmcnt(6)
	v_mfma_f32_16x16x32_bf16 v[12:15], v[76:79], v[182:185], v[12:15]
	global_load_lds_dwordx4 v255, s[10:11]
	ds_read_b128 v[178:181], v173 offset:20992
	ds_read_b128 v[182:185], v190
	s_add_u32 s100, s100, 0x80
	s_addc_u32 s101, s101, 0
	s_waitcnt lgkmcnt(7)
	v_mfma_f32_16x16x32_bf16 v[16:19], v[64:67], v[186:189], v[16:19]
	v_mfma_f32_16x16x32_bf16 v[20:23], v[68:71], v[186:189], v[20:23]
	v_mfma_f32_16x16x32_bf16 v[24:27], v[72:75], v[186:189], v[24:27]
	v_mfma_f32_16x16x32_bf16 v[28:31], v[76:79], v[186:189], v[28:31]
	ds_read_b128 v[186:189], v190 offset:2048
	s_waitcnt lgkmcnt(7)
	v_mfma_f32_16x16x32_bf16 v[32:35], v[64:67], v[246:249], v[32:35]
	v_mfma_f32_16x16x32_bf16 v[36:39], v[68:71], v[246:249], v[36:39]
	v_mfma_f32_16x16x32_bf16 v[40:43], v[72:75], v[246:249], v[40:43]
	v_mfma_f32_16x16x32_bf16 v[44:47], v[76:79], v[246:249], v[44:47]
	ds_read_b128 v[246:249], v190 offset:4096
	s_waitcnt lgkmcnt(7)
	v_mfma_f32_16x16x32_bf16 v[48:51], v[64:67], v[250:253], v[48:51]
	v_mfma_f32_16x16x32_bf16 v[52:55], v[68:71], v[250:253], v[52:55]
	v_mfma_f32_16x16x32_bf16 v[56:59], v[72:75], v[250:253], v[56:59]
	v_mfma_f32_16x16x32_bf16 v[60:63], v[76:79], v[250:253], v[60:63]
	ds_read_b128 v[250:253], v190 offset:6144
	s_waitcnt lgkmcnt(3)
	v_mfma_f32_16x16x32_bf16 v[0:3], v[80:83], v[182:185], v[0:3]
	v_mfma_f32_16x16x32_bf16 v[4:7], v[128:131], v[182:185], v[4:7]
	v_mfma_f32_16x16x32_bf16 v[8:11], v[174:177], v[182:185], v[8:11]
	v_mfma_f32_16x16x32_bf16 v[12:15], v[178:181], v[182:185], v[12:15]
	s_waitcnt lgkmcnt(2)
	v_mfma_f32_16x16x32_bf16 v[16:19], v[80:83], v[186:189], v[16:19]
	v_mfma_f32_16x16x32_bf16 v[20:23], v[128:131], v[186:189], v[20:23]
	v_mfma_f32_16x16x32_bf16 v[24:27], v[174:177], v[186:189], v[24:27]
	v_mfma_f32_16x16x32_bf16 v[28:31], v[178:181], v[186:189], v[28:31]
	s_waitcnt vmcnt(0)
	s_waitcnt lgkmcnt(0)
	s_barrier
	s_add_i32 s5, s5, 0x8000
	s_cmp_eq_u32 s5, 0x78000
	s_cbranch_scc1 .Lgk_tail_154
	v_or_b32_e32 v173, s9, v142
	v_add_u32_e32 v190, s9, v139
	s_add_i32 s12, s8, s13
	ds_read_b128 v[182:185], v190
	ds_read_b128 v[64:67], v173 offset:16384
	s_mov_b32 m0, s12
	v_mfma_f32_16x16x32_bf16 v[32:35], v[80:83], v[246:249], v[32:35]
	global_load_lds_dwordx4 v254, s[98:99]
	ds_read_b128 v[68:71], v173 offset:16896
	s_add_i32 m0, s12, 0x1000
	s_add_u32 s10, s98, s14
	s_addc_u32 s11, s99, 0
	v_mfma_f32_16x16x32_bf16 v[36:39], v[128:131], v[246:249], v[36:39]
	global_load_lds_dwordx4 v254, s[10:11]
	ds_read_b128 v[72:75], v173 offset:20480
	s_add_i32 m0, s12, 0x2000
	s_add_u32 s10, s10, s14
	s_addc_u32 s11, s11, 0
	v_mfma_f32_16x16x32_bf16 v[40:43], v[174:177], v[246:249], v[40:43]
	global_load_lds_dwordx4 v254, s[10:11]
	ds_read_b128 v[76:79], v173 offset:20992
	s_add_i32 m0, s12, 0x3000
	s_add_u32 s10, s10, s14
	s_addc_u32 s11, s11, 0
	v_mfma_f32_16x16x32_bf16 v[44:47], v[178:181], v[246:249], v[44:47]
	global_load_lds_dwordx4 v254, s[10:11]
	ds_read_b128 v[186:189], v190 offset:2048
	ds_read_b128 v[246:249], v190 offset:4096
	s_add_u32 s98, s98, 0x80
	s_addc_u32 s99, s99, 0
	v_mfma_f32_16x16x32_bf16 v[48:51], v[80:83], v[250:253], v[48:51]
	v_mfma_f32_16x16x32_bf16 v[52:55], v[128:131], v[250:253], v[52:55]
	v_mfma_f32_16x16x32_bf16 v[56:59], v[174:177], v[250:253], v[56:59]
	v_mfma_f32_16x16x32_bf16 v[60:63], v[178:181], v[250:253], v[60:63]
	ds_read_b128 v[250:253], v190 offset:6144
	s_branch .Lgk_loop_154
; __device__ __forceinline__ f32x4 mfma16(bf16x8 a, bf16x8 b, f32x4 c) { return __builtin_amdgcn_mfma_f32_16x16x32_bf16(a, b, c, 0, 0, 0); }
; template <class Epi>
; __device__ __forceinline__ void gemm_tile(const bf16_t* __restrict__ A, const bf16_t* __restrict__ Bt, int K, int row0, int col0, const Epi& epi, char* smem,
;                                           bool prefetched, bool nvalid, int nrow0, int ncol0) {
;     ...
;         const char* cb = smem + cur * 2 * TILE_B;
; #pragma unroll
;         for (int ks = 0; ks < 2; ++ks) {
;             bf16x8 a[4], b[4];
; #pragma unroll
;             for (int m = 0; m < 4; ++m) a[m] = *(const bf16x8*)(cb + offA[m][ks]);
; #pragma unroll
;             for (int n = 0; n < 4; ++n) b[n] = *(const bf16x8*)(cb + offB[n][ks]);
; #pragma unroll
;             for (int m = 0; m < 4; ++m)
; #pragma unroll
;                 for (int n = 0; n < 4; ++n) acc[m][n] = mfma16(b[n], a[m], acc[m][n]);
;         }
;         asm volatile("s_waitcnt vmcnt(0)" ::: "memory");
;         __syncthreads();
;     }
;     if (nvalid) { const bf16_t* qA = A + (size_t)nrow0 * K; const bf16_t* qB = Bt + (size_t)ncol0 * K; GLDS_STAGE(0, qA, qB, 0); }
; template <class Epi>
; __device__ __forceinline__ void gemm_phase(const bf16_t* A, const bf16_t* Bt, int M, int N, int K, const Epi& epi, char* smem) {
;     ...
;     for (int i = blockIdx.x; i < ntiles; i += G) {
;         const int j = i + G; const bool nv = j < ntiles;
;         gemm_tile(A, Bt, K, (i / nN) << 7, (i % nN) << 7, epi, smem, pre, nv, (j / nN) << 7, (j % nN) << 7);
.Lgk_tail_154:
	v_mfma_f32_16x16x32_bf16 v[32:35], v[80:83], v[246:249], v[32:35]
	v_mfma_f32_16x16x32_bf16 v[36:39], v[128:131], v[246:249], v[36:39]
	v_mfma_f32_16x16x32_bf16 v[40:43], v[174:177], v[246:249], v[40:43]
	v_mfma_f32_16x16x32_bf16 v[44:47], v[178:181], v[246:249], v[44:47]
	v_mfma_f32_16x16x32_bf16 v[48:51], v[80:83], v[250:253], v[48:51]
	v_mfma_f32_16x16x32_bf16 v[52:55], v[128:131], v[250:253], v[52:55]
	v_mfma_f32_16x16x32_bf16 v[56:59], v[174:177], v[250:253], v[56:59]
	v_mfma_f32_16x16x32_bf16 v[60:63], v[178:181], v[250:253], v[60:63]
	ds_read_b128 v[64:67], v142 offset:49152
	ds_read_b128 v[68:71], v139 offset:32768
	ds_read_b128 v[72:75], v142 offset:49664
	ds_read_b128 v[76:79], v142 offset:53248
	ds_read_b128 v[80:83], v142 offset:53760
	s_add_i32 s21, s21, s58
	s_waitcnt lgkmcnt(3)
	v_mfma_f32_16x16x32_bf16 v[0:3], v[64:67], v[68:71], v[0:3]
	s_cmpk_gt_i32 s21, 0x10ff
	s_cselect_b64 s[8:9], -1, 0
	s_cmpk_lt_i32 s21, 0x1100
	s_waitcnt lgkmcnt(2)
	v_mfma_f32_16x16x32_bf16 v[4:7], v[72:75], v[68:71], v[4:7]
	ds_read_b128 v[182:185], v141 offset:49152
	ds_read_b128 v[186:189], v141 offset:53760
	s_waitcnt lgkmcnt(3)
	v_mfma_f32_16x16x32_bf16 v[8:11], v[76:79], v[68:71], v[8:11]
	s_waitcnt lgkmcnt(2)
	v_mfma_f32_16x16x32_bf16 v[12:15], v[80:83], v[68:71], v[12:15]
	ds_read_b128 v[68:71], v139 offset:34816
	s_waitcnt lgkmcnt(0)
	v_mfma_f32_16x16x32_bf16 v[16:19], v[64:67], v[68:71], v[16:19]
	v_mfma_f32_16x16x32_bf16 v[20:23], v[72:75], v[68:71], v[20:23]
	v_mfma_f32_16x16x32_bf16 v[24:27], v[76:79], v[68:71], v[24:27]
	v_mfma_f32_16x16x32_bf16 v[28:31], v[80:83], v[68:71], v[28:31]
	ds_read_b128 v[68:71], v139 offset:36864
	s_waitcnt lgkmcnt(0)
	v_mfma_f32_16x16x32_bf16 v[128:131], v[64:67], v[68:71], v[32:35]
	s_nop 2
	ds_read_b128 v[32:35], v139 offset:38912
	v_mfma_f32_16x16x32_bf16 v[174:177], v[72:75], v[68:71], v[36:39]
	v_mfma_f32_16x16x32_bf16 v[178:181], v[76:79], v[68:71], v[40:43]
	v_mfma_f32_16x16x32_bf16 v[68:71], v[80:83], v[68:71], v[44:47]
	s_waitcnt lgkmcnt(0)
	v_mfma_f32_16x16x32_bf16 v[64:67], v[64:67], v[32:35], v[48:51]
	v_mfma_f32_16x16x32_bf16 v[72:75], v[72:75], v[32:35], v[52:55]
	v_mfma_f32_16x16x32_bf16 v[76:79], v[76:79], v[32:35], v[56:59]
	v_mfma_f32_16x16x32_bf16 v[80:83], v[80:83], v[32:35], v[60:63]
	ds_read_b128 v[32:35], v140 offset:32768
	s_waitcnt lgkmcnt(0)
	v_mfma_f32_16x16x32_bf16 v[56:59], v[182:185], v[32:35], v[0:3]
	s_nop 2
	ds_read_b128 v[0:3], v141 offset:49664
	s_waitcnt lgkmcnt(0)
	v_mfma_f32_16x16x32_bf16 v[60:63], v[0:3], v[32:35], v[4:7]
	s_nop 2
	ds_read_b128 v[4:7], v141 offset:53248
	s_waitcnt lgkmcnt(0)
	v_mfma_f32_16x16x32_bf16 v[48:51], v[4:7], v[32:35], v[8:11]
	s_nop 2
	ds_read_b128 v[8:11], v140 offset:34816
	v_mfma_f32_16x16x32_bf16 v[52:55], v[186:189], v[32:35], v[12:15]
	s_waitcnt lgkmcnt(0)
	v_mfma_f32_16x16x32_bf16 v[40:43], v[182:185], v[8:11], v[16:19]
	v_mfma_f32_16x16x32_bf16 v[44:47], v[0:3], v[8:11], v[20:23]
	v_mfma_f32_16x16x32_bf16 v[32:35], v[4:7], v[8:11], v[24:27]
	v_mfma_f32_16x16x32_bf16 v[36:39], v[186:189], v[8:11], v[28:31]
	ds_read_b128 v[8:11], v140 offset:36864
	s_waitcnt lgkmcnt(0)
	v_mfma_f32_16x16x32_bf16 v[20:23], v[186:189], v[8:11], v[68:71]
	s_nop 2
	ds_read_b128 v[68:71], v140 offset:38912
	s_waitcnt vmcnt(0)
	v_mfma_f32_16x16x32_bf16 v[24:27], v[182:185], v[8:11], v[128:131]
	s_waitcnt lgkmcnt(0)
	s_barrier
	v_mfma_f32_16x16x32_bf16 v[28:31], v[0:3], v[8:11], v[174:177]
	v_mfma_f32_16x16x32_bf16 v[16:19], v[4:7], v[8:11], v[178:181]
	v_mfma_f32_16x16x32_bf16 v[8:11], v[182:185], v[68:71], v[64:67]
	v_mfma_f32_16x16x32_bf16 v[12:15], v[0:3], v[68:71], v[72:75]
	v_mfma_f32_16x16x32_bf16 v[0:3], v[4:7], v[68:71], v[76:79]
	v_mfma_f32_16x16x32_bf16 v[4:7], v[186:189], v[68:71], v[80:83]
	s_cbranch_scc0 .LBB0_157
	s_mul_hi_i32 s0, s21, 0x78787879
	s_lshr_b32 s1, s0, 31
	s_ashr_i32 s0, s0, 3
	s_add_i32 s1, s0, s1
	s_lshl_b32 s0, s1, 7
	s_mul_i32 s1, s1, 17
	s_sub_i32 s1, s21, s1
	s_lshl_b32 s10, s1, 7
	s_ashr_i32 s1, s0, 31
	s_lshl_b64 s[0:1], s[0:1], 11
	v_readlane_b32 s5, v245, 53
	s_add_u32 s0, s5, s0
	v_readlane_b32 s5, v245, 54
	s_addc_u32 s1, s5, s1
	s_ashr_i32 s11, s10, 31
	s_lshl_b64 s[10:11], s[10:11], 11
	s_add_u32 s10, s56, s10
	v_readfirstlane_b32 s5, v149
	s_addc_u32 s11, s57, s11
	s_mov_b32 m0, s5
	v_readfirstlane_b32 s5, v159
	global_load_lds_dwordx4 v167, s[0:1]
	v_lshl_add_u64 v[64:65], v[84:85], 1, s[10:11]
	s_mov_b32 m0, s5
	v_readfirstlane_b32 s5, v160
	global_load_lds_dwordx4 v[64:65], off
	s_mov_b32 m0, s5
	v_readfirstlane_b32 s5, v161
	global_load_lds_dwordx4 v168, s[0:1]
	v_lshl_add_u64 v[64:65], v[86:87], 1, s[10:11]
	s_mov_b32 m0, s5
	v_readfirstlane_b32 s5, v162
	global_load_lds_dwordx4 v[64:65], off
	s_mov_b32 m0, s5
	v_readfirstlane_b32 s5, v163
	global_load_lds_dwordx4 v169, s[0:1]
	v_lshl_add_u64 v[64:65], v[88:89], 1, s[10:11]
	s_mov_b32 m0, s5
	v_readfirstlane_b32 s5, v164
	global_load_lds_dwordx4 v[64:65], off
	s_mov_b32 m0, s5
	v_lshl_add_u64 v[64:65], v[90:91], 1, s[10:11]
	global_load_lds_dwordx4 v170, s[0:1]
	v_readfirstlane_b32 s0, v165
	s_mov_b32 m0, s0
	s_nop 0
	global_load_lds_dwordx4 v[64:65], off

; __device__ __forceinline__ f32x4 mfma16(bf16x8 a, bf16x8 b, f32x4 c) { return __builtin_amdgcn_mfma_f32_16x16x32_bf16(a, b, c, 0, 0, 0); }
; template <class Epi>
; __device__ __forceinline__ void gemm_tile(const bf16_t* __restrict__ A, const bf16_t* __restrict__ Bt, int K, int row0, int col0, const Epi& epi, char* smem,
;                                           bool prefetched, bool nvalid, int nrow0, int ncol0) {
;     ...
;     for (int kt = 0; kt < nk; ++kt) {
;         const int cur = kt & 1;
;         if (kt + 1 < nk) GLDS_STAGE(cur ^ 1, pA, pB, kt + 1);
;         const char* cb = smem + cur * 2 * TILE_B;
; #pragma unroll
;         for (int ks = 0; ks < 2; ++ks) {
;             bf16x8 a[4], b[4];
; #pragma unroll
;             for (int m = 0; m < 4; ++m) a[m] = *(const bf16x8*)(cb + offA[m][ks]);
; #pragma unroll
;             for (int n = 0; n < 4; ++n) b[n] = *(const bf16x8*)(cb + offB[n][ks]);
; #pragma unroll
;             for (int m = 0; m < 4; ++m)
; #pragma unroll
;                 for (int n = 0; n < 4; ++n) acc[m][n] = mfma16(b[n], a[m], acc[m][n]);
;         }
;         asm volatile("s_waitcnt vmcnt(0)" ::: "memory");
;         __syncthreads();
;     }
.LBB0_197:
	v_readfirstlane_b32 s98, v106
	v_readfirstlane_b32 s99, v107
	v_readfirstlane_b32 s8, v108
	v_readfirstlane_b32 s100, v120
	v_readfirstlane_b32 s101, v121
	v_readfirstlane_b32 s11, v149
	s_nop 3
	s_sub_u32 s15, s8, s98
	s_and_b32 s98, s98, 0xffffff80
	s_and_b32 s100, s100, 0xffffff80
	s_nop 1
	v_subrev_u32_e32 v254, s98, v106
	v_subrev_u32_e32 v255, s100, v120
	s_add_i32 s10, s11, 0x8000
	s_mov_b32 m0, s10
	s_nop 1
	global_load_lds_dwordx4 v254, s[98:99]
	s_add_i32 m0, s10, 0x1000
	s_add_u32 s8, s98, s15
	s_addc_u32 s9, s99, 0
	global_load_lds_dwordx4 v254, s[8:9]
	s_add_i32 m0, s10, 0x2000
	s_add_u32 s8, s8, s15
	s_addc_u32 s9, s9, 0
	global_load_lds_dwordx4 v254, s[8:9]
	s_add_i32 m0, s10, 0x3000
	s_add_u32 s8, s8, s15
	s_addc_u32 s9, s9, 0
	global_load_lds_dwordx4 v254, s[8:9]
	s_add_u32 s98, s98, 0x80
	s_addc_u32 s99, s99, 0
	ds_read_b128 v[188:191], v117
	ds_read_b128 v[106:109], v130 offset:16384
	ds_read_b128 v[118:121], v130 offset:16896
	ds_read_b128 v[122:125], v130 offset:20480
	ds_read_b128 v[168:171], v130 offset:20992
	ds_read_b128 v[192:195], v117 offset:2048
	ds_read_b128 v[196:199], v117 offset:4096
	ds_read_b128 v[246:249], v117 offset:6144
.Lgk_loop_197:
	s_and_b32 s6, s1, 0x8000
	s_xor_b32 s7, s6, 0x8000
	s_add_i32 s10, s7, s11
	v_or_b32_e32 v167, s6, v129
	v_add_u32_e32 v250, s6, v128
	s_add_i32 m0, s10, 0x4000
	s_waitcnt lgkmcnt(6)
	v_mfma_f32_16x16x32_bf16 v[0:3], v[106:109], v[188:191], v[0:3]
	global_load_lds_dwordx4 v255, s[100:101]
	ds_read_b128 v[172:175], v167 offset:16384
	s_add_i32 m0, s10, 0x5000
	s_add_u32 s8, s100, s15
	s_addc_u32 s9, s101, 0
	s_waitcnt lgkmcnt(6)
	v_mfma_f32_16x16x32_bf16 v[4:7], v[118:121], v[188:191], v[4:7]
	global_load_lds_dwordx4 v255, s[8:9]
	ds_read_b128 v[176:179], v167 offset:16896
	s_add_i32 m0, s10, 0x6000
	s_add_u32 s8, s8, s15
	s_addc_u32 s9, s9, 0
	s_waitcnt lgkmcnt(6)
	v_mfma_f32_16x16x32_bf16 v[8:11], v[122:125], v[188:191], v[8:11]
	global_load_lds_dwordx4 v255, s[8:9]
	ds_read_b128 v[180:183], v167 offset:20480
	s_add_i32 m0, s10, 0x7000
	s_add_u32 s8, s8, s15
	s_addc_u32 s9, s9, 0
	s_waitcnt lgkmcnt(6)
	v_mfma_f32_16x16x32_bf16 v[12:15], v[168:171], v[188:191], v[12:15]
	global_load_lds_dwordx4 v255, s[8:9]
	ds_read_b128 v[184:187], v167 offset:20992
	ds_read_b128 v[188:191], v250
	s_add_u32 s100, s100, 0x80
	s_addc_u32 s101, s101, 0
	s_waitcnt lgkmcnt(7)
	v_mfma_f32_16x16x32_bf16 v[16:19], v[106:109], v[192:195], v[16:19]
	v_mfma_f32_16x16x32_bf16 v[20:23], v[118:121], v[192:195], v[20:23]
	v_mfma_f32_16x16x32_bf16 v[24:27], v[122:125], v[192:195], v[24:27]
	v_mfma_f32_16x16x32_bf16 v[28:31], v[168:171], v[192:195], v[28:31]
	ds_read_b128 v[192:195], v250 offset:2048
	s_waitcnt lgkmcnt(7)
	v_mfma_f32_16x16x32_bf16 v[32:35], v[106:109], v[196:199], v[32:35]
	v_mfma_f32_16x16x32_bf16 v[36:39], v[118:121], v[196:199], v[36:39]
	v_mfma_f32_16x16x32_bf16 v[40:43], v[122:125], v[196:199], v[40:43]
	v_mfma_f32_16x16x32_bf16 v[44:47], v[168:171], v[196:199], v[44:47]
	ds_read_b128 v[196:199], v250 offset:4096
	s_waitcnt lgkmcnt(7)
	v_mfma_f32_16x16x32_bf16 v[48:51], v[106:109], v[246:249], v[48:51]
	v_mfma_f32_16x16x32_bf16 v[52:55], v[118:121], v[246:249], v[52:55]
	v_mfma_f32_16x16x32_bf16 v[56:59], v[122:125], v[246:249], v[56:59]
	v_mfma_f32_16x16x32_bf16 v[60:63], v[168:171], v[246:249], v[60:63]
	ds_read_b128 v[246:249], v250 offset:6144
	s_waitcnt lgkmcnt(3)
	v_mfma_f32_16x16x32_bf16 v[0:3], v[172:175], v[188:191], v[0:3]
	v_mfma_f32_16x16x32_bf16 v[4:7], v[176:179], v[188:191], v[4:7]
	v_mfma_f32_16x16x32_bf16 v[8:11], v[180:183], v[188:191], v[8:11]
	v_mfma_f32_16x16x32_bf16 v[12:15], v[184:187], v[188:191], v[12:15]
	s_waitcnt lgkmcnt(2)
	v_mfma_f32_16x16x32_bf16 v[16:19], v[172:175], v[192:195], v[16:19]
	v_mfma_f32_16x16x32_bf16 v[20:23], v[176:179], v[192:195], v[20:23]
	v_mfma_f32_16x16x32_bf16 v[24:27], v[180:183], v[192:195], v[24:27]
	v_mfma_f32_16x16x32_bf16 v[28:31], v[184:187], v[192:195], v[28:31]
	s_waitcnt vmcnt(0)
	s_waitcnt lgkmcnt(0)
	s_barrier
	s_add_i32 s1, s1, 0x8000
	s_cmp_eq_u32 s1, 0x78000
	s_cbranch_scc1 .Lgk_tail_197
	v_or_b32_e32 v167, s7, v130
	v_add_u32_e32 v250, s7, v117
	s_add_i32 s10, s6, s11
	ds_read_b128 v[188:191], v250
	ds_read_b128 v[106:109], v167 offset:16384
	s_mov_b32 m0, s10
	v_mfma_f32_16x16x32_bf16 v[32:35], v[172:175], v[196:199], v[32:35]
	global_load_lds_dwordx4 v254, s[98:99]
	ds_read_b128 v[118:121], v167 offset:16896
	s_add_i32 m0, s10, 0x1000
	s_add_u32 s8, s98, s15
	s_addc_u32 s9, s99, 0
	v_mfma_f32_16x16x32_bf16 v[36:39], v[176:179], v[196:199], v[36:39]
	global_load_lds_dwordx4 v254, s[8:9]
	ds_read_b128 v[122:125], v167 offset:20480
	s_add_i32 m0, s10, 0x2000
	s_add_u32 s8, s8, s15
	s_addc_u32 s9, s9, 0
	v_mfma_f32_16x16x32_bf16 v[40:43], v[180:183], v[196:199], v[40:43]
	global_load_lds_dwordx4 v254, s[8:9]
	ds_read_b128 v[168:171], v167 offset:20992
	s_add_i32 m0, s10, 0x3000
	s_add_u32 s8, s8, s15
	s_addc_u32 s9, s9, 0
	v_mfma_f32_16x16x32_bf16 v[44:47], v[184:187], v[196:199], v[44:47]
	global_load_lds_dwordx4 v254, s[8:9]
	ds_read_b128 v[192:195], v250 offset:2048
	ds_read_b128 v[196:199], v250 offset:4096
	s_add_u32 s98, s98, 0x80
	s_addc_u32 s99, s99, 0
	v_mfma_f32_16x16x32_bf16 v[48:51], v[172:175], v[246:249], v[48:51]
	v_mfma_f32_16x16x32_bf16 v[52:55], v[176:179], v[246:249], v[52:55]
	v_mfma_f32_16x16x32_bf16 v[56:59], v[180:183], v[246:249], v[56:59]
	v_mfma_f32_16x16x32_bf16 v[60:63], v[184:187], v[246:249], v[60:63]
	ds_read_b128 v[246:249], v250 offset:6144
	s_branch .Lgk_loop_197
; __device__ __forceinline__ f32x4 mfma16(bf16x8 a, bf16x8 b, f32x4 c) { return __builtin_amdgcn_mfma_f32_16x16x32_bf16(a, b, c, 0, 0, 0); }
; template <class Epi>
; __device__ __forceinline__ void gemm_tile(const bf16_t* __restrict__ A, const bf16_t* __restrict__ Bt, int K, int row0, int col0, const Epi& epi, char* smem,
;                                           bool prefetched, bool nvalid, int nrow0, int ncol0) {
;     ...
;         const char* cb = smem + cur * 2 * TILE_B;
; #pragma unroll
;         for (int ks = 0; ks < 2; ++ks) {
;             bf16x8 a[4], b[4];
; #pragma unroll
;             for (int m = 0; m < 4; ++m) a[m] = *(const bf16x8*)(cb + offA[m][ks]);
; #pragma unroll
;             for (int n = 0; n < 4; ++n) b[n] = *(const bf16x8*)(cb + offB[n][ks]);
; #pragma unroll
;             for (int m = 0; m < 4; ++m)
; #pragma unroll
;                 for (int n = 0; n < 4; ++n) acc[m][n] = mfma16(b[n], a[m], acc[m][n]);
;         }
;         asm volatile("s_waitcnt vmcnt(0)" ::: "memory");
;         __syncthreads();
;     }
;     if (nvalid) { const bf16_t* qA = A + (size_t)nrow0 * K; const bf16_t* qB = Bt + (size_t)ncol0 * K; GLDS_STAGE(0, qA, qB, 0); }
; template <class E1, class E2>
; __device__ __forceinline__ void gemm_phase2(const bf16_t* A1, const bf16_t* B1, int M1, int N1, const E1& e1,
;                                             const bf16_t* A2, const bf16_t* B2, int M2, int N2, const E2& e2, int K, char* smem) {
;     ...
;     for (int i = (blockIdx.x + (G >> 1)) % G; i < nt2; i += G) {
;         const int j = i + G; const bool nv = j < nt2;
;         gemm_tile(A2, B2, K, (i % nM2) << 7, (i / nM2) << 7, e2, smem, pre, nv, (j % nM2) << 7, (j / nM2) << 7);
.Lgk_tail_197:
	v_mfma_f32_16x16x32_bf16 v[32:35], v[172:175], v[196:199], v[32:35]
	v_mfma_f32_16x16x32_bf16 v[36:39], v[176:179], v[196:199], v[36:39]
	v_mfma_f32_16x16x32_bf16 v[40:43], v[180:183], v[196:199], v[40:43]
	v_mfma_f32_16x16x32_bf16 v[44:47], v[184:187], v[196:199], v[44:47]
	v_mfma_f32_16x16x32_bf16 v[48:51], v[172:175], v[246:249], v[48:51]
	v_mfma_f32_16x16x32_bf16 v[52:55], v[176:179], v[246:249], v[52:55]
	v_mfma_f32_16x16x32_bf16 v[56:59], v[180:183], v[246:249], v[56:59]
	v_mfma_f32_16x16x32_bf16 v[60:63], v[184:187], v[246:249], v[60:63]
	ds_read_b128 v[106:109], v130 offset:49152
	ds_read_b128 v[118:121], v117 offset:32768
	ds_read_b128 v[122:125], v130 offset:49664
	ds_read_b128 v[168:171], v130 offset:53248
	ds_read_b128 v[172:175], v130 offset:53760
	s_add_i32 s14, s14, s58
	s_waitcnt lgkmcnt(3)
	v_mfma_f32_16x16x32_bf16 v[0:3], v[106:109], v[118:121], v[0:3]
	s_cmpk_gt_i32 s14, 0x3ff
	s_cselect_b64 s[4:5], -1, 0
	s_cmpk_lt_i32 s14, 0x400
	s_waitcnt lgkmcnt(2)
	v_mfma_f32_16x16x32_bf16 v[4:7], v[122:125], v[118:121], v[4:7]
	ds_read_b128 v[188:191], v129 offset:49152
	ds_read_b128 v[192:195], v129 offset:53248
	ds_read_b128 v[196:199], v129 offset:53760
	s_waitcnt lgkmcnt(4)
	v_mfma_f32_16x16x32_bf16 v[8:11], v[168:171], v[118:121], v[8:11]
	s_waitcnt lgkmcnt(3)
	v_mfma_f32_16x16x32_bf16 v[12:15], v[172:175], v[118:121], v[12:15]
	ds_read_b128 v[118:121], v117 offset:34816
	s_waitcnt lgkmcnt(0)
	v_mfma_f32_16x16x32_bf16 v[16:19], v[106:109], v[118:121], v[16:19]
	v_mfma_f32_16x16x32_bf16 v[20:23], v[122:125], v[118:121], v[20:23]
	v_mfma_f32_16x16x32_bf16 v[24:27], v[168:171], v[118:121], v[24:27]
	v_mfma_f32_16x16x32_bf16 v[28:31], v[172:175], v[118:121], v[28:31]
	ds_read_b128 v[118:121], v117 offset:36864
	s_waitcnt lgkmcnt(0)
	v_mfma_f32_16x16x32_bf16 v[176:179], v[106:109], v[118:121], v[32:35]
	s_nop 2
	ds_read_b128 v[32:35], v117 offset:38912
	v_mfma_f32_16x16x32_bf16 v[180:183], v[122:125], v[118:121], v[36:39]
	v_mfma_f32_16x16x32_bf16 v[184:187], v[168:171], v[118:121], v[40:43]
	v_mfma_f32_16x16x32_bf16 v[118:121], v[172:175], v[118:121], v[44:47]
	s_waitcnt lgkmcnt(0)
	v_mfma_f32_16x16x32_bf16 v[106:109], v[106:109], v[32:35], v[48:51]
	v_mfma_f32_16x16x32_bf16 v[122:125], v[122:125], v[32:35], v[52:55]
	v_mfma_f32_16x16x32_bf16 v[168:171], v[168:171], v[32:35], v[56:59]
	v_mfma_f32_16x16x32_bf16 v[172:175], v[172:175], v[32:35], v[60:63]
	ds_read_b128 v[32:35], v128 offset:32768
	s_waitcnt lgkmcnt(0)
	v_mfma_f32_16x16x32_bf16 v[56:59], v[188:191], v[32:35], v[0:3]
	s_nop 2
	ds_read_b128 v[0:3], v129 offset:49664
	s_waitcnt lgkmcnt(0)
	v_mfma_f32_16x16x32_bf16 v[60:63], v[0:3], v[32:35], v[4:7]
	s_nop 2
	ds_read_b128 v[4:7], v128 offset:34816
	v_mfma_f32_16x16x32_bf16 v[48:51], v[192:195], v[32:35], v[8:11]
	v_mfma_f32_16x16x32_bf16 v[52:55], v[196:199], v[32:35], v[12:15]
	s_nop 2
	ds_read_b128 v[12:15], v128 offset:38912
	s_waitcnt lgkmcnt(1)
	v_mfma_f32_16x16x32_bf16 v[44:47], v[188:191], v[4:7], v[16:19]
	v_mfma_f32_16x16x32_bf16 v[40:43], v[0:3], v[4:7], v[20:23]
	v_mfma_f32_16x16x32_bf16 v[36:39], v[192:195], v[4:7], v[24:27]
	v_mfma_f32_16x16x32_bf16 v[32:35], v[196:199], v[4:7], v[28:31]
	ds_read_b128 v[4:7], v128 offset:36864
	s_waitcnt vmcnt(0)
	s_waitcnt lgkmcnt(0)
	v_mfma_f32_16x16x32_bf16 v[28:31], v[188:191], v[4:7], v[176:179]
	s_barrier
	v_mfma_f32_16x16x32_bf16 v[24:27], v[0:3], v[4:7], v[180:183]
	v_mfma_f32_16x16x32_bf16 v[20:23], v[192:195], v[4:7], v[184:187]
	v_mfma_f32_16x16x32_bf16 v[16:19], v[196:199], v[4:7], v[118:121]
	v_mfma_f32_16x16x32_bf16 v[4:7], v[188:191], v[12:15], v[106:109]
	v_mfma_f32_16x16x32_bf16 v[8:11], v[0:3], v[12:15], v[122:125]
	v_mfma_f32_16x16x32_bf16 v[0:3], v[192:195], v[12:15], v[168:171]
	v_mfma_f32_16x16x32_bf16 v[12:15], v[196:199], v[12:15], v[172:175]
	s_cbranch_scc0 .LBB0_191
	s_ashr_i32 s1, s14, 31
	s_lshr_b32 s1, s1, 30
	s_add_i32 s1, s14, s1
	s_and_b32 s6, s1, 0x1fffffc
	s_sub_i32 s6, s14, s6
	s_lshl_b32 s6, s6, 7
	s_lshl_b32 s1, s1, 5
	s_ashr_i32 s7, s6, 31
	s_and_b32 s8, s1, 0xffffff80
	s_lshl_b64 s[6:7], s[6:7], 11
	s_add_u32 s6, s12, s6
	s_addc_u32 s7, s13, s7
	s_ashr_i32 s9, s8, 31
	s_lshl_b64 s[8:9], s[8:9], 11
	v_readlane_b32 s1, v245, 53
	s_add_u32 s8, s1, s8
	v_readlane_b32 s1, v245, 54
	s_addc_u32 s9, s1, s9
	v_readfirstlane_b32 s1, v149
	s_mov_b32 m0, s1
	v_readfirstlane_b32 s1, v131
	global_load_lds_dwordx4 v163, s[6:7]
	v_lshl_add_u64 v[106:107], v[64:65], 1, s[8:9]
	s_mov_b32 m0, s1
	v_readfirstlane_b32 s1, v139
	global_load_lds_dwordx4 v[106:107], off
	s_mov_b32 m0, s1
	v_readfirstlane_b32 s1, v140
	global_load_lds_dwordx4 v164, s[6:7]
	v_lshl_add_u64 v[106:107], v[66:67], 1, s[8:9]
	s_mov_b32 m0, s1
	v_readfirstlane_b32 s1, v141
	global_load_lds_dwordx4 v[106:107], off
	s_mov_b32 m0, s1
	v_readfirstlane_b32 s1, v142
	global_load_lds_dwordx4 v165, s[6:7]
	v_lshl_add_u64 v[106:107], v[68:69], 1, s[8:9]
	s_mov_b32 m0, s1
	v_readfirstlane_b32 s1, v143
	global_load_lds_dwordx4 v[106:107], off
	s_mov_b32 m0, s1
	v_readfirstlane_b32 s1, v144
	global_load_lds_dwordx4 v166, s[6:7]
	v_lshl_add_u64 v[106:107], v[70:71], 1, s[8:9]
	s_mov_b32 m0, s1
	s_nop 0
	global_load_lds_dwordx4 v[106:107], off
	s_branch .LBB0_191

; __device__ __forceinline__ f32x4 mfma16(bf16x8 a, bf16x8 b, f32x4 c) { return __builtin_amdgcn_mfma_f32_16x16x32_bf16(a, b, c, 0, 0, 0); }
; template <int KW, int VD, bool SEL> ...
;     ...
;         if (tiles) { jn = __ffsll((long long)tiles) - 1; tiles &= tiles - 1; FL_ISSUE(cur ^ 1, jn); }
;         const char* sK = smem + cur * BUFB;
;         const char* sV = smem + cur * BUFB + KB;
;         f32x4 s[2][4];
;         const float mref0 = (mrow[0] < -1e29f) ? 0.f : mrow[0], mref1 = (mrow[1] < -1e29f) ? 0.f : mrow[1];
;         const float ci0 = (SEL && !((((const u64*)(smem + 69632))[fr] >> j) & 1ull)) ? -1e30f : -mref0;
;         const float ci1 = (SEL && !((((const u64*)(smem + 69632))[16 + fr] >> j) & 1ull)) ? -1e30f : -mref1;
;         const f32x4 cinit0 = (f32x4){ci0, ci0, ci0, ci0}, cinit1 = (f32x4){ci1, ci1, ci1, ci1};
; #pragma unroll
;         for (int tt = 0; tt < 4; ++tt) {
;             const int kr = 32 * (tt >> 1) + (fr >> 2) * 8 + (tt & 1) * 4 + (fr & 3);
;             const bf16x8 kf0 = *(const bf16x8*)(sK + kr * KROWB + (((kcol >> 3) + fq) ^ kswz) * 16);
;             const bf16x8 kf1 = *(const bf16x8*)(sK + kr * KROWB + (((kcol >> 3) + 4 + fq) ^ kswz) * 16);
;             s[0][tt] = mfma16(kf0, qf[0][0], cinit0);
;             s[1][tt] = mfma16(kf0, qf[1][0], cinit1);
;             s[0][tt] = mfma16(kf1, qf[0][1], s[0][tt]);
;             s[1][tt] = mfma16(kf1, qf[1][1], s[1][tt]);
;         }
;         const bool pm = (j * 64 + 63 > tmin) || (j * 64 <= lomax);
.LBB0_373:
	v_add_u32_e32 v72, s12, v129
	ds_read2_b64 v[52:55], v124 offset1:16
	v_add_u32_e32 v141, v72, v125
	ds_read_b128 v[56:59], v141
	s_lshl_b64 s[0:1], 1, s4
	v_cmp_ngt_f32_e32 vcc, s16, v130
	s_waitcnt lgkmcnt(0)
	v_and_b32_e32 v107, s1, v53
	v_and_b32_e32 v106, s0, v52
	v_and_b32_e32 v3, s1, v55
	v_and_b32_e32 v2, s0, v54
	ds_read_b128 v[52:55], v141 offset:512
	v_cndmask_b32_e32 v171, 0, v130, vcc
	v_cmp_ngt_f32_e32 vcc, s16, v0
	v_add_u32_e32 v166, v72, v126
	ds_read_b128 v[72:75], v166
	ds_read_b128 v[76:79], v166 offset:512
	v_cndmask_b32_e32 v131, 0, v0, vcc
	v_cmp_ne_u64_e32 vcc, 0, v[106:107]
	s_lshl_b32 s13, s4, 6
	s_or_b32 s0, s13, 63
	v_cndmask_b32_e64 v64, v85, -v171, vcc
	v_mov_b32_e32 v65, v64
	v_mov_b32_e32 v66, v64
	v_mov_b32_e32 v67, v64
	v_cmp_ne_u64_e32 vcc, 0, v[2:3]
	s_cmp_le_u32 s0, s21
	v_mfma_f32_16x16x32_bf16 v[60:63], v[56:59], v[4:7], v[64:67]
	v_cndmask_b32_e64 v68, v85, -v131, vcc
	v_mov_b32_e32 v69, v68
	v_mov_b32_e32 v70, v68
	v_mov_b32_e32 v71, v68
	s_waitcnt lgkmcnt(1)
	v_mfma_f32_16x16x32_bf16 v[80:83], v[72:75], v[8:11], v[60:63]
	s_cselect_b64 s[4:5], -1, 0
	s_cmp_gt_u32 s0, s21
	s_mov_b64 s[0:1], -1
	v_mfma_f32_16x16x32_bf16 v[56:59], v[56:59], v[12:15], v[68:71]
	v_mfma_f32_16x16x32_bf16 v[60:63], v[52:55], v[4:7], v[64:67]
	v_mfma_f32_16x16x32_bf16 v[52:55], v[52:55], v[12:15], v[68:71]
	v_mfma_f32_16x16x32_bf16 v[56:59], v[72:75], v[16:19], v[56:59]
	s_waitcnt lgkmcnt(0)
	v_mfma_f32_16x16x32_bf16 v[72:75], v[76:79], v[8:11], v[60:63]
	v_mfma_f32_16x16x32_bf16 v[60:63], v[76:79], v[16:19], v[52:55]
	s_nop 3
	ds_read_b128 v[52:55], v141 offset:4096
	ds_read_b128 v[142:145], v141 offset:4608
	ds_read_b128 v[162:165], v166 offset:4096
	ds_read_b128 v[166:169], v166 offset:4608
	s_waitcnt lgkmcnt(3)
	v_mfma_f32_16x16x32_bf16 v[76:79], v[52:55], v[4:7], v[64:67]
	v_mfma_f32_16x16x32_bf16 v[52:55], v[52:55], v[12:15], v[68:71]
	s_waitcnt lgkmcnt(2)
	v_mfma_f32_16x16x32_bf16 v[64:67], v[142:145], v[4:7], v[64:67]
	v_mfma_f32_16x16x32_bf16 v[142:145], v[142:145], v[12:15], v[68:71]
	s_waitcnt lgkmcnt(1)
	v_mfma_f32_16x16x32_bf16 v[76:79], v[162:165], v[8:11], v[76:79]
	v_mfma_f32_16x16x32_bf16 v[52:55], v[162:165], v[16:19], v[52:55]
	s_waitcnt lgkmcnt(0)
	v_mfma_f32_16x16x32_bf16 v[68:71], v[166:169], v[8:11], v[64:67]
	v_mfma_f32_16x16x32_bf16 v[64:67], v[166:169], v[16:19], v[142:145]
	s_cbranch_scc1 .LBB0_375
	s_mov_b64 s[0:1], 0

; __device__ __forceinline__ f32x4 mfma16(bf16x8 a, bf16x8 b, f32x4 c) { return __builtin_amdgcn_mfma_f32_16x16x32_bf16(a, b, c, 0, 0, 0); }
; template <int KW, int VD, bool SEL> ...
;     ...
;     while (true) {
;         int jn = -1;
;         if (tiles) { jn = __ffsll((long long)tiles) - 1; tiles &= tiles - 1; FL_ISSUE(cur ^ 1, jn); }
;         const char* sK = smem + cur * BUFB;
;         const char* sV = smem + cur * BUFB + KB;
;         f32x4 s[2][4];
;         const float mref0 = (mrow[0] < -1e29f) ? 0.f : mrow[0], mref1 = (mrow[1] < -1e29f) ? 0.f : mrow[1];
;         const float ci0 = (SEL && !((((const u64*)(smem + 69632))[fr] >> j) & 1ull)) ? -1e30f : -mref0;
;         const float ci1 = (SEL && !((((const u64*)(smem + 69632))[16 + fr] >> j) & 1ull)) ? -1e30f : -mref1;
;         const f32x4 cinit0 = (f32x4){ci0, ci0, ci0, ci0}, cinit1 = (f32x4){ci1, ci1, ci1, ci1};
; #pragma unroll
;         for (int tt = 0; tt < 4; ++tt) {
;             const int kr = 32 * (tt >> 1) + (fr >> 2) * 8 + (tt & 1) * 4 + (fr & 3);
;             const bf16x8 kf0 = *(const bf16x8*)(sK + kr * KROWB + (((kcol >> 3) + fq) ^ kswz) * 16);
;             const bf16x8 kf1 = *(const bf16x8*)(sK + kr * KROWB + (((kcol >> 3) + 4 + fq) ^ kswz) * 16);
;             s[0][tt] = mfma16(kf0, qf[0][0], cinit0);
;             s[1][tt] = mfma16(kf0, qf[1][0], cinit1);
;             s[0][tt] = mfma16(kf1, qf[0][1], s[0][tt]);
;             s[1][tt] = mfma16(kf1, qf[1][1], s[1][tt]);
;         }
;         const bool pm = (j * 64 + 63 > tmin) || (j * 64 <= lomax);
.LBB0_394:
	v_add_u32_e32 v3, s13, v127
	v_add_u32_e32 v129, v3, v123
	ds_read_b128 v[52:55], v129
	ds_read_b128 v[60:63], v129 offset:512
	v_cmp_ngt_f32_e32 vcc, s16, v0
	v_add_u32_e32 v3, v3, v124
	ds_read_b128 v[68:71], v3
	ds_read_b128 v[72:75], v3 offset:512
	v_cndmask_b32_e32 v167, 0, v0, vcc
	v_cmp_ngt_f32_e32 vcc, s16, v128
	v_xor_b32_e32 v64, 0x80000000, v167
	v_mov_b32_e32 v65, v64
	v_cndmask_b32_e32 v2, 0, v128, vcc
	v_xor_b32_e32 v76, 0x80000000, v2
	v_mov_b32_e32 v66, v64
	v_mov_b32_e32 v67, v64
	v_mov_b32_e32 v77, v76
	v_mov_b32_e32 v78, v76
	v_mov_b32_e32 v79, v76
	s_waitcnt lgkmcnt(0)
	v_mfma_f32_16x16x32_bf16 v[56:59], v[52:55], v[4:7], v[64:67]
	s_lshl_b32 s14, s4, 6
	s_or_b32 s0, s14, 63
	s_cmp_gt_u32 s0, s21
	v_mfma_f32_16x16x32_bf16 v[52:55], v[52:55], v[12:15], v[76:79]
	s_cselect_b64 s[0:1], -1, 0
	s_cmp_le_i32 s14, s10
	s_cselect_b64 s[4:5], -1, 0
	v_mfma_f32_16x16x32_bf16 v[80:83], v[68:71], v[8:11], v[56:59]
	s_or_b64 s[4:5], s[4:5], s[0:1]
	s_mov_b64 s[0:1], -1
	s_and_b64 vcc, exec, s[4:5]
	v_mfma_f32_16x16x32_bf16 v[56:59], v[68:71], v[16:19], v[52:55]
	v_mfma_f32_16x16x32_bf16 v[52:55], v[60:63], v[4:7], v[64:67]
	v_mfma_f32_16x16x32_bf16 v[68:71], v[72:75], v[8:11], v[52:55]
	s_nop 6
	ds_read_b128 v[52:55], v129 offset:4096
	ds_read_b128 v[142:145], v129 offset:4608
	ds_read_b128 v[162:165], v3 offset:4096
	ds_read_b128 v[168:171], v3 offset:4608
	v_mfma_f32_16x16x32_bf16 v[60:63], v[60:63], v[12:15], v[76:79]
	v_mfma_f32_16x16x32_bf16 v[60:63], v[72:75], v[16:19], v[60:63]
	s_waitcnt lgkmcnt(3)
	v_mfma_f32_16x16x32_bf16 v[72:75], v[52:55], v[4:7], v[64:67]
	v_mfma_f32_16x16x32_bf16 v[52:55], v[52:55], v[12:15], v[76:79]
	s_waitcnt lgkmcnt(2)
	v_mfma_f32_16x16x32_bf16 v[64:67], v[142:145], v[4:7], v[64:67]
	v_mfma_f32_16x16x32_bf16 v[142:145], v[142:145], v[12:15], v[76:79]
	s_waitcnt lgkmcnt(1)
	v_mfma_f32_16x16x32_bf16 v[72:75], v[162:165], v[8:11], v[72:75]
	v_mfma_f32_16x16x32_bf16 v[52:55], v[162:165], v[16:19], v[52:55]
	s_waitcnt lgkmcnt(0)
	v_mfma_f32_16x16x32_bf16 v[76:79], v[168:171], v[8:11], v[64:67]
	v_mfma_f32_16x16x32_bf16 v[64:67], v[168:171], v[16:19], v[142:145]
	s_cbranch_vccnz .LBB0_396
	s_mov_b64 s[0:1], 0

; __device__ __forceinline__ f32x4 mfma16(bf16x8 a, bf16x8 b, f32x4 c) { return __builtin_amdgcn_mfma_f32_16x16x32_bf16(a, b, c, 0, 0, 0); }
; template <class Epi>
; __device__ __forceinline__ void gemm_tile(const bf16_t* __restrict__ A, const bf16_t* __restrict__ Bt, int K, int row0, int col0, const Epi& epi, char* smem,
;                                           bool prefetched, bool nvalid, int nrow0, int ncol0) {
;     ...
;     for (int kt = 0; kt < nk; ++kt) {
;         const int cur = kt & 1;
;         if (kt + 1 < nk) GLDS_STAGE(cur ^ 1, pA, pB, kt + 1);
;         const char* cb = smem + cur * 2 * TILE_B;
; #pragma unroll
;         for (int ks = 0; ks < 2; ++ks) {
;             bf16x8 a[4], b[4];
; #pragma unroll
;             for (int m = 0; m < 4; ++m) a[m] = *(const bf16x8*)(cb + offA[m][ks]);
; #pragma unroll
;             for (int n = 0; n < 4; ++n) b[n] = *(const bf16x8*)(cb + offB[n][ks]);
; #pragma unroll
;             for (int m = 0; m < 4; ++m)
; #pragma unroll
;                 for (int n = 0; n < 4; ++n) acc[m][n] = mfma16(b[n], a[m], acc[m][n]);
;         }
;         asm volatile("s_waitcnt vmcnt(0)" ::: "memory");
;         __syncthreads();
;     }
.LBB0_460:
	v_readfirstlane_b32 s98, v94
	v_readfirstlane_b32 s99, v95
	v_readfirstlane_b32 s8, v96
	v_readfirstlane_b32 s100, v102
	v_readfirstlane_b32 s101, v103
	v_readfirstlane_b32 s12, v149
	s_nop 3
	s_sub_u32 s13, s8, s98
	s_and_b32 s98, s98, 0xffffff80
	s_and_b32 s100, s100, 0xffffff80
	s_nop 1
	v_subrev_u32_e32 v254, s98, v94
	v_subrev_u32_e32 v255, s100, v102
	s_add_i32 s11, s12, 0x8000
	s_mov_b32 m0, s11
	s_nop 1
	global_load_lds_dwordx4 v254, s[98:99]
	s_add_i32 m0, s11, 0x1000
	s_add_u32 s8, s98, s13
	s_addc_u32 s9, s99, 0
	global_load_lds_dwordx4 v254, s[8:9]
	s_add_i32 m0, s11, 0x2000
	s_add_u32 s8, s8, s13
	s_addc_u32 s9, s9, 0
	global_load_lds_dwordx4 v254, s[8:9]
	s_add_i32 m0, s11, 0x3000
	s_add_u32 s8, s8, s13
	s_addc_u32 s9, s9, 0
	global_load_lds_dwordx4 v254, s[8:9]
	s_add_u32 s98, s98, 0x80
	s_addc_u32 s99, s99, 0
	ds_read_b128 v[174:177], v110
	ds_read_b128 v[94:97], v87 offset:16384
	ds_read_b128 v[98:101], v87 offset:16896
	ds_read_b128 v[102:105], v87 offset:20480
	ds_read_b128 v[106:109], v87 offset:20992
	ds_read_b128 v[178:181], v110 offset:2048
	ds_read_b128 v[246:249], v110 offset:4096
	ds_read_b128 v[250:253], v110 offset:6144
.Lgk_loop_460:
	s_and_b32 s5, s1, 0x8000
	s_xor_b32 s10, s5, 0x8000
	s_add_i32 s11, s10, s12
	v_or_b32_e32 v130, s5, v118
	v_add_u32_e32 v131, s5, v111
	s_add_i32 m0, s11, 0x4000
	s_waitcnt lgkmcnt(6)
	v_mfma_f32_16x16x32_bf16 v[0:3], v[94:97], v[174:177], v[0:3]
	global_load_lds_dwordx4 v255, s[100:101]
	ds_read_b128 v[142:145], v130 offset:16384
	s_add_i32 m0, s11, 0x5000
	s_add_u32 s8, s100, s13
	s_addc_u32 s9, s101, 0
	s_waitcnt lgkmcnt(6)
	v_mfma_f32_16x16x32_bf16 v[4:7], v[98:101], v[174:177], v[4:7]
	global_load_lds_dwordx4 v255, s[8:9]
	ds_read_b128 v[162:165], v130 offset:16896
	s_add_i32 m0, s11, 0x6000
	s_add_u32 s8, s8, s13
	s_addc_u32 s9, s9, 0
	s_waitcnt lgkmcnt(6)
	v_mfma_f32_16x16x32_bf16 v[8:11], v[102:105], v[174:177], v[8:11]
	global_load_lds_dwordx4 v255, s[8:9]
	ds_read_b128 v[166:169], v130 offset:20480
	s_add_i32 m0, s11, 0x7000
	s_add_u32 s8, s8, s13
	s_addc_u32 s9, s9, 0
	s_waitcnt lgkmcnt(6)
	v_mfma_f32_16x16x32_bf16 v[12:15], v[106:109], v[174:177], v[12:15]
	global_load_lds_dwordx4 v255, s[8:9]
	ds_read_b128 v[170:173], v130 offset:20992
	ds_read_b128 v[174:177], v131
	s_add_u32 s100, s100, 0x80
	s_addc_u32 s101, s101, 0
	s_waitcnt lgkmcnt(7)
	v_mfma_f32_16x16x32_bf16 v[16:19], v[94:97], v[178:181], v[16:19]
	v_mfma_f32_16x16x32_bf16 v[20:23], v[98:101], v[178:181], v[20:23]
	v_mfma_f32_16x16x32_bf16 v[24:27], v[102:105], v[178:181], v[24:27]
	v_mfma_f32_16x16x32_bf16 v[28:31], v[106:109], v[178:181], v[28:31]
	ds_read_b128 v[178:181], v131 offset:2048
	s_waitcnt lgkmcnt(7)
	v_mfma_f32_16x16x32_bf16 v[32:35], v[94:97], v[246:249], v[32:35]
	v_mfma_f32_16x16x32_bf16 v[36:39], v[98:101], v[246:249], v[36:39]
	v_mfma_f32_16x16x32_bf16 v[40:43], v[102:105], v[246:249], v[40:43]
	v_mfma_f32_16x16x32_bf16 v[44:47], v[106:109], v[246:249], v[44:47]
	ds_read_b128 v[246:249], v131 offset:4096
	s_waitcnt lgkmcnt(7)
	v_mfma_f32_16x16x32_bf16 v[48:51], v[94:97], v[250:253], v[48:51]
	v_mfma_f32_16x16x32_bf16 v[52:55], v[98:101], v[250:253], v[52:55]
	v_mfma_f32_16x16x32_bf16 v[56:59], v[102:105], v[250:253], v[56:59]
	v_mfma_f32_16x16x32_bf16 v[60:63], v[106:109], v[250:253], v[60:63]
	ds_read_b128 v[250:253], v131 offset:6144
	s_waitcnt lgkmcnt(3)
	v_mfma_f32_16x16x32_bf16 v[0:3], v[142:145], v[174:177], v[0:3]
	v_mfma_f32_16x16x32_bf16 v[4:7], v[162:165], v[174:177], v[4:7]
	v_mfma_f32_16x16x32_bf16 v[8:11], v[166:169], v[174:177], v[8:11]
	v_mfma_f32_16x16x32_bf16 v[12:15], v[170:173], v[174:177], v[12:15]
	s_waitcnt lgkmcnt(2)
	v_mfma_f32_16x16x32_bf16 v[16:19], v[142:145], v[178:181], v[16:19]
	v_mfma_f32_16x16x32_bf16 v[20:23], v[162:165], v[178:181], v[20:23]
	v_mfma_f32_16x16x32_bf16 v[24:27], v[166:169], v[178:181], v[24:27]
	v_mfma_f32_16x16x32_bf16 v[28:31], v[170:173], v[178:181], v[28:31]
	s_waitcnt vmcnt(0)
	s_waitcnt lgkmcnt(0)
	s_barrier
	s_add_i32 s1, s1, 0x8000
	s_cmp_eq_u32 s1, 0x78000
	s_cbranch_scc1 .Lgk_tail_460
	v_or_b32_e32 v130, s10, v87
	v_add_u32_e32 v131, s10, v110
	s_add_i32 s11, s5, s12
	ds_read_b128 v[174:177], v131
	ds_read_b128 v[94:97], v130 offset:16384
	s_mov_b32 m0, s11
	v_mfma_f32_16x16x32_bf16 v[32:35], v[142:145], v[246:249], v[32:35]
	global_load_lds_dwordx4 v254, s[98:99]
	ds_read_b128 v[98:101], v130 offset:16896
	s_add_i32 m0, s11, 0x1000
	s_add_u32 s8, s98, s13
	s_addc_u32 s9, s99, 0
	v_mfma_f32_16x16x32_bf16 v[36:39], v[162:165], v[246:249], v[36:39]
	global_load_lds_dwordx4 v254, s[8:9]
	ds_read_b128 v[102:105], v130 offset:20480
	s_add_i32 m0, s11, 0x2000
	s_add_u32 s8, s8, s13
	s_addc_u32 s9, s9, 0
	v_mfma_f32_16x16x32_bf16 v[40:43], v[166:169], v[246:249], v[40:43]
	global_load_lds_dwordx4 v254, s[8:9]
	ds_read_b128 v[106:109], v130 offset:20992
	s_add_i32 m0, s11, 0x3000
	s_add_u32 s8, s8, s13
	s_addc_u32 s9, s9, 0
	v_mfma_f32_16x16x32_bf16 v[44:47], v[170:173], v[246:249], v[44:47]
	global_load_lds_dwordx4 v254, s[8:9]
	ds_read_b128 v[178:181], v131 offset:2048
	ds_read_b128 v[246:249], v131 offset:4096
	s_add_u32 s98, s98, 0x80
	s_addc_u32 s99, s99, 0
	v_mfma_f32_16x16x32_bf16 v[48:51], v[142:145], v[250:253], v[48:51]
	v_mfma_f32_16x16x32_bf16 v[52:55], v[162:165], v[250:253], v[52:55]
	v_mfma_f32_16x16x32_bf16 v[56:59], v[166:169], v[250:253], v[56:59]
	v_mfma_f32_16x16x32_bf16 v[60:63], v[170:173], v[250:253], v[60:63]
	ds_read_b128 v[250:253], v131 offset:6144
	s_branch .Lgk_loop_460
; __device__ __forceinline__ f32x4 mfma16(bf16x8 a, bf16x8 b, f32x4 c) { return __builtin_amdgcn_mfma_f32_16x16x32_bf16(a, b, c, 0, 0, 0); }
; template <class Epi>
; __device__ __forceinline__ void gemm_tile(const bf16_t* __restrict__ A, const bf16_t* __restrict__ Bt, int K, int row0, int col0, const Epi& epi, char* smem,
;                                           bool prefetched, bool nvalid, int nrow0, int ncol0) {
;     ...
;     for (int kt = 0; kt < nk; ++kt) {
;         const int cur = kt & 1;
;         if (kt + 1 < nk) GLDS_STAGE(cur ^ 1, pA, pB, kt + 1);
;         const char* cb = smem + cur * 2 * TILE_B;
; #pragma unroll
;         for (int ks = 0; ks < 2; ++ks) {
;             bf16x8 a[4], b[4];
; #pragma unroll
;             for (int m = 0; m < 4; ++m) a[m] = *(const bf16x8*)(cb + offA[m][ks]);
; #pragma unroll
;             for (int n = 0; n < 4; ++n) b[n] = *(const bf16x8*)(cb + offB[n][ks]);
; #pragma unroll
;             for (int m = 0; m < 4; ++m)
; #pragma unroll
;                 for (int n = 0; n < 4; ++n) acc[m][n] = mfma16(b[n], a[m], acc[m][n]);
;         }
;         asm volatile("s_waitcnt vmcnt(0)" ::: "memory");
;         __syncthreads();
;     }
;     if (nvalid) { const bf16_t* qA = A + (size_t)nrow0 * K; const bf16_t* qB = Bt + (size_t)ncol0 * K; GLDS_STAGE(0, qA, qB, 0); }
.Lgk_tail_460:
	v_mfma_f32_16x16x32_bf16 v[32:35], v[142:145], v[246:249], v[32:35]
	v_mfma_f32_16x16x32_bf16 v[36:39], v[162:165], v[246:249], v[36:39]
	v_mfma_f32_16x16x32_bf16 v[40:43], v[166:169], v[246:249], v[40:43]
	v_mfma_f32_16x16x32_bf16 v[44:47], v[170:173], v[246:249], v[44:47]
	v_mfma_f32_16x16x32_bf16 v[48:51], v[142:145], v[250:253], v[48:51]
	v_mfma_f32_16x16x32_bf16 v[52:55], v[162:165], v[250:253], v[52:55]
	v_mfma_f32_16x16x32_bf16 v[56:59], v[166:169], v[250:253], v[56:59]
	v_mfma_f32_16x16x32_bf16 v[60:63], v[170:173], v[250:253], v[60:63]
	ds_read_b128 v[94:97], v87 offset:49152
	ds_read_b128 v[98:101], v87 offset:49664
	ds_read_b128 v[102:105], v110 offset:32768
	ds_read_b128 v[106:109], v110 offset:34816
	ds_read_b128 v[142:145], v87 offset:53248
	ds_read_b128 v[162:165], v87 offset:53760
	s_add_i32 s16, s16, s58
	s_waitcnt lgkmcnt(3)
	v_mfma_f32_16x16x32_bf16 v[0:3], v[94:97], v[102:105], v[0:3]
	s_cmpk_gt_i32 s16, 0x7ff
	s_cselect_b64 s[6:7], -1, 0
	s_cmpk_lt_i32 s16, 0x800
	v_mfma_f32_16x16x32_bf16 v[4:7], v[98:101], v[102:105], v[4:7]
	s_waitcnt lgkmcnt(1)
	v_mfma_f32_16x16x32_bf16 v[8:11], v[142:145], v[102:105], v[8:11]
	s_waitcnt lgkmcnt(0)
	v_mfma_f32_16x16x32_bf16 v[12:15], v[162:165], v[102:105], v[12:15]
	v_mfma_f32_16x16x32_bf16 v[16:19], v[94:97], v[106:109], v[16:19]
	v_mfma_f32_16x16x32_bf16 v[20:23], v[98:101], v[106:109], v[20:23]
	v_mfma_f32_16x16x32_bf16 v[24:27], v[142:145], v[106:109], v[24:27]
	v_mfma_f32_16x16x32_bf16 v[28:31], v[162:165], v[106:109], v[28:31]
	ds_read_b128 v[102:105], v110 offset:36864
	ds_read_b128 v[106:109], v110 offset:38912
	ds_read_b128 v[178:181], v118 offset:49152
	s_waitcnt lgkmcnt(2)
	v_mfma_f32_16x16x32_bf16 v[166:169], v[94:97], v[102:105], v[32:35]
	v_mfma_f32_16x16x32_bf16 v[170:173], v[98:101], v[102:105], v[36:39]
	v_mfma_f32_16x16x32_bf16 v[174:177], v[142:145], v[102:105], v[40:43]
	v_mfma_f32_16x16x32_bf16 v[102:105], v[162:165], v[102:105], v[44:47]
	s_waitcnt lgkmcnt(1)
	v_mfma_f32_16x16x32_bf16 v[94:97], v[94:97], v[106:109], v[48:51]
	v_mfma_f32_16x16x32_bf16 v[98:101], v[98:101], v[106:109], v[52:55]
	v_mfma_f32_16x16x32_bf16 v[142:145], v[142:145], v[106:109], v[56:59]
	v_mfma_f32_16x16x32_bf16 v[106:109], v[162:165], v[106:109], v[60:63]
	ds_read_b128 v[162:165], v118 offset:49664
	ds_read_b128 v[32:35], v111 offset:32768
	ds_read_b128 v[36:39], v111 offset:34816
	ds_read_b128 v[182:185], v118 offset:53760
	s_waitcnt lgkmcnt(2)
	v_mfma_f32_16x16x32_bf16 v[52:55], v[178:181], v[32:35], v[0:3]
	s_nop 2
	ds_read_b128 v[0:3], v118 offset:53248
	v_mfma_f32_16x16x32_bf16 v[56:59], v[162:165], v[32:35], v[4:7]
	s_nop 2
	ds_read_b128 v[4:7], v111 offset:36864
	ds_read_b128 v[186:189], v111 offset:38912
	s_waitcnt vmcnt(0)
	s_waitcnt lgkmcnt(0)
	v_mfma_f32_16x16x32_bf16 v[60:63], v[0:3], v[32:35], v[8:11]
	s_barrier
	v_mfma_f32_16x16x32_bf16 v[48:51], v[182:185], v[32:35], v[12:15]
	v_mfma_f32_16x16x32_bf16 v[44:47], v[178:181], v[36:39], v[16:19]
	v_mfma_f32_16x16x32_bf16 v[40:43], v[162:165], v[36:39], v[20:23]
	v_mfma_f32_16x16x32_bf16 v[32:35], v[0:3], v[36:39], v[24:27]
	v_mfma_f32_16x16x32_bf16 v[24:27], v[182:185], v[36:39], v[28:31]
	v_mfma_f32_16x16x32_bf16 v[36:39], v[178:181], v[4:7], v[166:169]
	v_mfma_f32_16x16x32_bf16 v[28:31], v[162:165], v[4:7], v[170:173]
	v_mfma_f32_16x16x32_bf16 v[20:23], v[0:3], v[4:7], v[174:177]
	v_mfma_f32_16x16x32_bf16 v[16:19], v[182:185], v[4:7], v[102:105]
	v_mfma_f32_16x16x32_bf16 v[12:15], v[178:181], v[186:189], v[94:97]
	v_mfma_f32_16x16x32_bf16 v[8:11], v[162:165], v[186:189], v[98:101]
	v_mfma_f32_16x16x32_bf16 v[4:7], v[0:3], v[186:189], v[142:145]
	v_mfma_f32_16x16x32_bf16 v[0:3], v[182:185], v[186:189], v[106:109]
	s_cbranch_scc0 .LBB0_454
	s_ashr_i32 s1, s16, 31
	s_lshr_b32 s1, s1, 29
	s_add_i32 s1, s16, s1
	s_lshl_b32 s5, s1, 4
	s_and_b32 s8, s5, 0xffffff80
	s_and_b32 s1, s1, 0x1fffff8
	s_sub_i32 s1, s16, s1
	s_ashr_i32 s9, s8, 31
	s_lshl_b32 s10, s1, 7
	s_lshl_b64 s[8:9], s[8:9], 11
	v_readlane_b32 s12, v245, 60
	v_readlane_b32 s13, v245, 61
	s_add_u32 s8, s12, s8
	s_addc_u32 s9, s13, s9
	s_ashr_i32 s11, s10, 31
	s_lshl_b64 s[10:11], s[10:11], 11
	s_add_u32 s10, s14, s10
	v_readfirstlane_b32 s1, v149
	s_addc_u32 s11, s15, s11
	s_mov_b32 m0, s1
	v_readfirstlane_b32 s1, v119
	global_load_lds_dwordx4 v126, s[8:9]
	v_lshl_add_u64 v[94:95], v[64:65], 1, s[10:11]
	s_mov_b32 m0, s1
	v_readfirstlane_b32 s1, v120
	global_load_lds_dwordx4 v[94:95], off
	s_mov_b32 m0, s1
	v_readfirstlane_b32 s1, v121
	global_load_lds_dwordx4 v127, s[8:9]
	v_lshl_add_u64 v[94:95], v[66:67], 1, s[10:11]
	s_mov_b32 m0, s1
	v_readfirstlane_b32 s1, v122
	global_load_lds_dwordx4 v[94:95], off
	s_mov_b32 m0, s1
	v_readfirstlane_b32 s1, v123
	global_load_lds_dwordx4 v128, s[8:9]
	v_lshl_add_u64 v[94:95], v[68:69], 1, s[10:11]
	s_mov_b32 m0, s1
	v_readfirstlane_b32 s1, v124
	global_load_lds_dwordx4 v[94:95], off
	s_mov_b32 m0, s1
	v_readfirstlane_b32 s1, v125
	global_load_lds_dwordx4 v129, s[8:9]
	v_lshl_add_u64 v[94:95], v[70:71], 1, s[10:11]
	s_mov_b32 m0, s1
	s_nop 0
	global_load_lds_dwordx4 v[94:95], off
	s_branch .LBB0_454

; __device__ __forceinline__ f32x4 mfma16(bf16x8 a, bf16x8 b, f32x4 c) { return __builtin_amdgcn_mfma_f32_16x16x32_bf16(a, b, c, 0, 0, 0); }
; template <class Epi>
; __device__ __forceinline__ void gemm_tile(const bf16_t* __restrict__ A, const bf16_t* __restrict__ Bt, int K, int row0, int col0, const Epi& epi, char* smem,
;                                           bool prefetched, bool nvalid, int nrow0, int ncol0) {
;     ...
;     for (int kt = 0; kt < nk; ++kt) {
;         const int cur = kt & 1;
;         if (kt + 1 < nk) GLDS_STAGE(cur ^ 1, pA, pB, kt + 1);
;         const char* cb = smem + cur * 2 * TILE_B;
; #pragma unroll
;         for (int ks = 0; ks < 2; ++ks) {
;             bf16x8 a[4], b[4];
; #pragma unroll
;             for (int m = 0; m < 4; ++m) a[m] = *(const bf16x8*)(cb + offA[m][ks]);
; #pragma unroll
;             for (int n = 0; n < 4; ++n) b[n] = *(const bf16x8*)(cb + offB[n][ks]);
; #pragma unroll
;             for (int m = 0; m < 4; ++m)
; #pragma unroll
;                 for (int n = 0; n < 4; ++n) acc[m][n] = mfma16(b[n], a[m], acc[m][n]);
;         }
;         asm volatile("s_waitcnt vmcnt(0)" ::: "memory");
;         __syncthreads();
;     }
.LBB0_563:
	v_readfirstlane_b32 s98, v110
	v_readfirstlane_b32 s99, v111
	v_readfirstlane_b32 s10, v118
	v_readfirstlane_b32 s100, v124
	v_readfirstlane_b32 s101, v125
	v_readfirstlane_b32 s17, v149
	s_nop 3
	s_sub_u32 s18, s10, s98
	s_and_b32 s98, s98, 0xffffff80
	s_and_b32 s100, s100, 0xffffff80
	s_nop 1
	v_subrev_u32_e32 v254, s98, v110
	v_subrev_u32_e32 v255, s100, v124
	s_add_i32 s13, s17, 0x8000
	s_mov_b32 m0, s13
	s_nop 1
	global_load_lds_dwordx4 v254, s[98:99]
	s_add_i32 m0, s13, 0x1000
	s_add_u32 s10, s98, s18
	s_addc_u32 s11, s99, 0
	global_load_lds_dwordx4 v254, s[10:11]
	s_add_i32 m0, s13, 0x2000
	s_add_u32 s10, s10, s18
	s_addc_u32 s11, s11, 0
	global_load_lds_dwordx4 v254, s[10:11]
	s_add_i32 m0, s13, 0x3000
	s_add_u32 s10, s10, s18
	s_addc_u32 s11, s11, 0
	global_load_lds_dwordx4 v254, s[10:11]
	s_add_u32 s98, s98, 0x80
	s_addc_u32 s99, s99, 0
	ds_read_b128 v[192:195], v85
	ds_read_b128 v[118:121], v142 offset:16384
	ds_read_b128 v[122:125], v142 offset:16896
	ds_read_b128 v[126:129], v142 offset:20480
	ds_read_b128 v[172:175], v142 offset:20992
	ds_read_b128 v[196:199], v85 offset:2048
	ds_read_b128 v[246:249], v85 offset:4096
	ds_read_b128 v[250:253], v85 offset:6144
.Lgk_loop_563:
	s_and_b32 s9, s8, 0x8000
	s_xor_b32 s12, s9, 0x8000
	s_add_i32 s13, s12, s17
	v_or_b32_e32 v110, s9, v141
	v_add_u32_e32 v111, s9, v87
	s_add_i32 m0, s13, 0x4000
	s_waitcnt lgkmcnt(6)
	v_mfma_f32_16x16x32_bf16 v[0:3], v[118:121], v[192:195], v[0:3]
	global_load_lds_dwordx4 v255, s[100:101]
	ds_read_b128 v[176:179], v110 offset:16384
	s_add_i32 m0, s13, 0x5000
	s_add_u32 s10, s100, s18
	s_addc_u32 s11, s101, 0
	s_waitcnt lgkmcnt(6)
	v_mfma_f32_16x16x32_bf16 v[4:7], v[122:125], v[192:195], v[4:7]
	global_load_lds_dwordx4 v255, s[10:11]
	ds_read_b128 v[180:183], v110 offset:16896
	s_add_i32 m0, s13, 0x6000
	s_add_u32 s10, s10, s18
	s_addc_u32 s11, s11, 0
	s_waitcnt lgkmcnt(6)
	v_mfma_f32_16x16x32_bf16 v[8:11], v[126:129], v[192:195], v[8:11]
	global_load_lds_dwordx4 v255, s[10:11]
	ds_read_b128 v[184:187], v110 offset:20480
	s_add_i32 m0, s13, 0x7000
	s_add_u32 s10, s10, s18
	s_addc_u32 s11, s11, 0
	s_waitcnt lgkmcnt(6)
	v_mfma_f32_16x16x32_bf16 v[12:15], v[172:175], v[192:195], v[12:15]
	global_load_lds_dwordx4 v255, s[10:11]
	ds_read_b128 v[188:191], v110 offset:20992
	ds_read_b128 v[192:195], v111
	s_add_u32 s100, s100, 0x80
	s_addc_u32 s101, s101, 0
	s_waitcnt lgkmcnt(7)
	v_mfma_f32_16x16x32_bf16 v[16:19], v[118:121], v[196:199], v[16:19]
	v_mfma_f32_16x16x32_bf16 v[20:23], v[122:125], v[196:199], v[20:23]
	v_mfma_f32_16x16x32_bf16 v[24:27], v[126:129], v[196:199], v[24:27]
	v_mfma_f32_16x16x32_bf16 v[28:31], v[172:175], v[196:199], v[28:31]
	ds_read_b128 v[196:199], v111 offset:2048
	s_waitcnt lgkmcnt(7)
	v_mfma_f32_16x16x32_bf16 v[32:35], v[118:121], v[246:249], v[32:35]
	v_mfma_f32_16x16x32_bf16 v[36:39], v[122:125], v[246:249], v[36:39]
	v_mfma_f32_16x16x32_bf16 v[40:43], v[126:129], v[246:249], v[40:43]
	v_mfma_f32_16x16x32_bf16 v[44:47], v[172:175], v[246:249], v[44:47]
	ds_read_b128 v[246:249], v111 offset:4096
	s_waitcnt lgkmcnt(7)
	v_mfma_f32_16x16x32_bf16 v[48:51], v[118:121], v[250:253], v[48:51]
	v_mfma_f32_16x16x32_bf16 v[52:55], v[122:125], v[250:253], v[52:55]
	v_mfma_f32_16x16x32_bf16 v[56:59], v[126:129], v[250:253], v[56:59]
	v_mfma_f32_16x16x32_bf16 v[60:63], v[172:175], v[250:253], v[60:63]
	ds_read_b128 v[250:253], v111 offset:6144
	s_waitcnt lgkmcnt(3)
	v_mfma_f32_16x16x32_bf16 v[0:3], v[176:179], v[192:195], v[0:3]
	v_mfma_f32_16x16x32_bf16 v[4:7], v[180:183], v[192:195], v[4:7]
	v_mfma_f32_16x16x32_bf16 v[8:11], v[184:187], v[192:195], v[8:11]
	v_mfma_f32_16x16x32_bf16 v[12:15], v[188:191], v[192:195], v[12:15]
	s_waitcnt lgkmcnt(2)
	v_mfma_f32_16x16x32_bf16 v[16:19], v[176:179], v[196:199], v[16:19]
	v_mfma_f32_16x16x32_bf16 v[20:23], v[180:183], v[196:199], v[20:23]
	v_mfma_f32_16x16x32_bf16 v[24:27], v[184:187], v[196:199], v[24:27]
	v_mfma_f32_16x16x32_bf16 v[28:31], v[188:191], v[196:199], v[28:31]
	s_waitcnt vmcnt(0)
	s_waitcnt lgkmcnt(0)
	s_barrier
	s_add_i32 s8, s8, 0x8000
	s_cmp_eq_u32 s8, 0x78000
	s_cbranch_scc1 .Lgk_tail_563
	v_or_b32_e32 v110, s12, v142
	v_add_u32_e32 v111, s12, v85
	s_add_i32 s13, s9, s17
	ds_read_b128 v[192:195], v111
	ds_read_b128 v[118:121], v110 offset:16384
	s_mov_b32 m0, s13
	v_mfma_f32_16x16x32_bf16 v[32:35], v[176:179], v[246:249], v[32:35]
	global_load_lds_dwordx4 v254, s[98:99]
	ds_read_b128 v[122:125], v110 offset:16896
	s_add_i32 m0, s13, 0x1000
	s_add_u32 s10, s98, s18
	s_addc_u32 s11, s99, 0
	v_mfma_f32_16x16x32_bf16 v[36:39], v[180:183], v[246:249], v[36:39]
	global_load_lds_dwordx4 v254, s[10:11]
	ds_read_b128 v[126:129], v110 offset:20480
	s_add_i32 m0, s13, 0x2000
	s_add_u32 s10, s10, s18
	s_addc_u32 s11, s11, 0
	v_mfma_f32_16x16x32_bf16 v[40:43], v[184:187], v[246:249], v[40:43]
	global_load_lds_dwordx4 v254, s[10:11]
	ds_read_b128 v[172:175], v110 offset:20992
	s_add_i32 m0, s13, 0x3000
	s_add_u32 s10, s10, s18
	s_addc_u32 s11, s11, 0
	v_mfma_f32_16x16x32_bf16 v[44:47], v[188:191], v[246:249], v[44:47]
	global_load_lds_dwordx4 v254, s[10:11]
	ds_read_b128 v[196:199], v111 offset:2048
	ds_read_b128 v[246:249], v111 offset:4096
	s_add_u32 s98, s98, 0x80
	s_addc_u32 s99, s99, 0
	v_mfma_f32_16x16x32_bf16 v[48:51], v[176:179], v[250:253], v[48:51]
	v_mfma_f32_16x16x32_bf16 v[52:55], v[180:183], v[250:253], v[52:55]
	v_mfma_f32_16x16x32_bf16 v[56:59], v[184:187], v[250:253], v[56:59]
	v_mfma_f32_16x16x32_bf16 v[60:63], v[188:191], v[250:253], v[60:63]
	ds_read_b128 v[250:253], v111 offset:6144
	s_branch .Lgk_loop_563
; __device__ __forceinline__ f32x4 mfma16(bf16x8 a, bf16x8 b, f32x4 c) { return __builtin_amdgcn_mfma_f32_16x16x32_bf16(a, b, c, 0, 0, 0); }
; template <class Epi>
; __device__ __forceinline__ void gemm_tile(const bf16_t* __restrict__ A, const bf16_t* __restrict__ Bt, int K, int row0, int col0, const Epi& epi, char* smem,
;                                           bool prefetched, bool nvalid, int nrow0, int ncol0) {
;     ...
;     for (int kt = 0; kt < nk; ++kt) {
;         const int cur = kt & 1;
;         if (kt + 1 < nk) GLDS_STAGE(cur ^ 1, pA, pB, kt + 1);
;         const char* cb = smem + cur * 2 * TILE_B;
; #pragma unroll
;         for (int ks = 0; ks < 2; ++ks) {
;             bf16x8 a[4], b[4];
; #pragma unroll
;             for (int m = 0; m < 4; ++m) a[m] = *(const bf16x8*)(cb + offA[m][ks]);
; #pragma unroll
;             for (int n = 0; n < 4; ++n) b[n] = *(const bf16x8*)(cb + offB[n][ks]);
; #pragma unroll
;             for (int m = 0; m < 4; ++m)
; #pragma unroll
;                 for (int n = 0; n < 4; ++n) acc[m][n] = mfma16(b[n], a[m], acc[m][n]);
;         }
;         asm volatile("s_waitcnt vmcnt(0)" ::: "memory");
;         __syncthreads();
;     }
;     if (nvalid) { const bf16_t* qA = A + (size_t)nrow0 * K; const bf16_t* qB = Bt + (size_t)ncol0 * K; GLDS_STAGE(0, qA, qB, 0); }
.Lgk_tail_563:
	v_mfma_f32_16x16x32_bf16 v[32:35], v[176:179], v[246:249], v[32:35]
	v_mfma_f32_16x16x32_bf16 v[36:39], v[180:183], v[246:249], v[36:39]
	v_mfma_f32_16x16x32_bf16 v[40:43], v[184:187], v[246:249], v[40:43]
	v_mfma_f32_16x16x32_bf16 v[44:47], v[188:191], v[246:249], v[44:47]
	v_mfma_f32_16x16x32_bf16 v[48:51], v[176:179], v[250:253], v[48:51]
	v_mfma_f32_16x16x32_bf16 v[52:55], v[180:183], v[250:253], v[52:55]
	v_mfma_f32_16x16x32_bf16 v[56:59], v[184:187], v[250:253], v[56:59]
	v_mfma_f32_16x16x32_bf16 v[60:63], v[188:191], v[250:253], v[60:63]
	ds_read_b128 v[118:121], v142 offset:49152
	ds_read_b128 v[122:125], v85 offset:32768
	ds_read_b128 v[126:129], v142 offset:49664
	ds_read_b128 v[172:175], v142 offset:53248
	ds_read_b128 v[176:179], v142 offset:53760
	s_add_i32 s16, s16, s58
	s_waitcnt lgkmcnt(3)
	v_mfma_f32_16x16x32_bf16 v[0:3], v[118:121], v[122:125], v[0:3]
	s_cmpk_gt_i32 s16, 0x1fff
	s_cselect_b64 s[6:7], -1, 0
	s_cmpk_lt_i32 s16, 0x2000
	s_waitcnt lgkmcnt(2)
	v_mfma_f32_16x16x32_bf16 v[4:7], v[126:129], v[122:125], v[4:7]
	ds_read_b128 v[192:195], v141 offset:49152
	ds_read_b128 v[196:199], v141 offset:53760
	s_waitcnt lgkmcnt(3)
	v_mfma_f32_16x16x32_bf16 v[8:11], v[172:175], v[122:125], v[8:11]
	s_waitcnt lgkmcnt(2)
	v_mfma_f32_16x16x32_bf16 v[12:15], v[176:179], v[122:125], v[12:15]
	ds_read_b128 v[122:125], v85 offset:34816
	s_waitcnt lgkmcnt(0)
	v_mfma_f32_16x16x32_bf16 v[16:19], v[118:121], v[122:125], v[16:19]
	v_mfma_f32_16x16x32_bf16 v[20:23], v[126:129], v[122:125], v[20:23]
	v_mfma_f32_16x16x32_bf16 v[24:27], v[172:175], v[122:125], v[24:27]
	v_mfma_f32_16x16x32_bf16 v[28:31], v[176:179], v[122:125], v[28:31]
	ds_read_b128 v[122:125], v85 offset:36864
	s_waitcnt lgkmcnt(0)
	v_mfma_f32_16x16x32_bf16 v[180:183], v[118:121], v[122:125], v[32:35]
	s_nop 2
	ds_read_b128 v[32:35], v85 offset:38912
	v_mfma_f32_16x16x32_bf16 v[184:187], v[126:129], v[122:125], v[36:39]
	v_mfma_f32_16x16x32_bf16 v[188:191], v[172:175], v[122:125], v[40:43]
	v_mfma_f32_16x16x32_bf16 v[122:125], v[176:179], v[122:125], v[44:47]
	s_waitcnt lgkmcnt(0)
	v_mfma_f32_16x16x32_bf16 v[118:121], v[118:121], v[32:35], v[48:51]
	v_mfma_f32_16x16x32_bf16 v[126:129], v[126:129], v[32:35], v[52:55]
	v_mfma_f32_16x16x32_bf16 v[172:175], v[172:175], v[32:35], v[56:59]
	v_mfma_f32_16x16x32_bf16 v[176:179], v[176:179], v[32:35], v[60:63]
	ds_read_b128 v[32:35], v87 offset:32768
	s_waitcnt lgkmcnt(0)
	v_mfma_f32_16x16x32_bf16 v[56:59], v[192:195], v[32:35], v[0:3]
	s_nop 2
	ds_read_b128 v[0:3], v141 offset:49664
	s_waitcnt lgkmcnt(0)
	v_mfma_f32_16x16x32_bf16 v[60:63], v[0:3], v[32:35], v[4:7]
	s_nop 2
	ds_read_b128 v[4:7], v141 offset:53248
	s_waitcnt lgkmcnt(0)
	v_mfma_f32_16x16x32_bf16 v[48:51], v[4:7], v[32:35], v[8:11]
	s_nop 2
	ds_read_b128 v[8:11], v87 offset:34816
	v_mfma_f32_16x16x32_bf16 v[52:55], v[196:199], v[32:35], v[12:15]
	s_waitcnt lgkmcnt(0)
	v_mfma_f32_16x16x32_bf16 v[44:47], v[192:195], v[8:11], v[16:19]
	v_mfma_f32_16x16x32_bf16 v[40:43], v[0:3], v[8:11], v[20:23]
	v_mfma_f32_16x16x32_bf16 v[36:39], v[4:7], v[8:11], v[24:27]
	v_mfma_f32_16x16x32_bf16 v[32:35], v[196:199], v[8:11], v[28:31]
	ds_read_b128 v[8:11], v87 offset:36864
	s_waitcnt lgkmcnt(0)
	v_mfma_f32_16x16x32_bf16 v[16:19], v[196:199], v[8:11], v[122:125]
	s_nop 2
	ds_read_b128 v[122:125], v87 offset:38912
	s_waitcnt vmcnt(0)
	v_mfma_f32_16x16x32_bf16 v[28:31], v[192:195], v[8:11], v[180:183]
	s_waitcnt lgkmcnt(0)
	s_barrier
	v_mfma_f32_16x16x32_bf16 v[24:27], v[0:3], v[8:11], v[184:187]
	v_mfma_f32_16x16x32_bf16 v[20:23], v[4:7], v[8:11], v[188:191]
	v_mfma_f32_16x16x32_bf16 v[8:11], v[192:195], v[122:125], v[118:121]
	v_mfma_f32_16x16x32_bf16 v[12:15], v[0:3], v[122:125], v[126:129]
	v_mfma_f32_16x16x32_bf16 v[0:3], v[4:7], v[122:125], v[172:175]
	v_mfma_f32_16x16x32_bf16 v[4:7], v[196:199], v[122:125], v[176:179]
	s_cbranch_scc0 .LBB0_557
	s_ashr_i32 s8, s16, 31
	s_lshr_b32 s8, s8, 27
	s_add_i32 s9, s16, s8
	s_lshl_b32 s8, s9, 2
	s_and_b32 s9, s9, 0x1ffffe0
	s_and_b32 s8, s8, 0xffffff80
	s_sub_i32 s9, s16, s9
	s_lshl_b32 s10, s9, 7
	s_ashr_i32 s9, s8, 31
	s_lshl_b64 s[8:9], s[8:9], 11
	v_readlane_b32 s11, v245, 53
	s_add_u32 s8, s11, s8
	v_readlane_b32 s11, v245, 54
	s_addc_u32 s9, s11, s9
	s_ashr_i32 s11, s10, 31
	s_lshl_b64 s[10:11], s[10:11], 11
	s_add_u32 s10, s14, s10
	v_readfirstlane_b32 s12, v149
	s_addc_u32 s11, s15, s11
	s_mov_b32 m0, s12
	v_readfirstlane_b32 s12, v143
	global_load_lds_dwordx4 v168, s[8:9]
	v_lshl_add_u64 v[110:111], v[64:65], 1, s[10:11]
	s_mov_b32 m0, s12
	v_readfirstlane_b32 s12, v144
	global_load_lds_dwordx4 v[110:111], off
	s_mov_b32 m0, s12
	v_readfirstlane_b32 s12, v145
	global_load_lds_dwordx4 v169, s[8:9]
	v_lshl_add_u64 v[110:111], v[66:67], 1, s[10:11]
	s_mov_b32 m0, s12
	v_readfirstlane_b32 s12, v162
	global_load_lds_dwordx4 v[110:111], off
	s_mov_b32 m0, s12
	v_readfirstlane_b32 s12, v163
	global_load_lds_dwordx4 v170, s[8:9]
	v_lshl_add_u64 v[110:111], v[68:69], 1, s[10:11]
	s_mov_b32 m0, s12
	v_readfirstlane_b32 s12, v164
	global_load_lds_dwordx4 v[110:111], off
	s_mov_b32 m0, s12
	v_lshl_add_u64 v[110:111], v[70:71], 1, s[10:11]
	global_load_lds_dwordx4 v171, s[8:9]
	v_readfirstlane_b32 s8, v165
	s_mov_b32 m0, s8
	s_nop 0
	global_load_lds_dwordx4 v[110:111], off
	s_branch .LBB0_557

; __device__ __forceinline__ f32x4 mfma16(bf16x8 a, bf16x8 b, f32x4 c) { return __builtin_amdgcn_mfma_f32_16x16x32_bf16(a, b, c, 0, 0, 0); }
; template <class Epi>
; __device__ __forceinline__ void gemm_tile(const bf16_t* __restrict__ A, const bf16_t* __restrict__ Bt, int K, int row0, int col0, const Epi& epi, char* smem,
;                                           bool prefetched, bool nvalid, int nrow0, int ncol0) {
;     ...
;     for (int kt = 0; kt < nk; ++kt) {
;         const int cur = kt & 1;
;         if (kt + 1 < nk) GLDS_STAGE(cur ^ 1, pA, pB, kt + 1);
;         const char* cb = smem + cur * 2 * TILE_B;
; #pragma unroll
;         for (int ks = 0; ks < 2; ++ks) {
;             bf16x8 a[4], b[4];
; #pragma unroll
;             for (int m = 0; m < 4; ++m) a[m] = *(const bf16x8*)(cb + offA[m][ks]);
; #pragma unroll
;             for (int n = 0; n < 4; ++n) b[n] = *(const bf16x8*)(cb + offB[n][ks]);
; #pragma unroll
;             for (int m = 0; m < 4; ++m)
; #pragma unroll
;                 for (int n = 0; n < 4; ++n) acc[m][n] = mfma16(b[n], a[m], acc[m][n]);
;         }
;         asm volatile("s_waitcnt vmcnt(0)" ::: "memory");
;         __syncthreads();
;     }
.LBB0_619:
	v_readfirstlane_b32 s98, v92
	v_readfirstlane_b32 s99, v93
	v_readfirstlane_b32 s8, v94
	v_readfirstlane_b32 s100, v100
	v_readfirstlane_b32 s101, v101
	v_readfirstlane_b32 s12, v149
	s_nop 3
	s_sub_u32 s13, s8, s98
	s_and_b32 s98, s98, 0xffffff80
	s_and_b32 s100, s100, 0xffffff80
	s_nop 1
	v_subrev_u32_e32 v254, s98, v92
	v_subrev_u32_e32 v255, s100, v100
	s_add_i32 s11, s12, 0x8000
	s_mov_b32 m0, s11
	s_nop 1
	global_load_lds_dwordx4 v254, s[98:99]
	s_add_i32 m0, s11, 0x1000
	s_add_u32 s8, s98, s13
	s_addc_u32 s9, s99, 0
	global_load_lds_dwordx4 v254, s[8:9]
	s_add_i32 m0, s11, 0x2000
	s_add_u32 s8, s8, s13
	s_addc_u32 s9, s9, 0
	global_load_lds_dwordx4 v254, s[8:9]
	s_add_i32 m0, s11, 0x3000
	s_add_u32 s8, s8, s13
	s_addc_u32 s9, s9, 0
	global_load_lds_dwordx4 v254, s[8:9]
	s_add_u32 s98, s98, 0x80
	s_addc_u32 s99, s99, 0
	ds_read_b128 v[174:177], v108
	ds_read_b128 v[92:95], v110 offset:16384
	ds_read_b128 v[96:99], v110 offset:16896
	ds_read_b128 v[100:103], v110 offset:20480
	ds_read_b128 v[104:107], v110 offset:20992
	ds_read_b128 v[178:181], v108 offset:2048
	ds_read_b128 v[246:249], v108 offset:4096
	ds_read_b128 v[250:253], v108 offset:6144
.Lgk_loop_619:
	s_and_b32 s3, s1, 0x8000
	s_xor_b32 s10, s3, 0x8000
	s_add_i32 s11, s10, s12
	v_or_b32_e32 v129, s3, v111
	v_add_u32_e32 v130, s3, v109
	s_add_i32 m0, s11, 0x4000
	s_waitcnt lgkmcnt(6)
	v_mfma_f32_16x16x32_bf16 v[0:3], v[92:95], v[174:177], v[0:3]
	global_load_lds_dwordx4 v255, s[100:101]
	ds_read_b128 v[142:145], v129 offset:16384
	s_add_i32 m0, s11, 0x5000
	s_add_u32 s8, s100, s13
	s_addc_u32 s9, s101, 0
	s_waitcnt lgkmcnt(6)
	v_mfma_f32_16x16x32_bf16 v[4:7], v[96:99], v[174:177], v[4:7]
	global_load_lds_dwordx4 v255, s[8:9]
	ds_read_b128 v[162:165], v129 offset:16896
	s_add_i32 m0, s11, 0x6000
	s_add_u32 s8, s8, s13
	s_addc_u32 s9, s9, 0
	s_waitcnt lgkmcnt(6)
	v_mfma_f32_16x16x32_bf16 v[8:11], v[100:103], v[174:177], v[8:11]
	global_load_lds_dwordx4 v255, s[8:9]
	ds_read_b128 v[166:169], v129 offset:20480
	s_add_i32 m0, s11, 0x7000
	s_add_u32 s8, s8, s13
	s_addc_u32 s9, s9, 0
	s_waitcnt lgkmcnt(6)
	v_mfma_f32_16x16x32_bf16 v[12:15], v[104:107], v[174:177], v[12:15]
	global_load_lds_dwordx4 v255, s[8:9]
	ds_read_b128 v[170:173], v129 offset:20992
	ds_read_b128 v[174:177], v130
	s_add_u32 s100, s100, 0x80
	s_addc_u32 s101, s101, 0
	s_waitcnt lgkmcnt(7)
	v_mfma_f32_16x16x32_bf16 v[16:19], v[92:95], v[178:181], v[16:19]
	v_mfma_f32_16x16x32_bf16 v[20:23], v[96:99], v[178:181], v[20:23]
	v_mfma_f32_16x16x32_bf16 v[24:27], v[100:103], v[178:181], v[24:27]
	v_mfma_f32_16x16x32_bf16 v[28:31], v[104:107], v[178:181], v[28:31]
	ds_read_b128 v[178:181], v130 offset:2048
	s_waitcnt lgkmcnt(7)
	v_mfma_f32_16x16x32_bf16 v[32:35], v[92:95], v[246:249], v[32:35]
	v_mfma_f32_16x16x32_bf16 v[36:39], v[96:99], v[246:249], v[36:39]
	v_mfma_f32_16x16x32_bf16 v[40:43], v[100:103], v[246:249], v[40:43]
	v_mfma_f32_16x16x32_bf16 v[44:47], v[104:107], v[246:249], v[44:47]
	ds_read_b128 v[246:249], v130 offset:4096
	s_waitcnt lgkmcnt(7)
	v_mfma_f32_16x16x32_bf16 v[48:51], v[92:95], v[250:253], v[48:51]
	v_mfma_f32_16x16x32_bf16 v[52:55], v[96:99], v[250:253], v[52:55]
	v_mfma_f32_16x16x32_bf16 v[56:59], v[100:103], v[250:253], v[56:59]
	v_mfma_f32_16x16x32_bf16 v[60:63], v[104:107], v[250:253], v[60:63]
	ds_read_b128 v[250:253], v130 offset:6144
	s_waitcnt lgkmcnt(3)
	v_mfma_f32_16x16x32_bf16 v[0:3], v[142:145], v[174:177], v[0:3]
	v_mfma_f32_16x16x32_bf16 v[4:7], v[162:165], v[174:177], v[4:7]
	v_mfma_f32_16x16x32_bf16 v[8:11], v[166:169], v[174:177], v[8:11]
	v_mfma_f32_16x16x32_bf16 v[12:15], v[170:173], v[174:177], v[12:15]
	s_waitcnt lgkmcnt(2)
	v_mfma_f32_16x16x32_bf16 v[16:19], v[142:145], v[178:181], v[16:19]
	v_mfma_f32_16x16x32_bf16 v[20:23], v[162:165], v[178:181], v[20:23]
	v_mfma_f32_16x16x32_bf16 v[24:27], v[166:169], v[178:181], v[24:27]
	v_mfma_f32_16x16x32_bf16 v[28:31], v[170:173], v[178:181], v[28:31]
	s_waitcnt vmcnt(0)
	s_waitcnt lgkmcnt(0)
	s_barrier
	s_add_i32 s1, s1, 0x8000
	s_cmp_eq_u32 s1, 0x1f8000
	s_cbranch_scc1 .Lgk_tail_619
	v_or_b32_e32 v129, s10, v110
	v_add_u32_e32 v130, s10, v108
	s_add_i32 s11, s3, s12
	ds_read_b128 v[174:177], v130
	ds_read_b128 v[92:95], v129 offset:16384
	s_mov_b32 m0, s11
	v_mfma_f32_16x16x32_bf16 v[32:35], v[142:145], v[246:249], v[32:35]
	global_load_lds_dwordx4 v254, s[98:99]
	ds_read_b128 v[96:99], v129 offset:16896
	s_add_i32 m0, s11, 0x1000
	s_add_u32 s8, s98, s13
	s_addc_u32 s9, s99, 0
	v_mfma_f32_16x16x32_bf16 v[36:39], v[162:165], v[246:249], v[36:39]
	global_load_lds_dwordx4 v254, s[8:9]
	ds_read_b128 v[100:103], v129 offset:20480
	s_add_i32 m0, s11, 0x2000
	s_add_u32 s8, s8, s13
	s_addc_u32 s9, s9, 0
	v_mfma_f32_16x16x32_bf16 v[40:43], v[166:169], v[246:249], v[40:43]
	global_load_lds_dwordx4 v254, s[8:9]
	ds_read_b128 v[104:107], v129 offset:20992
	s_add_i32 m0, s11, 0x3000
	s_add_u32 s8, s8, s13
	s_addc_u32 s9, s9, 0
	v_mfma_f32_16x16x32_bf16 v[44:47], v[170:173], v[246:249], v[44:47]
	global_load_lds_dwordx4 v254, s[8:9]
	ds_read_b128 v[178:181], v130 offset:2048
	ds_read_b128 v[246:249], v130 offset:4096
	s_add_u32 s98, s98, 0x80
	s_addc_u32 s99, s99, 0
	v_mfma_f32_16x16x32_bf16 v[48:51], v[142:145], v[250:253], v[48:51]
	v_mfma_f32_16x16x32_bf16 v[52:55], v[162:165], v[250:253], v[52:55]
	v_mfma_f32_16x16x32_bf16 v[56:59], v[166:169], v[250:253], v[56:59]
	v_mfma_f32_16x16x32_bf16 v[60:63], v[170:173], v[250:253], v[60:63]
	ds_read_b128 v[250:253], v130 offset:6144
	s_branch .Lgk_loop_619
; __device__ __forceinline__ f32x4 mfma16(bf16x8 a, bf16x8 b, f32x4 c) { return __builtin_amdgcn_mfma_f32_16x16x32_bf16(a, b, c, 0, 0, 0); }
; template <class Epi>
; __device__ __forceinline__ void gemm_tile(const bf16_t* __restrict__ A, const bf16_t* __restrict__ Bt, int K, int row0, int col0, const Epi& epi, char* smem,
;                                           bool prefetched, bool nvalid, int nrow0, int ncol0) {
;     ...
;     for (int kt = 0; kt < nk; ++kt) {
;         const int cur = kt & 1;
;         if (kt + 1 < nk) GLDS_STAGE(cur ^ 1, pA, pB, kt + 1);
;         const char* cb = smem + cur * 2 * TILE_B;
; #pragma unroll
;         for (int ks = 0; ks < 2; ++ks) {
;             bf16x8 a[4], b[4];
; #pragma unroll
;             for (int m = 0; m < 4; ++m) a[m] = *(const bf16x8*)(cb + offA[m][ks]);
; #pragma unroll
;             for (int n = 0; n < 4; ++n) b[n] = *(const bf16x8*)(cb + offB[n][ks]);
; #pragma unroll
;             for (int m = 0; m < 4; ++m)
; #pragma unroll
;                 for (int n = 0; n < 4; ++n) acc[m][n] = mfma16(b[n], a[m], acc[m][n]);
;         }
;         asm volatile("s_waitcnt vmcnt(0)" ::: "memory");
;         __syncthreads();
;     }
;     if (nvalid) { const bf16_t* qA = A + (size_t)nrow0 * K; const bf16_t* qB = Bt + (size_t)ncol0 * K; GLDS_STAGE(0, qA, qB, 0); }
.Lgk_tail_619:
	v_mfma_f32_16x16x32_bf16 v[32:35], v[142:145], v[246:249], v[32:35]
	v_mfma_f32_16x16x32_bf16 v[36:39], v[162:165], v[246:249], v[36:39]
	v_mfma_f32_16x16x32_bf16 v[40:43], v[166:169], v[246:249], v[40:43]
	v_mfma_f32_16x16x32_bf16 v[44:47], v[170:173], v[246:249], v[44:47]
	v_mfma_f32_16x16x32_bf16 v[48:51], v[142:145], v[250:253], v[48:51]
	v_mfma_f32_16x16x32_bf16 v[52:55], v[162:165], v[250:253], v[52:55]
	v_mfma_f32_16x16x32_bf16 v[56:59], v[166:169], v[250:253], v[56:59]
	v_mfma_f32_16x16x32_bf16 v[60:63], v[170:173], v[250:253], v[60:63]
	ds_read_b128 v[92:95], v110 offset:49152
	ds_read_b128 v[96:99], v110 offset:49664
	ds_read_b128 v[100:103], v108 offset:32768
	ds_read_b128 v[104:107], v108 offset:34816
	ds_read_b128 v[142:145], v110 offset:53248
	ds_read_b128 v[162:165], v110 offset:53760
	s_add_i32 s16, s16, s58
	s_waitcnt lgkmcnt(3)
	v_mfma_f32_16x16x32_bf16 v[0:3], v[92:95], v[100:103], v[0:3]
	s_cmpk_gt_i32 s16, 0x7ff
	s_cselect_b64 s[6:7], -1, 0
	s_cmpk_lt_i32 s16, 0x800
	v_mfma_f32_16x16x32_bf16 v[4:7], v[96:99], v[100:103], v[4:7]
	s_waitcnt lgkmcnt(1)
	v_mfma_f32_16x16x32_bf16 v[8:11], v[142:145], v[100:103], v[8:11]
	s_waitcnt lgkmcnt(0)
	v_mfma_f32_16x16x32_bf16 v[12:15], v[162:165], v[100:103], v[12:15]
	v_mfma_f32_16x16x32_bf16 v[16:19], v[92:95], v[104:107], v[16:19]
	v_mfma_f32_16x16x32_bf16 v[20:23], v[96:99], v[104:107], v[20:23]
	v_mfma_f32_16x16x32_bf16 v[24:27], v[142:145], v[104:107], v[24:27]
	v_mfma_f32_16x16x32_bf16 v[28:31], v[162:165], v[104:107], v[28:31]
	ds_read_b128 v[100:103], v108 offset:36864
	ds_read_b128 v[104:107], v108 offset:38912
	ds_read_b128 v[178:181], v111 offset:49152
	s_waitcnt lgkmcnt(2)
	v_mfma_f32_16x16x32_bf16 v[166:169], v[92:95], v[100:103], v[32:35]
	v_mfma_f32_16x16x32_bf16 v[170:173], v[96:99], v[100:103], v[36:39]
	v_mfma_f32_16x16x32_bf16 v[174:177], v[142:145], v[100:103], v[40:43]
	v_mfma_f32_16x16x32_bf16 v[100:103], v[162:165], v[100:103], v[44:47]
	s_waitcnt lgkmcnt(1)
	v_mfma_f32_16x16x32_bf16 v[92:95], v[92:95], v[104:107], v[48:51]
	v_mfma_f32_16x16x32_bf16 v[96:99], v[96:99], v[104:107], v[52:55]
	v_mfma_f32_16x16x32_bf16 v[142:145], v[142:145], v[104:107], v[56:59]
	v_mfma_f32_16x16x32_bf16 v[104:107], v[162:165], v[104:107], v[60:63]
	ds_read_b128 v[162:165], v111 offset:49664
	ds_read_b128 v[32:35], v109 offset:32768
	ds_read_b128 v[36:39], v109 offset:34816
	ds_read_b128 v[182:185], v111 offset:53760
	s_waitcnt lgkmcnt(2)
	v_mfma_f32_16x16x32_bf16 v[52:55], v[178:181], v[32:35], v[0:3]
	s_nop 2
	ds_read_b128 v[0:3], v111 offset:53248
	v_mfma_f32_16x16x32_bf16 v[56:59], v[162:165], v[32:35], v[4:7]
	s_nop 2
	ds_read_b128 v[4:7], v109 offset:36864
	ds_read_b128 v[186:189], v109 offset:38912
	s_waitcnt vmcnt(0)
	s_waitcnt lgkmcnt(0)
	v_mfma_f32_16x16x32_bf16 v[60:63], v[0:3], v[32:35], v[8:11]
	s_barrier
	v_mfma_f32_16x16x32_bf16 v[48:51], v[182:185], v[32:35], v[12:15]
	v_mfma_f32_16x16x32_bf16 v[44:47], v[178:181], v[36:39], v[16:19]
	v_mfma_f32_16x16x32_bf16 v[40:43], v[162:165], v[36:39], v[20:23]
	v_mfma_f32_16x16x32_bf16 v[32:35], v[0:3], v[36:39], v[24:27]
	v_mfma_f32_16x16x32_bf16 v[24:27], v[182:185], v[36:39], v[28:31]
	v_mfma_f32_16x16x32_bf16 v[36:39], v[178:181], v[4:7], v[166:169]
	v_mfma_f32_16x16x32_bf16 v[28:31], v[162:165], v[4:7], v[170:173]
	v_mfma_f32_16x16x32_bf16 v[20:23], v[0:3], v[4:7], v[174:177]
	v_mfma_f32_16x16x32_bf16 v[16:19], v[182:185], v[4:7], v[100:103]
	v_mfma_f32_16x16x32_bf16 v[12:15], v[178:181], v[186:189], v[92:95]
	v_mfma_f32_16x16x32_bf16 v[8:11], v[162:165], v[186:189], v[96:99]
	v_mfma_f32_16x16x32_bf16 v[4:7], v[0:3], v[186:189], v[142:145]
	v_mfma_f32_16x16x32_bf16 v[0:3], v[182:185], v[186:189], v[104:107]
	s_cbranch_scc0 .LBB0_613
	s_ashr_i32 s1, s16, 31
	s_lshr_b32 s1, s1, 29
	s_add_i32 s1, s16, s1
	s_lshl_b32 s3, s1, 4
	s_and_b32 s8, s3, 0xffffff80
	s_and_b32 s1, s1, 0x1fffff8
	s_sub_i32 s1, s16, s1
	s_ashr_i32 s9, s8, 31
	s_lshl_b32 s10, s1, 7
	s_lshl_b64 s[8:9], s[8:9], 13
	v_readlane_b32 s12, v245, 55
	v_readlane_b32 s13, v245, 56
	s_add_u32 s8, s12, s8
	s_addc_u32 s9, s13, s9
	s_ashr_i32 s11, s10, 31
	s_lshl_b64 s[10:11], s[10:11], 13
	s_add_u32 s10, s14, s10
	v_readfirstlane_b32 s1, v149
	s_addc_u32 s11, s15, s11
	s_mov_b32 m0, s1
	v_readfirstlane_b32 s1, v118
	global_load_lds_dwordx4 v125, s[8:9]
	v_lshl_add_u64 v[92:93], v[64:65], 1, s[10:11]
	s_mov_b32 m0, s1
	v_readfirstlane_b32 s1, v119
	global_load_lds_dwordx4 v[92:93], off
	s_mov_b32 m0, s1
	v_readfirstlane_b32 s1, v120
	global_load_lds_dwordx4 v126, s[8:9]
	v_lshl_add_u64 v[92:93], v[66:67], 1, s[10:11]
	s_mov_b32 m0, s1
	v_readfirstlane_b32 s1, v121
	global_load_lds_dwordx4 v[92:93], off
	s_mov_b32 m0, s1
	v_readfirstlane_b32 s1, v122
	global_load_lds_dwordx4 v127, s[8:9]
	v_lshl_add_u64 v[92:93], v[68:69], 1, s[10:11]
	s_mov_b32 m0, s1
	v_readfirstlane_b32 s1, v123
	global_load_lds_dwordx4 v[92:93], off
	s_mov_b32 m0, s1
	v_readfirstlane_b32 s1, v124
	global_load_lds_dwordx4 v128, s[8:9]
	v_lshl_add_u64 v[92:93], v[70:71], 1, s[10:11]
	s_mov_b32 m0, s1
	s_nop 0
	global_load_lds_dwordx4 v[92:93], off
	s_branch .LBB0_613

; __device__ __forceinline__ f32x4 mfma16(bf16x8 a, bf16x8 b, f32x4 c) { return __builtin_amdgcn_mfma_f32_16x16x32_bf16(a, b, c, 0, 0, 0); }
; template <class Epi>
; __device__ __forceinline__ void gemm_tile(const bf16_t* __restrict__ A, const bf16_t* __restrict__ Bt, int K, int row0, int col0, const Epi& epi, char* smem,
;                                           bool prefetched, bool nvalid, int nrow0, int ncol0) {
;     ...
;     for (int kt = 0; kt < nk; ++kt) {
;         const int cur = kt & 1;
;         if (kt + 1 < nk) GLDS_STAGE(cur ^ 1, pA, pB, kt + 1);
;         const char* cb = smem + cur * 2 * TILE_B;
; #pragma unroll
;         for (int ks = 0; ks < 2; ++ks) {
;             bf16x8 a[4], b[4];
; #pragma unroll
;             for (int m = 0; m < 4; ++m) a[m] = *(const bf16x8*)(cb + offA[m][ks]);
; #pragma unroll
;             for (int n = 0; n < 4; ++n) b[n] = *(const bf16x8*)(cb + offB[n][ks]);
; #pragma unroll
;             for (int m = 0; m < 4; ++m)
; #pragma unroll
;                 for (int n = 0; n < 4; ++n) acc[m][n] = mfma16(b[n], a[m], acc[m][n]);
;         }
;         asm volatile("s_waitcnt vmcnt(0)" ::: "memory");
;         __syncthreads();
;     }
.LBB0_723:
	v_readfirstlane_b32 s98, v64
	v_readfirstlane_b32 s99, v65
	v_readfirstlane_b32 s12, v66
	v_readfirstlane_b32 s100, v72
	v_readfirstlane_b32 s101, v73
	v_readfirstlane_b32 s15, v149
	s_nop 3
	s_sub_u32 s16, s12, s98
	s_and_b32 s98, s98, 0xffffff80
	s_and_b32 s100, s100, 0xffffff80
	s_nop 1
	v_subrev_u32_e32 v254, s98, v64
	v_subrev_u32_e32 v255, s100, v72
	s_add_i32 s14, s15, 0x8000
	s_mov_b32 m0, s14
	s_nop 1
	global_load_lds_dwordx4 v254, s[98:99]
	s_add_i32 m0, s14, 0x1000
	s_add_u32 s12, s98, s16
	s_addc_u32 s13, s99, 0
	global_load_lds_dwordx4 v254, s[12:13]
	s_add_i32 m0, s14, 0x2000
	s_add_u32 s12, s12, s16
	s_addc_u32 s13, s13, 0
	global_load_lds_dwordx4 v254, s[12:13]
	s_add_i32 m0, s14, 0x3000
	s_add_u32 s12, s12, s16
	s_addc_u32 s13, s13, 0
	global_load_lds_dwordx4 v254, s[12:13]
	s_add_u32 s98, s98, 0x80
	s_addc_u32 s99, s99, 0
	ds_read_b128 v[188:191], v137
	ds_read_b128 v[64:67], v143 offset:16384
	ds_read_b128 v[68:71], v143 offset:16896
	ds_read_b128 v[72:75], v143 offset:20480
	ds_read_b128 v[76:79], v143 offset:20992
	ds_read_b128 v[192:195], v137 offset:2048
	ds_read_b128 v[246:249], v137 offset:4096
	ds_read_b128 v[250:253], v137 offset:6144
.Lgk_loop_723:
	s_and_b32 s10, s7, 0x8000
	s_xor_b32 s11, s10, 0x8000
	s_add_i32 s14, s11, s15
	v_or_b32_e32 v179, s10, v142
	v_add_u32_e32 v196, s10, v141
	s_add_i32 m0, s14, 0x4000
	s_waitcnt lgkmcnt(6)
	v_mfma_f32_16x16x32_bf16 v[0:3], v[64:67], v[188:191], v[0:3]
	global_load_lds_dwordx4 v255, s[100:101]
	ds_read_b128 v[80:83], v179 offset:16384
	s_add_i32 m0, s14, 0x5000
	s_add_u32 s12, s100, s16
	s_addc_u32 s13, s101, 0
	s_waitcnt lgkmcnt(6)
	v_mfma_f32_16x16x32_bf16 v[4:7], v[68:71], v[188:191], v[4:7]
	global_load_lds_dwordx4 v255, s[12:13]
	ds_read_b128 v[128:131], v179 offset:16896
	s_add_i32 m0, s14, 0x6000
	s_add_u32 s12, s12, s16
	s_addc_u32 s13, s13, 0
	s_waitcnt lgkmcnt(6)
	v_mfma_f32_16x16x32_bf16 v[8:11], v[72:75], v[188:191], v[8:11]
	global_load_lds_dwordx4 v255, s[12:13]
	ds_read_b128 v[180:183], v179 offset:20480
	s_add_i32 m0, s14, 0x7000
	s_add_u32 s12, s12, s16
	s_addc_u32 s13, s13, 0
	s_waitcnt lgkmcnt(6)
	v_mfma_f32_16x16x32_bf16 v[12:15], v[76:79], v[188:191], v[12:15]
	global_load_lds_dwordx4 v255, s[12:13]
	ds_read_b128 v[184:187], v179 offset:20992
	ds_read_b128 v[188:191], v196
	s_add_u32 s100, s100, 0x80
	s_addc_u32 s101, s101, 0
	s_waitcnt lgkmcnt(7)
	v_mfma_f32_16x16x32_bf16 v[16:19], v[64:67], v[192:195], v[16:19]
	v_mfma_f32_16x16x32_bf16 v[20:23], v[68:71], v[192:195], v[20:23]
	v_mfma_f32_16x16x32_bf16 v[24:27], v[72:75], v[192:195], v[24:27]
	v_mfma_f32_16x16x32_bf16 v[28:31], v[76:79], v[192:195], v[28:31]
	ds_read_b128 v[192:195], v196 offset:2048
	s_waitcnt lgkmcnt(7)
	v_mfma_f32_16x16x32_bf16 v[32:35], v[64:67], v[246:249], v[32:35]
	v_mfma_f32_16x16x32_bf16 v[36:39], v[68:71], v[246:249], v[36:39]
	v_mfma_f32_16x16x32_bf16 v[40:43], v[72:75], v[246:249], v[40:43]
	v_mfma_f32_16x16x32_bf16 v[44:47], v[76:79], v[246:249], v[44:47]
	ds_read_b128 v[246:249], v196 offset:4096
	s_waitcnt lgkmcnt(7)
	v_mfma_f32_16x16x32_bf16 v[48:51], v[64:67], v[250:253], v[48:51]
	v_mfma_f32_16x16x32_bf16 v[52:55], v[68:71], v[250:253], v[52:55]
	v_mfma_f32_16x16x32_bf16 v[56:59], v[72:75], v[250:253], v[56:59]
	v_mfma_f32_16x16x32_bf16 v[60:63], v[76:79], v[250:253], v[60:63]
	ds_read_b128 v[250:253], v196 offset:6144
	s_waitcnt lgkmcnt(3)
	v_mfma_f32_16x16x32_bf16 v[0:3], v[80:83], v[188:191], v[0:3]
	v_mfma_f32_16x16x32_bf16 v[4:7], v[128:131], v[188:191], v[4:7]
	v_mfma_f32_16x16x32_bf16 v[8:11], v[180:183], v[188:191], v[8:11]
	v_mfma_f32_16x16x32_bf16 v[12:15], v[184:187], v[188:191], v[12:15]
	s_waitcnt lgkmcnt(2)
	v_mfma_f32_16x16x32_bf16 v[16:19], v[80:83], v[192:195], v[16:19]
	v_mfma_f32_16x16x32_bf16 v[20:23], v[128:131], v[192:195], v[20:23]
	v_mfma_f32_16x16x32_bf16 v[24:27], v[180:183], v[192:195], v[24:27]
	v_mfma_f32_16x16x32_bf16 v[28:31], v[184:187], v[192:195], v[28:31]
	s_waitcnt vmcnt(0)
	s_waitcnt lgkmcnt(0)
	s_barrier
	s_add_i32 s7, s7, 0x8000
	s_cmp_eq_u32 s7, 0x78000
	s_cbranch_scc1 .Lgk_tail_723
	v_or_b32_e32 v179, s11, v143
	v_add_u32_e32 v196, s11, v137
	s_add_i32 s14, s10, s15
	ds_read_b128 v[188:191], v196
	ds_read_b128 v[64:67], v179 offset:16384
	s_mov_b32 m0, s14
	v_mfma_f32_16x16x32_bf16 v[32:35], v[80:83], v[246:249], v[32:35]
	global_load_lds_dwordx4 v254, s[98:99]
	ds_read_b128 v[68:71], v179 offset:16896
	s_add_i32 m0, s14, 0x1000
	s_add_u32 s12, s98, s16
	s_addc_u32 s13, s99, 0
	v_mfma_f32_16x16x32_bf16 v[36:39], v[128:131], v[246:249], v[36:39]
	global_load_lds_dwordx4 v254, s[12:13]
	ds_read_b128 v[72:75], v179 offset:20480
	s_add_i32 m0, s14, 0x2000
	s_add_u32 s12, s12, s16
	s_addc_u32 s13, s13, 0
	v_mfma_f32_16x16x32_bf16 v[40:43], v[180:183], v[246:249], v[40:43]
	global_load_lds_dwordx4 v254, s[12:13]
	ds_read_b128 v[76:79], v179 offset:20992
	s_add_i32 m0, s14, 0x3000
	s_add_u32 s12, s12, s16
	s_addc_u32 s13, s13, 0
	v_mfma_f32_16x16x32_bf16 v[44:47], v[184:187], v[246:249], v[44:47]
	global_load_lds_dwordx4 v254, s[12:13]
	ds_read_b128 v[192:195], v196 offset:2048
	ds_read_b128 v[246:249], v196 offset:4096
	s_add_u32 s98, s98, 0x80
	s_addc_u32 s99, s99, 0
	v_mfma_f32_16x16x32_bf16 v[48:51], v[80:83], v[250:253], v[48:51]
	v_mfma_f32_16x16x32_bf16 v[52:55], v[128:131], v[250:253], v[52:55]
	v_mfma_f32_16x16x32_bf16 v[56:59], v[180:183], v[250:253], v[56:59]
	v_mfma_f32_16x16x32_bf16 v[60:63], v[184:187], v[250:253], v[60:63]
	ds_read_b128 v[250:253], v196 offset:6144
	s_branch .Lgk_loop_723
; __device__ __forceinline__ f32x4 mfma16(bf16x8 a, bf16x8 b, f32x4 c) { return __builtin_amdgcn_mfma_f32_16x16x32_bf16(a, b, c, 0, 0, 0); }
; template <class Epi>
; __device__ __forceinline__ void gemm_tile(const bf16_t* __restrict__ A, const bf16_t* __restrict__ Bt, int K, int row0, int col0, const Epi& epi, char* smem,
;                                           bool prefetched, bool nvalid, int nrow0, int ncol0) {
;     ...
;     for (int kt = 0; kt < nk; ++kt) {
;         const int cur = kt & 1;
;         if (kt + 1 < nk) GLDS_STAGE(cur ^ 1, pA, pB, kt + 1);
;         const char* cb = smem + cur * 2 * TILE_B;
; #pragma unroll
;         for (int ks = 0; ks < 2; ++ks) {
;             bf16x8 a[4], b[4];
; #pragma unroll
;             for (int m = 0; m < 4; ++m) a[m] = *(const bf16x8*)(cb + offA[m][ks]);
; #pragma unroll
;             for (int n = 0; n < 4; ++n) b[n] = *(const bf16x8*)(cb + offB[n][ks]);
; #pragma unroll
;             for (int m = 0; m < 4; ++m)
; #pragma unroll
;                 for (int n = 0; n < 4; ++n) acc[m][n] = mfma16(b[n], a[m], acc[m][n]);
;         }
;         asm volatile("s_waitcnt vmcnt(0)" ::: "memory");
;         __syncthreads();
;     }
;     if (nvalid) { const bf16_t* qA = A + (size_t)nrow0 * K; const bf16_t* qB = Bt + (size_t)ncol0 * K; GLDS_STAGE(0, qA, qB, 0); }
.Lgk_tail_723:
	v_mfma_f32_16x16x32_bf16 v[32:35], v[80:83], v[246:249], v[32:35]
	v_mfma_f32_16x16x32_bf16 v[36:39], v[128:131], v[246:249], v[36:39]
	v_mfma_f32_16x16x32_bf16 v[40:43], v[180:183], v[246:249], v[40:43]
	v_mfma_f32_16x16x32_bf16 v[44:47], v[184:187], v[246:249], v[44:47]
	v_mfma_f32_16x16x32_bf16 v[48:51], v[80:83], v[250:253], v[48:51]
	v_mfma_f32_16x16x32_bf16 v[52:55], v[128:131], v[250:253], v[52:55]
	v_mfma_f32_16x16x32_bf16 v[56:59], v[180:183], v[250:253], v[56:59]
	v_mfma_f32_16x16x32_bf16 v[60:63], v[184:187], v[250:253], v[60:63]
	ds_read_b128 v[64:67], v143 offset:49152
	ds_read_b128 v[68:71], v137 offset:32768
	ds_read_b128 v[72:75], v143 offset:49664
	ds_read_b128 v[76:79], v143 offset:53248
	ds_read_b128 v[80:83], v143 offset:53760
	s_add_i32 s24, s24, s58
	s_waitcnt lgkmcnt(3)
	v_mfma_f32_16x16x32_bf16 v[0:3], v[64:67], v[68:71], v[0:3]
	s_cmpk_gt_i32 s24, 0xfff
	s_cselect_b64 s[10:11], -1, 0
	s_cmpk_lt_i32 s24, 0x1000
	s_waitcnt lgkmcnt(2)
	v_mfma_f32_16x16x32_bf16 v[4:7], v[72:75], v[68:71], v[4:7]
	ds_read_b128 v[188:191], v142 offset:49152
	ds_read_b128 v[192:195], v142 offset:53760
	s_waitcnt lgkmcnt(3)
	v_mfma_f32_16x16x32_bf16 v[8:11], v[76:79], v[68:71], v[8:11]
	s_waitcnt lgkmcnt(2)
	v_mfma_f32_16x16x32_bf16 v[12:15], v[80:83], v[68:71], v[12:15]
	ds_read_b128 v[68:71], v137 offset:34816
	s_waitcnt lgkmcnt(0)
	v_mfma_f32_16x16x32_bf16 v[16:19], v[64:67], v[68:71], v[16:19]
	v_mfma_f32_16x16x32_bf16 v[20:23], v[72:75], v[68:71], v[20:23]
	v_mfma_f32_16x16x32_bf16 v[24:27], v[76:79], v[68:71], v[24:27]
	v_mfma_f32_16x16x32_bf16 v[28:31], v[80:83], v[68:71], v[28:31]
	ds_read_b128 v[68:71], v137 offset:36864
	s_waitcnt lgkmcnt(0)
	v_mfma_f32_16x16x32_bf16 v[128:131], v[64:67], v[68:71], v[32:35]
	s_nop 2
	ds_read_b128 v[32:35], v137 offset:38912
	v_mfma_f32_16x16x32_bf16 v[180:183], v[72:75], v[68:71], v[36:39]
	v_mfma_f32_16x16x32_bf16 v[184:187], v[76:79], v[68:71], v[40:43]
	v_mfma_f32_16x16x32_bf16 v[68:71], v[80:83], v[68:71], v[44:47]
	s_waitcnt lgkmcnt(0)
	v_mfma_f32_16x16x32_bf16 v[64:67], v[64:67], v[32:35], v[48:51]
	v_mfma_f32_16x16x32_bf16 v[72:75], v[72:75], v[32:35], v[52:55]
	v_mfma_f32_16x16x32_bf16 v[76:79], v[76:79], v[32:35], v[56:59]
	v_mfma_f32_16x16x32_bf16 v[80:83], v[80:83], v[32:35], v[60:63]
	ds_read_b128 v[32:35], v141 offset:32768
	s_waitcnt lgkmcnt(0)
	v_mfma_f32_16x16x32_bf16 v[56:59], v[188:191], v[32:35], v[0:3]
	s_nop 2
	ds_read_b128 v[0:3], v142 offset:49664
	s_waitcnt lgkmcnt(0)
	v_mfma_f32_16x16x32_bf16 v[60:63], v[0:3], v[32:35], v[4:7]
	s_nop 2
	ds_read_b128 v[4:7], v142 offset:53248
	s_waitcnt lgkmcnt(0)
	v_mfma_f32_16x16x32_bf16 v[48:51], v[4:7], v[32:35], v[8:11]
	s_nop 2
	ds_read_b128 v[8:11], v141 offset:34816
	v_mfma_f32_16x16x32_bf16 v[52:55], v[192:195], v[32:35], v[12:15]
	s_waitcnt lgkmcnt(0)
	v_mfma_f32_16x16x32_bf16 v[40:43], v[188:191], v[8:11], v[16:19]
	v_mfma_f32_16x16x32_bf16 v[44:47], v[0:3], v[8:11], v[20:23]
	v_mfma_f32_16x16x32_bf16 v[32:35], v[4:7], v[8:11], v[24:27]
	v_mfma_f32_16x16x32_bf16 v[36:39], v[192:195], v[8:11], v[28:31]
	ds_read_b128 v[8:11], v141 offset:36864
	s_waitcnt lgkmcnt(0)
	v_mfma_f32_16x16x32_bf16 v[20:23], v[192:195], v[8:11], v[68:71]
	s_nop 2
	ds_read_b128 v[68:71], v141 offset:38912
	s_waitcnt vmcnt(0)
	v_mfma_f32_16x16x32_bf16 v[24:27], v[188:191], v[8:11], v[128:131]
	s_waitcnt lgkmcnt(0)
	s_barrier
	v_mfma_f32_16x16x32_bf16 v[28:31], v[0:3], v[8:11], v[180:183]
	v_mfma_f32_16x16x32_bf16 v[16:19], v[4:7], v[8:11], v[184:187]
	v_mfma_f32_16x16x32_bf16 v[8:11], v[188:191], v[68:71], v[64:67]
	v_mfma_f32_16x16x32_bf16 v[12:15], v[0:3], v[68:71], v[72:75]
	v_mfma_f32_16x16x32_bf16 v[0:3], v[4:7], v[68:71], v[76:79]
	v_mfma_f32_16x16x32_bf16 v[4:7], v[192:195], v[68:71], v[80:83]
	s_cbranch_scc0 .LBB0_726
	s_ashr_i32 s0, s24, 31
	s_lshr_b32 s0, s0, 28
	s_add_i32 s1, s24, s0
	s_lshl_b32 s0, s1, 3
	s_and_b32 s1, s1, 0x1fffff0
	s_and_b32 s0, s0, 0xffffff80
	s_sub_i32 s1, s24, s1
	s_lshl_b32 s12, s1, 7
	s_ashr_i32 s1, s0, 31
	s_lshl_b64 s[0:1], s[0:1], 11
	v_readlane_b32 s7, v245, 53
	s_add_u32 s0, s7, s0
	v_readlane_b32 s7, v245, 54
	s_addc_u32 s1, s7, s1
	s_ashr_i32 s13, s12, 31
	s_lshl_b64 s[12:13], s[12:13], 11
	s_add_u32 s12, s3, s12
	v_readfirstlane_b32 s7, v149
	s_addc_u32 s13, s20, s13
	s_mov_b32 m0, s7
	v_readfirstlane_b32 s7, v163
	global_load_lds_dwordx4 v174, s[0:1]
	v_lshl_add_u64 v[64:65], v[84:85], 1, s[12:13]
	s_mov_b32 m0, s7
	v_readfirstlane_b32 s7, v164
	global_load_lds_dwordx4 v[64:65], off
	s_mov_b32 m0, s7
	v_readfirstlane_b32 s7, v165
	global_load_lds_dwordx4 v175, s[0:1]
	v_lshl_add_u64 v[64:65], v[86:87], 1, s[12:13]
	s_mov_b32 m0, s7
	v_readfirstlane_b32 s7, v166
	global_load_lds_dwordx4 v[64:65], off
	s_mov_b32 m0, s7
	v_readfirstlane_b32 s7, v170
	global_load_lds_dwordx4 v176, s[0:1]
	v_lshl_add_u64 v[64:65], v[88:89], 1, s[12:13]
	s_mov_b32 m0, s7
	v_readfirstlane_b32 s7, v171
	global_load_lds_dwordx4 v[64:65], off
	s_mov_b32 m0, s7
	v_lshl_add_u64 v[64:65], v[90:91], 1, s[12:13]
	global_load_lds_dwordx4 v177, s[0:1]
	v_readfirstlane_b32 s0, v172
	s_mov_b32 m0, s0
	s_nop 0
	global_load_lds_dwordx4 v[64:65], off

; __device__ __forceinline__ f32x4 mfma16(bf16x8 a, bf16x8 b, f32x4 c) { return __builtin_amdgcn_mfma_f32_16x16x32_bf16(a, b, c, 0, 0, 0); }
; template <class Epi>
; __device__ __forceinline__ void gemm_tile(const bf16_t* __restrict__ A, const bf16_t* __restrict__ Bt, int K, int row0, int col0, const Epi& epi, char* smem,
;                                           bool prefetched, bool nvalid, int nrow0, int ncol0) {
;     ...
;     for (int kt = 0; kt < nk; ++kt) {
;         const int cur = kt & 1;
;         if (kt + 1 < nk) GLDS_STAGE(cur ^ 1, pA, pB, kt + 1);
;         const char* cb = smem + cur * 2 * TILE_B;
; #pragma unroll
;         for (int ks = 0; ks < 2; ++ks) {
;             bf16x8 a[4], b[4];
; #pragma unroll
;             for (int m = 0; m < 4; ++m) a[m] = *(const bf16x8*)(cb + offA[m][ks]);
; #pragma unroll
;             for (int n = 0; n < 4; ++n) b[n] = *(const bf16x8*)(cb + offB[n][ks]);
; #pragma unroll
;             for (int m = 0; m < 4; ++m)
; #pragma unroll
;                 for (int n = 0; n < 4; ++n) acc[m][n] = mfma16(b[n], a[m], acc[m][n]);
;         }
;         asm volatile("s_waitcnt vmcnt(0)" ::: "memory");
;         __syncthreads();
;     }
.LBB0_766:
	v_readfirstlane_b32 s98, v106
	v_readfirstlane_b32 s99, v107
	v_readfirstlane_b32 s10, v108
	v_readfirstlane_b32 s100, v120
	v_readfirstlane_b32 s101, v121
	v_readfirstlane_b32 s13, v149
	s_nop 3
	s_sub_u32 s16, s10, s98
	s_and_b32 s98, s98, 0xffffff80
	s_and_b32 s100, s100, 0xffffff80
	s_nop 1
	v_subrev_u32_e32 v254, s98, v106
	v_subrev_u32_e32 v255, s100, v120
	s_add_i32 s12, s13, 0x8000
	s_mov_b32 m0, s12
	s_nop 1
	global_load_lds_dwordx4 v254, s[98:99]
	s_add_i32 m0, s12, 0x1000
	s_add_u32 s10, s98, s16
	s_addc_u32 s11, s99, 0
	global_load_lds_dwordx4 v254, s[10:11]
	s_add_i32 m0, s12, 0x2000
	s_add_u32 s10, s10, s16
	s_addc_u32 s11, s11, 0
	global_load_lds_dwordx4 v254, s[10:11]
	s_add_i32 m0, s12, 0x3000
	s_add_u32 s10, s10, s16
	s_addc_u32 s11, s11, 0
	global_load_lds_dwordx4 v254, s[10:11]
	s_add_u32 s98, s98, 0x80
	s_addc_u32 s99, s99, 0
	ds_read_b128 v[190:193], v128
	ds_read_b128 v[106:109], v131 offset:16384
	ds_read_b128 v[118:121], v131 offset:16896
	ds_read_b128 v[122:125], v131 offset:20480
	ds_read_b128 v[170:173], v131 offset:20992
	ds_read_b128 v[194:197], v128 offset:2048
	ds_read_b128 v[198:201], v128 offset:4096
	ds_read_b128 v[246:249], v128 offset:6144
.Lgk_loop_766:
	s_and_b32 s8, s1, 0x8000
	s_xor_b32 s9, s8, 0x8000
	s_add_i32 s12, s9, s13
	v_or_b32_e32 v164, s8, v130
	v_add_u32_e32 v165, s8, v129
	s_add_i32 m0, s12, 0x4000
	s_waitcnt lgkmcnt(6)
	v_mfma_f32_16x16x32_bf16 v[0:3], v[106:109], v[190:193], v[0:3]
	global_load_lds_dwordx4 v255, s[100:101]
	ds_read_b128 v[174:177], v164 offset:16384
	s_add_i32 m0, s12, 0x5000
	s_add_u32 s10, s100, s16
	s_addc_u32 s11, s101, 0
	s_waitcnt lgkmcnt(6)
	v_mfma_f32_16x16x32_bf16 v[4:7], v[118:121], v[190:193], v[4:7]
	global_load_lds_dwordx4 v255, s[10:11]
	ds_read_b128 v[178:181], v164 offset:16896
	s_add_i32 m0, s12, 0x6000
	s_add_u32 s10, s10, s16
	s_addc_u32 s11, s11, 0
	s_waitcnt lgkmcnt(6)
	v_mfma_f32_16x16x32_bf16 v[8:11], v[122:125], v[190:193], v[8:11]
	global_load_lds_dwordx4 v255, s[10:11]
	ds_read_b128 v[182:185], v164 offset:20480
	s_add_i32 m0, s12, 0x7000
	s_add_u32 s10, s10, s16
	s_addc_u32 s11, s11, 0
	s_waitcnt lgkmcnt(6)
	v_mfma_f32_16x16x32_bf16 v[12:15], v[170:173], v[190:193], v[12:15]
	global_load_lds_dwordx4 v255, s[10:11]
	ds_read_b128 v[186:189], v164 offset:20992
	ds_read_b128 v[190:193], v165
	s_add_u32 s100, s100, 0x80
	s_addc_u32 s101, s101, 0
	s_waitcnt lgkmcnt(7)
	v_mfma_f32_16x16x32_bf16 v[16:19], v[106:109], v[194:197], v[16:19]
	v_mfma_f32_16x16x32_bf16 v[20:23], v[118:121], v[194:197], v[20:23]
	v_mfma_f32_16x16x32_bf16 v[24:27], v[122:125], v[194:197], v[24:27]
	v_mfma_f32_16x16x32_bf16 v[28:31], v[170:173], v[194:197], v[28:31]
	ds_read_b128 v[194:197], v165 offset:2048
	s_waitcnt lgkmcnt(7)
	v_mfma_f32_16x16x32_bf16 v[32:35], v[106:109], v[198:201], v[32:35]
	v_mfma_f32_16x16x32_bf16 v[36:39], v[118:121], v[198:201], v[36:39]
	v_mfma_f32_16x16x32_bf16 v[40:43], v[122:125], v[198:201], v[40:43]
	v_mfma_f32_16x16x32_bf16 v[44:47], v[170:173], v[198:201], v[44:47]
	ds_read_b128 v[198:201], v165 offset:4096
	s_waitcnt lgkmcnt(7)
	v_mfma_f32_16x16x32_bf16 v[48:51], v[106:109], v[246:249], v[48:51]
	v_mfma_f32_16x16x32_bf16 v[52:55], v[118:121], v[246:249], v[52:55]
	v_mfma_f32_16x16x32_bf16 v[56:59], v[122:125], v[246:249], v[56:59]
	v_mfma_f32_16x16x32_bf16 v[60:63], v[170:173], v[246:249], v[60:63]
	ds_read_b128 v[246:249], v165 offset:6144
	s_waitcnt lgkmcnt(3)
	v_mfma_f32_16x16x32_bf16 v[0:3], v[174:177], v[190:193], v[0:3]
	v_mfma_f32_16x16x32_bf16 v[4:7], v[178:181], v[190:193], v[4:7]
	v_mfma_f32_16x16x32_bf16 v[8:11], v[182:185], v[190:193], v[8:11]
	v_mfma_f32_16x16x32_bf16 v[12:15], v[186:189], v[190:193], v[12:15]
	s_waitcnt lgkmcnt(2)
	v_mfma_f32_16x16x32_bf16 v[16:19], v[174:177], v[194:197], v[16:19]
	v_mfma_f32_16x16x32_bf16 v[20:23], v[178:181], v[194:197], v[20:23]
	v_mfma_f32_16x16x32_bf16 v[24:27], v[182:185], v[194:197], v[24:27]
	v_mfma_f32_16x16x32_bf16 v[28:31], v[186:189], v[194:197], v[28:31]
	s_waitcnt vmcnt(0)
	s_waitcnt lgkmcnt(0)
	s_barrier
	s_add_i32 s1, s1, 0x8000
	s_cmp_eq_u32 s1, 0x78000
	s_cbranch_scc1 .Lgk_tail_766
	v_or_b32_e32 v164, s9, v131
	v_add_u32_e32 v165, s9, v128
	s_add_i32 s12, s8, s13
	ds_read_b128 v[190:193], v165
	ds_read_b128 v[106:109], v164 offset:16384
	s_mov_b32 m0, s12
	v_mfma_f32_16x16x32_bf16 v[32:35], v[174:177], v[198:201], v[32:35]
	global_load_lds_dwordx4 v254, s[98:99]
	ds_read_b128 v[118:121], v164 offset:16896
	s_add_i32 m0, s12, 0x1000
	s_add_u32 s10, s98, s16
	s_addc_u32 s11, s99, 0
	v_mfma_f32_16x16x32_bf16 v[36:39], v[178:181], v[198:201], v[36:39]
	global_load_lds_dwordx4 v254, s[10:11]
	ds_read_b128 v[122:125], v164 offset:20480
	s_add_i32 m0, s12, 0x2000
	s_add_u32 s10, s10, s16
	s_addc_u32 s11, s11, 0
	v_mfma_f32_16x16x32_bf16 v[40:43], v[182:185], v[198:201], v[40:43]
	global_load_lds_dwordx4 v254, s[10:11]
	ds_read_b128 v[170:173], v164 offset:20992
	s_add_i32 m0, s12, 0x3000
	s_add_u32 s10, s10, s16
	s_addc_u32 s11, s11, 0
	v_mfma_f32_16x16x32_bf16 v[44:47], v[186:189], v[198:201], v[44:47]
	global_load_lds_dwordx4 v254, s[10:11]
	ds_read_b128 v[194:197], v165 offset:2048
	ds_read_b128 v[198:201], v165 offset:4096
	s_add_u32 s98, s98, 0x80
	s_addc_u32 s99, s99, 0
	v_mfma_f32_16x16x32_bf16 v[48:51], v[174:177], v[246:249], v[48:51]
	v_mfma_f32_16x16x32_bf16 v[52:55], v[178:181], v[246:249], v[52:55]
	v_mfma_f32_16x16x32_bf16 v[56:59], v[182:185], v[246:249], v[56:59]
	v_mfma_f32_16x16x32_bf16 v[60:63], v[186:189], v[246:249], v[60:63]
	ds_read_b128 v[246:249], v165 offset:6144
	s_branch .Lgk_loop_766
; __device__ __forceinline__ f32x4 mfma16(bf16x8 a, bf16x8 b, f32x4 c) { return __builtin_amdgcn_mfma_f32_16x16x32_bf16(a, b, c, 0, 0, 0); }
; template <class Epi>
; __device__ __forceinline__ void gemm_tile(const bf16_t* __restrict__ A, const bf16_t* __restrict__ Bt, int K, int row0, int col0, const Epi& epi, char* smem,
;                                           bool prefetched, bool nvalid, int nrow0, int ncol0) {
;     ...
;     for (int kt = 0; kt < nk; ++kt) {
;         const int cur = kt & 1;
;         if (kt + 1 < nk) GLDS_STAGE(cur ^ 1, pA, pB, kt + 1);
;         const char* cb = smem + cur * 2 * TILE_B;
; #pragma unroll
;         for (int ks = 0; ks < 2; ++ks) {
;             bf16x8 a[4], b[4];
; #pragma unroll
;             for (int m = 0; m < 4; ++m) a[m] = *(const bf16x8*)(cb + offA[m][ks]);
; #pragma unroll
;             for (int n = 0; n < 4; ++n) b[n] = *(const bf16x8*)(cb + offB[n][ks]);
; #pragma unroll
;             for (int m = 0; m < 4; ++m)
; #pragma unroll
;                 for (int n = 0; n < 4; ++n) acc[m][n] = mfma16(b[n], a[m], acc[m][n]);
;         }
;         asm volatile("s_waitcnt vmcnt(0)" ::: "memory");
;         __syncthreads();
;     }
;     if (nvalid) { const bf16_t* qA = A + (size_t)nrow0 * K; const bf16_t* qB = Bt + (size_t)ncol0 * K; GLDS_STAGE(0, qA, qB, 0); }
.Lgk_tail_766:
	v_mfma_f32_16x16x32_bf16 v[32:35], v[174:177], v[198:201], v[32:35]
	v_mfma_f32_16x16x32_bf16 v[36:39], v[178:181], v[198:201], v[36:39]
	v_mfma_f32_16x16x32_bf16 v[40:43], v[182:185], v[198:201], v[40:43]
	v_mfma_f32_16x16x32_bf16 v[44:47], v[186:189], v[198:201], v[44:47]
	v_mfma_f32_16x16x32_bf16 v[48:51], v[174:177], v[246:249], v[48:51]
	v_mfma_f32_16x16x32_bf16 v[52:55], v[178:181], v[246:249], v[52:55]
	v_mfma_f32_16x16x32_bf16 v[56:59], v[182:185], v[246:249], v[56:59]
	v_mfma_f32_16x16x32_bf16 v[60:63], v[186:189], v[246:249], v[60:63]
	ds_read_b128 v[106:109], v131 offset:49152
	ds_read_b128 v[118:121], v128 offset:32768
	ds_read_b128 v[122:125], v131 offset:49664
	ds_read_b128 v[170:173], v131 offset:53248
	ds_read_b128 v[174:177], v131 offset:53760
	v_readlane_b32 s1, v245, 59
	s_waitcnt lgkmcnt(3)
	v_mfma_f32_16x16x32_bf16 v[0:3], v[106:109], v[118:121], v[0:3]
	s_add_i32 s1, s1, s58
	s_cmpk_gt_i32 s1, 0x7ff
	s_cselect_b64 s[6:7], -1, 0
	s_waitcnt lgkmcnt(2)
	v_mfma_f32_16x16x32_bf16 v[4:7], v[122:125], v[118:121], v[4:7]
	ds_read_b128 v[190:193], v130 offset:49152
	s_cmpk_lt_i32 s1, 0x800
	v_writelane_b32 v245, s1, 59
	s_waitcnt lgkmcnt(2)
	v_mfma_f32_16x16x32_bf16 v[8:11], v[170:173], v[118:121], v[8:11]
	ds_read_b128 v[194:197], v130 offset:53248
	ds_read_b128 v[198:201], v130 offset:53760
	s_waitcnt lgkmcnt(3)
	v_mfma_f32_16x16x32_bf16 v[12:15], v[174:177], v[118:121], v[12:15]
	ds_read_b128 v[118:121], v128 offset:34816
	s_waitcnt lgkmcnt(0)
	v_mfma_f32_16x16x32_bf16 v[16:19], v[106:109], v[118:121], v[16:19]
	v_mfma_f32_16x16x32_bf16 v[20:23], v[122:125], v[118:121], v[20:23]
	v_mfma_f32_16x16x32_bf16 v[24:27], v[170:173], v[118:121], v[24:27]
	v_mfma_f32_16x16x32_bf16 v[28:31], v[174:177], v[118:121], v[28:31]
	ds_read_b128 v[118:121], v128 offset:36864
	s_waitcnt lgkmcnt(0)
	v_mfma_f32_16x16x32_bf16 v[178:181], v[106:109], v[118:121], v[32:35]
	s_nop 2
	ds_read_b128 v[32:35], v128 offset:38912
	v_mfma_f32_16x16x32_bf16 v[182:185], v[122:125], v[118:121], v[36:39]
	v_mfma_f32_16x16x32_bf16 v[186:189], v[170:173], v[118:121], v[40:43]
	v_mfma_f32_16x16x32_bf16 v[118:121], v[174:177], v[118:121], v[44:47]
	s_waitcnt lgkmcnt(0)
	v_mfma_f32_16x16x32_bf16 v[106:109], v[106:109], v[32:35], v[48:51]
	v_mfma_f32_16x16x32_bf16 v[122:125], v[122:125], v[32:35], v[52:55]
	v_mfma_f32_16x16x32_bf16 v[170:173], v[170:173], v[32:35], v[56:59]
	v_mfma_f32_16x16x32_bf16 v[174:177], v[174:177], v[32:35], v[60:63]
	ds_read_b128 v[32:35], v129 offset:32768
	s_waitcnt lgkmcnt(0)
	v_mfma_f32_16x16x32_bf16 v[56:59], v[190:193], v[32:35], v[0:3]
	s_nop 2
	ds_read_b128 v[0:3], v130 offset:49664
	s_waitcnt lgkmcnt(0)
	v_mfma_f32_16x16x32_bf16 v[60:63], v[0:3], v[32:35], v[4:7]
	s_nop 2
	ds_read_b128 v[4:7], v129 offset:34816
	v_mfma_f32_16x16x32_bf16 v[48:51], v[194:197], v[32:35], v[8:11]
	v_mfma_f32_16x16x32_bf16 v[52:55], v[198:201], v[32:35], v[12:15]
	s_nop 2
	ds_read_b128 v[12:15], v129 offset:38912
	s_waitcnt lgkmcnt(1)
	v_mfma_f32_16x16x32_bf16 v[44:47], v[190:193], v[4:7], v[16:19]
	v_mfma_f32_16x16x32_bf16 v[40:43], v[0:3], v[4:7], v[20:23]
	v_mfma_f32_16x16x32_bf16 v[36:39], v[194:197], v[4:7], v[24:27]
	v_mfma_f32_16x16x32_bf16 v[32:35], v[198:201], v[4:7], v[28:31]
	ds_read_b128 v[4:7], v129 offset:36864
	s_waitcnt vmcnt(0)
	s_waitcnt lgkmcnt(0)
	v_mfma_f32_16x16x32_bf16 v[28:31], v[190:193], v[4:7], v[178:181]
	s_barrier
	v_mfma_f32_16x16x32_bf16 v[24:27], v[0:3], v[4:7], v[182:185]
	v_mfma_f32_16x16x32_bf16 v[20:23], v[194:197], v[4:7], v[186:189]
	v_mfma_f32_16x16x32_bf16 v[16:19], v[198:201], v[4:7], v[118:121]
	v_mfma_f32_16x16x32_bf16 v[4:7], v[190:193], v[12:15], v[106:109]
	v_mfma_f32_16x16x32_bf16 v[8:11], v[0:3], v[12:15], v[122:125]
	v_mfma_f32_16x16x32_bf16 v[0:3], v[194:197], v[12:15], v[170:173]
	v_mfma_f32_16x16x32_bf16 v[12:15], v[198:201], v[12:15], v[174:177]
	s_cbranch_scc0 .LBB0_760
	v_readlane_b32 s9, v245, 59
	s_ashr_i32 s1, s9, 31
	s_lshr_b32 s1, s1, 29
	s_add_i32 s1, s9, s1
	s_and_b32 s8, s1, 0x1fffff8
	s_sub_i32 s8, s9, s8
	s_lshl_b32 s8, s8, 7
	s_lshl_b32 s1, s1, 4
	s_ashr_i32 s9, s8, 31
	s_and_b32 s10, s1, 0xffffff80
	s_lshl_b64 s[8:9], s[8:9], 11
	s_add_u32 s8, s14, s8
	s_addc_u32 s9, s15, s9
	s_ashr_i32 s11, s10, 31
	s_lshl_b64 s[10:11], s[10:11], 11
	v_readlane_b32 s1, v245, 53
	s_add_u32 s10, s1, s10
	v_readlane_b32 s1, v245, 54
	s_addc_u32 s11, s1, s11
	v_readfirstlane_b32 s1, v149
	s_mov_b32 m0, s1
	v_readfirstlane_b32 s1, v132
	global_load_lds_dwordx4 v144, s[8:9]
	v_lshl_add_u64 v[106:107], v[64:65], 1, s[10:11]
	s_mov_b32 m0, s1
	v_readfirstlane_b32 s1, v133
	global_load_lds_dwordx4 v[106:107], off
	s_mov_b32 m0, s1
	v_readfirstlane_b32 s1, v134
	global_load_lds_dwordx4 v145, s[8:9]
	v_lshl_add_u64 v[106:107], v[66:67], 1, s[10:11]
	s_mov_b32 m0, s1
	v_readfirstlane_b32 s1, v135
	global_load_lds_dwordx4 v[106:107], off
	s_mov_b32 m0, s1
	v_readfirstlane_b32 s1, v136
	global_load_lds_dwordx4 v162, s[8:9]
	v_lshl_add_u64 v[106:107], v[68:69], 1, s[10:11]
	s_mov_b32 m0, s1
	v_readfirstlane_b32 s1, v137
	global_load_lds_dwordx4 v[106:107], off
	s_mov_b32 m0, s1
	v_readfirstlane_b32 s1, v141
	global_load_lds_dwordx4 v163, s[8:9]
	v_lshl_add_u64 v[106:107], v[70:71], 1, s[10:11]
	s_mov_b32 m0, s1
	s_nop 0
	global_load_lds_dwordx4 v[106:107], off
	s_branch .LBB0_760

; __device__ __forceinline__ f32x4 mfma16(bf16x8 a, bf16x8 b, f32x4 c) { return __builtin_amdgcn_mfma_f32_16x16x32_bf16(a, b, c, 0, 0, 0); }
; template <int KW, int VD, bool SEL> ...
;     ...
;     while (true) {
;         int jn = -1;
;         if (tiles) { jn = __ffsll((long long)tiles) - 1; tiles &= tiles - 1; FL_ISSUE(cur ^ 1, jn); }
;         const char* sK = smem + cur * BUFB;
;         const char* sV = smem + cur * BUFB + KB;
;         f32x4 s[2][4];
;         const float mref0 = (mrow[0] < -1e29f) ? 0.f : mrow[0], mref1 = (mrow[1] < -1e29f) ? 0.f : mrow[1];
;         const float ci0 = (SEL && !((((const u64*)(smem + 69632))[fr] >> j) & 1ull)) ? -1e30f : -mref0;
;         const float ci1 = (SEL && !((((const u64*)(smem + 69632))[16 + fr] >> j) & 1ull)) ? -1e30f : -mref1;
;         const f32x4 cinit0 = (f32x4){ci0, ci0, ci0, ci0}, cinit1 = (f32x4){ci1, ci1, ci1, ci1};
; #pragma unroll
;         for (int tt = 0; tt < 4; ++tt) {
;             const int kr = 32 * (tt >> 1) + (fr >> 2) * 8 + (tt & 1) * 4 + (fr & 3);
;             const bf16x8 kf0 = *(const bf16x8*)(sK + kr * KROWB + (((kcol >> 3) + fq) ^ kswz) * 16);
;             const bf16x8 kf1 = *(const bf16x8*)(sK + kr * KROWB + (((kcol >> 3) + 4 + fq) ^ kswz) * 16);
;             s[0][tt] = mfma16(kf0, qf[0][0], cinit0);
;             s[1][tt] = mfma16(kf0, qf[1][0], cinit1);
;             s[0][tt] = mfma16(kf1, qf[0][1], s[0][tt]);
;             s[1][tt] = mfma16(kf1, qf[1][1], s[1][tt]);
;         }
;         const bool pm = (j * 64 + 63 > tmin) || (j * 64 <= lomax);
.LBB0_824:
	v_add_u32_e32 v100, s26, v179
	v_add_u32_e32 v185, v100, v175
	ds_read_b128 v[80:83], v185
	ds_read_b128 v[92:95], v185 offset:1024
	v_cmp_ngt_f32_e32 vcc, s13, v182
	v_add_u32_e32 v194, v100, v176
	ds_read_b128 v[100:103], v194
	ds_read_b128 v[186:189], v194 offset:1024
	v_cndmask_b32_e32 v199, 0, v182, vcc
	v_cmp_ngt_f32_e32 vcc, s13, v183
	v_xor_b32_e32 v84, 0x80000000, v199
	v_mov_b32_e32 v85, v84
	v_cndmask_b32_e32 v184, 0, v183, vcc
	v_xor_b32_e32 v88, 0x80000000, v184
	v_mov_b32_e32 v86, v84
	v_mov_b32_e32 v87, v84
	v_mov_b32_e32 v89, v88
	v_mov_b32_e32 v90, v88
	v_mov_b32_e32 v91, v88
	s_waitcnt lgkmcnt(0)
	v_mfma_f32_16x16x32_bf16 v[96:99], v[80:83], v[64:67], v[84:87]
	s_lshl_b32 s27, s10, 6
	s_or_b32 s10, s27, 63
	s_cmp_le_u32 s10, s19
	v_mfma_f32_16x16x32_bf16 v[80:83], v[80:83], v[72:75], v[88:91]
	s_cselect_b64 s[8:9], -1, 0
	s_cmp_gt_u32 s10, s19
	s_mov_b64 s[10:11], -1
	v_mfma_f32_16x16x32_bf16 v[108:111], v[100:103], v[68:71], v[96:99]
	v_mfma_f32_16x16x32_bf16 v[96:99], v[100:103], v[76:79], v[80:83]
	v_mfma_f32_16x16x32_bf16 v[80:83], v[92:95], v[64:67], v[84:87]
	v_mfma_f32_16x16x32_bf16 v[92:95], v[92:95], v[72:75], v[88:91]
	v_mfma_f32_16x16x32_bf16 v[104:107], v[186:189], v[68:71], v[80:83]
	v_mfma_f32_16x16x32_bf16 v[100:103], v[186:189], v[76:79], v[92:95]
	s_nop 4
	ds_read_b128 v[80:83], v185 offset:8192
	ds_read_b128 v[186:189], v185 offset:9216
	ds_read_b128 v[190:193], v194 offset:8192
	ds_read_b128 v[194:197], v194 offset:9216
	s_waitcnt lgkmcnt(3)
	v_mfma_f32_16x16x32_bf16 v[92:95], v[80:83], v[64:67], v[84:87]
	v_mfma_f32_16x16x32_bf16 v[80:83], v[80:83], v[72:75], v[88:91]
	s_waitcnt lgkmcnt(2)
	v_mfma_f32_16x16x32_bf16 v[84:87], v[186:189], v[64:67], v[84:87]
	v_mfma_f32_16x16x32_bf16 v[186:189], v[186:189], v[72:75], v[88:91]
	s_waitcnt lgkmcnt(1)
	v_mfma_f32_16x16x32_bf16 v[92:95], v[190:193], v[68:71], v[92:95]
	v_mfma_f32_16x16x32_bf16 v[80:83], v[190:193], v[76:79], v[80:83]
	s_waitcnt lgkmcnt(0)
	v_mfma_f32_16x16x32_bf16 v[88:91], v[194:197], v[68:71], v[84:87]
	v_mfma_f32_16x16x32_bf16 v[84:87], v[194:197], v[76:79], v[186:189]
	s_cbranch_scc1 .LBB0_826
	s_mov_b64 s[10:11], 0

; __device__ __forceinline__ f32x4 mfma16(bf16x8 a, bf16x8 b, f32x4 c) { return __builtin_amdgcn_mfma_f32_16x16x32_bf16(a, b, c, 0, 0, 0); }
; template <class Epi>
; __device__ __forceinline__ void gemm_tile(const bf16_t* __restrict__ A, const bf16_t* __restrict__ Bt, int K, int row0, int col0, const Epi& epi, char* smem,
;                                           bool prefetched, bool nvalid, int nrow0, int ncol0) {
;     ...
;     for (int kt = 0; kt < nk; ++kt) {
;         const int cur = kt & 1;
;         if (kt + 1 < nk) GLDS_STAGE(cur ^ 1, pA, pB, kt + 1);
;         const char* cb = smem + cur * 2 * TILE_B;
; #pragma unroll
;         for (int ks = 0; ks < 2; ++ks) {
;             bf16x8 a[4], b[4];
; #pragma unroll
;             for (int m = 0; m < 4; ++m) a[m] = *(const bf16x8*)(cb + offA[m][ks]);
; #pragma unroll
;             for (int n = 0; n < 4; ++n) b[n] = *(const bf16x8*)(cb + offB[n][ks]);
; #pragma unroll
;             for (int m = 0; m < 4; ++m)
; #pragma unroll
;                 for (int n = 0; n < 4; ++n) acc[m][n] = mfma16(b[n], a[m], acc[m][n]);
;         }
;         asm volatile("s_waitcnt vmcnt(0)" ::: "memory");
;         __syncthreads();
;     }
.Lgk_loop_895:
	s_and_b32 s3, s1, 0x8000
	s_xor_b32 s10, s3, 0x8000
	s_add_i32 s11, s10, s12
	v_or_b32_e32 v131, s3, v111
	v_add_u32_e32 v144, s3, v109
	s_add_i32 m0, s11, 0x4000
	s_waitcnt lgkmcnt(6)
	v_mfma_f32_16x16x32_bf16 v[0:3], v[92:95], v[174:177], v[0:3]
	global_load_lds_dwordx4 v255, s[100:101]
	ds_read_b128 v[132:135], v131 offset:16384
	s_add_i32 m0, s11, 0x5000
	s_add_u32 s8, s100, s13
	s_addc_u32 s9, s101, 0
	s_waitcnt lgkmcnt(6)
	v_mfma_f32_16x16x32_bf16 v[4:7], v[96:99], v[174:177], v[4:7]
	global_load_lds_dwordx4 v255, s[8:9]
	ds_read_b128 v[136:139], v131 offset:16896
	s_add_i32 m0, s11, 0x6000
	s_add_u32 s8, s8, s13
	s_addc_u32 s9, s9, 0
	s_waitcnt lgkmcnt(6)
	v_mfma_f32_16x16x32_bf16 v[8:11], v[100:103], v[174:177], v[8:11]
	global_load_lds_dwordx4 v255, s[8:9]
	ds_read_b128 v[140:143], v131 offset:20480
	s_add_i32 m0, s11, 0x7000
	s_add_u32 s8, s8, s13
	s_addc_u32 s9, s9, 0
	s_waitcnt lgkmcnt(6)
	v_mfma_f32_16x16x32_bf16 v[12:15], v[104:107], v[174:177], v[12:15]
	global_load_lds_dwordx4 v255, s[8:9]
	ds_read_b128 v[170:173], v131 offset:20992
	ds_read_b128 v[174:177], v144
	s_add_u32 s100, s100, 0x80
	s_addc_u32 s101, s101, 0
	s_waitcnt lgkmcnt(7)
	v_mfma_f32_16x16x32_bf16 v[16:19], v[92:95], v[178:181], v[16:19]
	v_mfma_f32_16x16x32_bf16 v[20:23], v[96:99], v[178:181], v[20:23]
	v_mfma_f32_16x16x32_bf16 v[24:27], v[100:103], v[178:181], v[24:27]
	v_mfma_f32_16x16x32_bf16 v[28:31], v[104:107], v[178:181], v[28:31]
	ds_read_b128 v[178:181], v144 offset:2048
	s_waitcnt lgkmcnt(7)
	v_mfma_f32_16x16x32_bf16 v[32:35], v[92:95], v[246:249], v[32:35]
	v_mfma_f32_16x16x32_bf16 v[36:39], v[96:99], v[246:249], v[36:39]
	v_mfma_f32_16x16x32_bf16 v[40:43], v[100:103], v[246:249], v[40:43]
	v_mfma_f32_16x16x32_bf16 v[44:47], v[104:107], v[246:249], v[44:47]
	ds_read_b128 v[246:249], v144 offset:4096
	s_waitcnt lgkmcnt(7)
	v_mfma_f32_16x16x32_bf16 v[48:51], v[92:95], v[250:253], v[48:51]
	v_mfma_f32_16x16x32_bf16 v[52:55], v[96:99], v[250:253], v[52:55]
	v_mfma_f32_16x16x32_bf16 v[56:59], v[100:103], v[250:253], v[56:59]
	v_mfma_f32_16x16x32_bf16 v[60:63], v[104:107], v[250:253], v[60:63]
	ds_read_b128 v[250:253], v144 offset:6144
	s_waitcnt lgkmcnt(3)
	v_mfma_f32_16x16x32_bf16 v[0:3], v[132:135], v[174:177], v[0:3]
	v_mfma_f32_16x16x32_bf16 v[4:7], v[136:139], v[174:177], v[4:7]
	v_mfma_f32_16x16x32_bf16 v[8:11], v[140:143], v[174:177], v[8:11]
	v_mfma_f32_16x16x32_bf16 v[12:15], v[170:173], v[174:177], v[12:15]
	s_waitcnt lgkmcnt(2)
	v_mfma_f32_16x16x32_bf16 v[16:19], v[132:135], v[178:181], v[16:19]
	v_mfma_f32_16x16x32_bf16 v[20:23], v[136:139], v[178:181], v[20:23]
	v_mfma_f32_16x16x32_bf16 v[24:27], v[140:143], v[178:181], v[24:27]
	v_mfma_f32_16x16x32_bf16 v[28:31], v[170:173], v[178:181], v[28:31]
	s_waitcnt vmcnt(0)
	s_waitcnt lgkmcnt(0)
	s_barrier
	s_add_i32 s1, s1, 0x8000
	s_cmp_eq_u32 s1, 0x78000
	s_cbranch_scc1 .Lgk_tail_895
	v_or_b32_e32 v131, s10, v110
	v_add_u32_e32 v144, s10, v108
	s_add_i32 s11, s3, s12
	ds_read_b128 v[174:177], v144
	ds_read_b128 v[92:95], v131 offset:16384
	s_mov_b32 m0, s11
	v_mfma_f32_16x16x32_bf16 v[32:35], v[132:135], v[246:249], v[32:35]
	global_load_lds_dwordx4 v254, s[98:99]
	ds_read_b128 v[96:99], v131 offset:16896
	s_add_i32 m0, s11, 0x1000
	s_add_u32 s8, s98, s13
	s_addc_u32 s9, s99, 0
	v_mfma_f32_16x16x32_bf16 v[36:39], v[136:139], v[246:249], v[36:39]
	global_load_lds_dwordx4 v254, s[8:9]
	ds_read_b128 v[100:103], v131 offset:20480
	s_add_i32 m0, s11, 0x2000
	s_add_u32 s8, s8, s13
	s_addc_u32 s9, s9, 0
	v_mfma_f32_16x16x32_bf16 v[40:43], v[140:143], v[246:249], v[40:43]
	global_load_lds_dwordx4 v254, s[8:9]
	ds_read_b128 v[104:107], v131 offset:20992
	s_add_i32 m0, s11, 0x3000
	s_add_u32 s8, s8, s13
	s_addc_u32 s9, s9, 0
	v_mfma_f32_16x16x32_bf16 v[44:47], v[170:173], v[246:249], v[44:47]
	global_load_lds_dwordx4 v254, s[8:9]
	ds_read_b128 v[178:181], v144 offset:2048
	ds_read_b128 v[246:249], v144 offset:4096
	s_add_u32 s98, s98, 0x80
	s_addc_u32 s99, s99, 0
	v_mfma_f32_16x16x32_bf16 v[48:51], v[132:135], v[250:253], v[48:51]
	v_mfma_f32_16x16x32_bf16 v[52:55], v[136:139], v[250:253], v[52:55]
	v_mfma_f32_16x16x32_bf16 v[56:59], v[140:143], v[250:253], v[56:59]
	v_mfma_f32_16x16x32_bf16 v[60:63], v[170:173], v[250:253], v[60:63]
	ds_read_b128 v[250:253], v144 offset:6144
	s_branch .Lgk_loop_895
; __device__ __forceinline__ f32x4 mfma16(bf16x8 a, bf16x8 b, f32x4 c) { return __builtin_amdgcn_mfma_f32_16x16x32_bf16(a, b, c, 0, 0, 0); }
; template <class Epi>
; __device__ __forceinline__ void gemm_tile(const bf16_t* __restrict__ A, const bf16_t* __restrict__ Bt, int K, int row0, int col0, const Epi& epi, char* smem,
;                                           bool prefetched, bool nvalid, int nrow0, int ncol0) {
;     ...
;     for (int kt = 0; kt < nk; ++kt) {
;         const int cur = kt & 1;
;         if (kt + 1 < nk) GLDS_STAGE(cur ^ 1, pA, pB, kt + 1);
;         const char* cb = smem + cur * 2 * TILE_B;
; #pragma unroll
;         for (int ks = 0; ks < 2; ++ks) {
;             bf16x8 a[4], b[4];
; #pragma unroll
;             for (int m = 0; m < 4; ++m) a[m] = *(const bf16x8*)(cb + offA[m][ks]);
; #pragma unroll
;             for (int n = 0; n < 4; ++n) b[n] = *(const bf16x8*)(cb + offB[n][ks]);
; #pragma unroll
;             for (int m = 0; m < 4; ++m)
; #pragma unroll
;                 for (int n = 0; n < 4; ++n) acc[m][n] = mfma16(b[n], a[m], acc[m][n]);
;         }
;         asm volatile("s_waitcnt vmcnt(0)" ::: "memory");
;         __syncthreads();
;     }
;     if (nvalid) { const bf16_t* qA = A + (size_t)nrow0 * K; const bf16_t* qB = Bt + (size_t)ncol0 * K; GLDS_STAGE(0, qA, qB, 0); }
.Lgk_tail_895:
	v_mfma_f32_16x16x32_bf16 v[32:35], v[132:135], v[246:249], v[32:35]
	v_mfma_f32_16x16x32_bf16 v[36:39], v[136:139], v[246:249], v[36:39]
	v_mfma_f32_16x16x32_bf16 v[40:43], v[140:143], v[246:249], v[40:43]
	v_mfma_f32_16x16x32_bf16 v[44:47], v[170:173], v[246:249], v[44:47]
	v_mfma_f32_16x16x32_bf16 v[48:51], v[132:135], v[250:253], v[48:51]
	v_mfma_f32_16x16x32_bf16 v[52:55], v[136:139], v[250:253], v[52:55]
	v_mfma_f32_16x16x32_bf16 v[56:59], v[140:143], v[250:253], v[56:59]
	v_mfma_f32_16x16x32_bf16 v[60:63], v[170:173], v[250:253], v[60:63]
	ds_read_b128 v[92:95], v110 offset:49152
	ds_read_b128 v[96:99], v110 offset:49664
	ds_read_b128 v[100:103], v108 offset:32768
	ds_read_b128 v[104:107], v108 offset:34816
	ds_read_b128 v[132:135], v110 offset:53248
	ds_read_b128 v[136:139], v110 offset:53760
	s_add_i32 s16, s16, s58
	s_waitcnt lgkmcnt(3)
	v_mfma_f32_16x16x32_bf16 v[0:3], v[92:95], v[100:103], v[0:3]
	s_cmpk_gt_i32 s16, 0x7ff
	s_cselect_b64 s[6:7], -1, 0
	s_cmpk_lt_i32 s16, 0x800
	v_mfma_f32_16x16x32_bf16 v[4:7], v[96:99], v[100:103], v[4:7]
	s_waitcnt lgkmcnt(1)
	v_mfma_f32_16x16x32_bf16 v[8:11], v[132:135], v[100:103], v[8:11]
	s_waitcnt lgkmcnt(0)
	v_mfma_f32_16x16x32_bf16 v[12:15], v[136:139], v[100:103], v[12:15]
	v_mfma_f32_16x16x32_bf16 v[16:19], v[92:95], v[104:107], v[16:19]
	v_mfma_f32_16x16x32_bf16 v[20:23], v[96:99], v[104:107], v[20:23]
	v_mfma_f32_16x16x32_bf16 v[24:27], v[132:135], v[104:107], v[24:27]
	v_mfma_f32_16x16x32_bf16 v[28:31], v[136:139], v[104:107], v[28:31]
	ds_read_b128 v[100:103], v108 offset:36864
	ds_read_b128 v[104:107], v108 offset:38912
	ds_read_b128 v[178:181], v111 offset:49152
	s_waitcnt lgkmcnt(2)
	v_mfma_f32_16x16x32_bf16 v[140:143], v[92:95], v[100:103], v[32:35]
	v_mfma_f32_16x16x32_bf16 v[170:173], v[96:99], v[100:103], v[36:39]
	v_mfma_f32_16x16x32_bf16 v[174:177], v[132:135], v[100:103], v[40:43]
	v_mfma_f32_16x16x32_bf16 v[100:103], v[136:139], v[100:103], v[44:47]
	s_waitcnt lgkmcnt(1)
	v_mfma_f32_16x16x32_bf16 v[92:95], v[92:95], v[104:107], v[48:51]
	v_mfma_f32_16x16x32_bf16 v[96:99], v[96:99], v[104:107], v[52:55]
	v_mfma_f32_16x16x32_bf16 v[132:135], v[132:135], v[104:107], v[56:59]
	v_mfma_f32_16x16x32_bf16 v[104:107], v[136:139], v[104:107], v[60:63]
	ds_read_b128 v[136:139], v111 offset:49664
	ds_read_b128 v[32:35], v109 offset:32768
	ds_read_b128 v[36:39], v109 offset:34816
	ds_read_b128 v[182:185], v111 offset:53760
	s_waitcnt lgkmcnt(2)
	v_mfma_f32_16x16x32_bf16 v[52:55], v[178:181], v[32:35], v[0:3]
	s_nop 2
	ds_read_b128 v[0:3], v111 offset:53248
	v_mfma_f32_16x16x32_bf16 v[56:59], v[136:139], v[32:35], v[4:7]
	s_nop 2
	ds_read_b128 v[4:7], v109 offset:36864
	ds_read_b128 v[186:189], v109 offset:38912
	s_waitcnt vmcnt(0)
	s_waitcnt lgkmcnt(0)
	v_mfma_f32_16x16x32_bf16 v[60:63], v[0:3], v[32:35], v[8:11]
	s_barrier
	v_mfma_f32_16x16x32_bf16 v[48:51], v[182:185], v[32:35], v[12:15]
	v_mfma_f32_16x16x32_bf16 v[44:47], v[178:181], v[36:39], v[16:19]
	v_mfma_f32_16x16x32_bf16 v[40:43], v[136:139], v[36:39], v[20:23]
	v_mfma_f32_16x16x32_bf16 v[32:35], v[0:3], v[36:39], v[24:27]
	v_mfma_f32_16x16x32_bf16 v[24:27], v[182:185], v[36:39], v[28:31]
	v_mfma_f32_16x16x32_bf16 v[36:39], v[178:181], v[4:7], v[140:143]
	v_mfma_f32_16x16x32_bf16 v[28:31], v[136:139], v[4:7], v[170:173]
	v_mfma_f32_16x16x32_bf16 v[20:23], v[0:3], v[4:7], v[174:177]
	v_mfma_f32_16x16x32_bf16 v[16:19], v[182:185], v[4:7], v[100:103]
	v_mfma_f32_16x16x32_bf16 v[12:15], v[178:181], v[186:189], v[92:95]
	v_mfma_f32_16x16x32_bf16 v[8:11], v[136:139], v[186:189], v[96:99]
	v_mfma_f32_16x16x32_bf16 v[4:7], v[0:3], v[186:189], v[132:135]
	v_mfma_f32_16x16x32_bf16 v[0:3], v[182:185], v[186:189], v[104:107]
	s_cbranch_scc0 .LBB0_889
	s_ashr_i32 s1, s16, 31
	s_lshr_b32 s1, s1, 29
	s_add_i32 s1, s16, s1
	s_lshl_b32 s3, s1, 4
	s_and_b32 s8, s3, 0xffffff80
	s_and_b32 s1, s1, 0x1fffff8
	s_sub_i32 s1, s16, s1
	s_ashr_i32 s9, s8, 31
	s_lshl_b32 s10, s1, 7
	s_lshl_b64 s[8:9], s[8:9], 11
	v_readlane_b32 s12, v245, 60
	v_readlane_b32 s13, v245, 61
	s_add_u32 s8, s12, s8
	s_addc_u32 s9, s13, s9
	s_ashr_i32 s11, s10, 31
	s_lshl_b64 s[10:11], s[10:11], 11
	s_add_u32 s10, s14, s10
	v_readfirstlane_b32 s1, v149
	s_addc_u32 s11, s15, s11
	s_mov_b32 m0, s1
	v_readfirstlane_b32 s1, v118
	global_load_lds_dwordx4 v125, s[8:9]
	v_lshl_add_u64 v[92:93], v[64:65], 1, s[10:11]
	s_mov_b32 m0, s1
	v_readfirstlane_b32 s1, v119
	global_load_lds_dwordx4 v[92:93], off
	s_mov_b32 m0, s1
	v_readfirstlane_b32 s1, v120
	global_load_lds_dwordx4 v126, s[8:9]
	v_lshl_add_u64 v[92:93], v[66:67], 1, s[10:11]
	s_mov_b32 m0, s1
	v_readfirstlane_b32 s1, v121
	global_load_lds_dwordx4 v[92:93], off
	s_mov_b32 m0, s1
	v_readfirstlane_b32 s1, v122
	global_load_lds_dwordx4 v127, s[8:9]
	v_lshl_add_u64 v[92:93], v[68:69], 1, s[10:11]
	s_mov_b32 m0, s1
	v_readfirstlane_b32 s1, v123
	global_load_lds_dwordx4 v[92:93], off
	s_mov_b32 m0, s1
	v_readfirstlane_b32 s1, v124
	global_load_lds_dwordx4 v130, s[8:9]
	v_lshl_add_u64 v[92:93], v[70:71], 1, s[10:11]
	s_mov_b32 m0, s1
	s_nop 0
	global_load_lds_dwordx4 v[92:93], off
	s_branch .LBB0_889

; __device__ __forceinline__ f32x4 mfma16(bf16x8 a, bf16x8 b, f32x4 c) { return __builtin_amdgcn_mfma_f32_16x16x32_bf16(a, b, c, 0, 0, 0); }
; template <class Epi>
; __device__ __forceinline__ void gemm_tile(const bf16_t* __restrict__ A, const bf16_t* __restrict__ Bt, int K, int row0, int col0, const Epi& epi, char* smem,
;                                           bool prefetched, bool nvalid, int nrow0, int ncol0) {
;     ...
;     for (int kt = 0; kt < nk; ++kt) {
;         const int cur = kt & 1;
;         if (kt + 1 < nk) GLDS_STAGE(cur ^ 1, pA, pB, kt + 1);
;         const char* cb = smem + cur * 2 * TILE_B;
; #pragma unroll
;         for (int ks = 0; ks < 2; ++ks) {
;             bf16x8 a[4], b[4];
; #pragma unroll
;             for (int m = 0; m < 4; ++m) a[m] = *(const bf16x8*)(cb + offA[m][ks]);
; #pragma unroll
;             for (int n = 0; n < 4; ++n) b[n] = *(const bf16x8*)(cb + offB[n][ks]);
; #pragma unroll
;             for (int m = 0; m < 4; ++m)
; #pragma unroll
;                 for (int n = 0; n < 4; ++n) acc[m][n] = mfma16(b[n], a[m], acc[m][n]);
;         }
;         asm volatile("s_waitcnt vmcnt(0)" ::: "memory");
;         __syncthreads();
;     }
.LBB0_998:
	v_readfirstlane_b32 s98, v106
	v_readfirstlane_b32 s99, v107
	v_readfirstlane_b32 s10, v108
	v_readfirstlane_b32 s100, v120
	v_readfirstlane_b32 s101, v121
	v_readfirstlane_b32 s17, v149
	s_nop 3
	s_sub_u32 s18, s10, s98
	s_and_b32 s98, s98, 0xffffff80
	s_and_b32 s100, s100, 0xffffff80
	s_nop 1
	v_subrev_u32_e32 v254, s98, v106
	v_subrev_u32_e32 v255, s100, v120
	s_add_i32 s13, s17, 0x8000
	s_mov_b32 m0, s13
	s_nop 1
	global_load_lds_dwordx4 v254, s[98:99]
	s_add_i32 m0, s13, 0x1000
	s_add_u32 s10, s98, s18
	s_addc_u32 s11, s99, 0
	global_load_lds_dwordx4 v254, s[10:11]
	s_add_i32 m0, s13, 0x2000
	s_add_u32 s10, s10, s18
	s_addc_u32 s11, s11, 0
	global_load_lds_dwordx4 v254, s[10:11]
	s_add_i32 m0, s13, 0x3000
	s_add_u32 s10, s10, s18
	s_addc_u32 s11, s11, 0
	global_load_lds_dwordx4 v254, s[10:11]
	s_add_u32 s98, s98, 0x80
	s_addc_u32 s99, s99, 0
	ds_read_b128 v[184:187], v130
	ds_read_b128 v[106:109], v133 offset:16384
	ds_read_b128 v[118:121], v133 offset:16896
	ds_read_b128 v[122:125], v133 offset:20480
	ds_read_b128 v[158:161], v133 offset:20992
	ds_read_b128 v[188:191], v130 offset:2048
	ds_read_b128 v[246:249], v130 offset:4096
	ds_read_b128 v[250:253], v130 offset:6144
.Lgk_loop_998:
	s_and_b32 s9, s8, 0x8000
	s_xor_b32 s12, s9, 0x8000
	s_add_i32 s13, s12, s17
	v_or_b32_e32 v167, s9, v132
	v_add_u32_e32 v110, s9, v131
	s_add_i32 m0, s13, 0x4000
	s_waitcnt lgkmcnt(6)
	v_mfma_f32_16x16x32_bf16 v[0:3], v[106:109], v[184:187], v[0:3]
	global_load_lds_dwordx4 v255, s[100:101]
	ds_read_b128 v[168:171], v167 offset:16384
	s_add_i32 m0, s13, 0x5000
	s_add_u32 s10, s100, s18
	s_addc_u32 s11, s101, 0
	s_waitcnt lgkmcnt(6)
	v_mfma_f32_16x16x32_bf16 v[4:7], v[118:121], v[184:187], v[4:7]
	global_load_lds_dwordx4 v255, s[10:11]
	ds_read_b128 v[172:175], v167 offset:16896
	s_add_i32 m0, s13, 0x6000
	s_add_u32 s10, s10, s18
	s_addc_u32 s11, s11, 0
	s_waitcnt lgkmcnt(6)
	v_mfma_f32_16x16x32_bf16 v[8:11], v[122:125], v[184:187], v[8:11]
	global_load_lds_dwordx4 v255, s[10:11]
	ds_read_b128 v[176:179], v167 offset:20480
	s_add_i32 m0, s13, 0x7000
	s_add_u32 s10, s10, s18
	s_addc_u32 s11, s11, 0
	s_waitcnt lgkmcnt(6)
	v_mfma_f32_16x16x32_bf16 v[12:15], v[158:161], v[184:187], v[12:15]
	global_load_lds_dwordx4 v255, s[10:11]
	ds_read_b128 v[180:183], v167 offset:20992
	ds_read_b128 v[184:187], v110
	s_add_u32 s100, s100, 0x80
	s_addc_u32 s101, s101, 0
	s_waitcnt lgkmcnt(7)
	v_mfma_f32_16x16x32_bf16 v[16:19], v[106:109], v[188:191], v[16:19]
	v_mfma_f32_16x16x32_bf16 v[20:23], v[118:121], v[188:191], v[20:23]
	v_mfma_f32_16x16x32_bf16 v[24:27], v[122:125], v[188:191], v[24:27]
	v_mfma_f32_16x16x32_bf16 v[28:31], v[158:161], v[188:191], v[28:31]
	ds_read_b128 v[188:191], v110 offset:2048
	s_waitcnt lgkmcnt(7)
	v_mfma_f32_16x16x32_bf16 v[32:35], v[106:109], v[246:249], v[32:35]
	v_mfma_f32_16x16x32_bf16 v[36:39], v[118:121], v[246:249], v[36:39]
	v_mfma_f32_16x16x32_bf16 v[40:43], v[122:125], v[246:249], v[40:43]
	v_mfma_f32_16x16x32_bf16 v[44:47], v[158:161], v[246:249], v[44:47]
	ds_read_b128 v[246:249], v110 offset:4096
	s_waitcnt lgkmcnt(7)
	v_mfma_f32_16x16x32_bf16 v[48:51], v[106:109], v[250:253], v[48:51]
	v_mfma_f32_16x16x32_bf16 v[52:55], v[118:121], v[250:253], v[52:55]
	v_mfma_f32_16x16x32_bf16 v[56:59], v[122:125], v[250:253], v[56:59]
	v_mfma_f32_16x16x32_bf16 v[60:63], v[158:161], v[250:253], v[60:63]
	ds_read_b128 v[250:253], v110 offset:6144
	s_waitcnt lgkmcnt(3)
	v_mfma_f32_16x16x32_bf16 v[0:3], v[168:171], v[184:187], v[0:3]
	v_mfma_f32_16x16x32_bf16 v[4:7], v[172:175], v[184:187], v[4:7]
	v_mfma_f32_16x16x32_bf16 v[8:11], v[176:179], v[184:187], v[8:11]
	v_mfma_f32_16x16x32_bf16 v[12:15], v[180:183], v[184:187], v[12:15]
	s_waitcnt lgkmcnt(2)
	v_mfma_f32_16x16x32_bf16 v[16:19], v[168:171], v[188:191], v[16:19]
	v_mfma_f32_16x16x32_bf16 v[20:23], v[172:175], v[188:191], v[20:23]
	v_mfma_f32_16x16x32_bf16 v[24:27], v[176:179], v[188:191], v[24:27]
	v_mfma_f32_16x16x32_bf16 v[28:31], v[180:183], v[188:191], v[28:31]
	s_waitcnt vmcnt(0)
	s_waitcnt lgkmcnt(0)
	s_barrier
	s_add_i32 s8, s8, 0x8000
	s_cmp_eq_u32 s8, 0x78000
	s_cbranch_scc1 .Lgk_tail_998
	v_or_b32_e32 v167, s12, v133
	v_add_u32_e32 v110, s12, v130
	s_add_i32 s13, s9, s17
	ds_read_b128 v[184:187], v110
	ds_read_b128 v[106:109], v167 offset:16384
	s_mov_b32 m0, s13
	v_mfma_f32_16x16x32_bf16 v[32:35], v[168:171], v[246:249], v[32:35]
	global_load_lds_dwordx4 v254, s[98:99]
	ds_read_b128 v[118:121], v167 offset:16896
	s_add_i32 m0, s13, 0x1000
	s_add_u32 s10, s98, s18
	s_addc_u32 s11, s99, 0
	v_mfma_f32_16x16x32_bf16 v[36:39], v[172:175], v[246:249], v[36:39]
	global_load_lds_dwordx4 v254, s[10:11]
	ds_read_b128 v[122:125], v167 offset:20480
	s_add_i32 m0, s13, 0x2000
	s_add_u32 s10, s10, s18
	s_addc_u32 s11, s11, 0
	v_mfma_f32_16x16x32_bf16 v[40:43], v[176:179], v[246:249], v[40:43]
	global_load_lds_dwordx4 v254, s[10:11]
	ds_read_b128 v[158:161], v167 offset:20992
	s_add_i32 m0, s13, 0x3000
	s_add_u32 s10, s10, s18
	s_addc_u32 s11, s11, 0
	v_mfma_f32_16x16x32_bf16 v[44:47], v[180:183], v[246:249], v[44:47]
	global_load_lds_dwordx4 v254, s[10:11]
	ds_read_b128 v[188:191], v110 offset:2048
	ds_read_b128 v[246:249], v110 offset:4096
	s_add_u32 s98, s98, 0x80
	s_addc_u32 s99, s99, 0
	v_mfma_f32_16x16x32_bf16 v[48:51], v[168:171], v[250:253], v[48:51]
	v_mfma_f32_16x16x32_bf16 v[52:55], v[172:175], v[250:253], v[52:55]
	v_mfma_f32_16x16x32_bf16 v[56:59], v[176:179], v[250:253], v[56:59]
	v_mfma_f32_16x16x32_bf16 v[60:63], v[180:183], v[250:253], v[60:63]
	ds_read_b128 v[250:253], v110 offset:6144
	s_branch .Lgk_loop_998
; __device__ __forceinline__ f32x4 mfma16(bf16x8 a, bf16x8 b, f32x4 c) { return __builtin_amdgcn_mfma_f32_16x16x32_bf16(a, b, c, 0, 0, 0); }
; template <class Epi>
; __device__ __forceinline__ void gemm_tile(const bf16_t* __restrict__ A, const bf16_t* __restrict__ Bt, int K, int row0, int col0, const Epi& epi, char* smem,
;                                           bool prefetched, bool nvalid, int nrow0, int ncol0) {
;     ...
;     for (int kt = 0; kt < nk; ++kt) {
;         const int cur = kt & 1;
;         if (kt + 1 < nk) GLDS_STAGE(cur ^ 1, pA, pB, kt + 1);
;         const char* cb = smem + cur * 2 * TILE_B;
; #pragma unroll
;         for (int ks = 0; ks < 2; ++ks) {
;             bf16x8 a[4], b[4];
; #pragma unroll
;             for (int m = 0; m < 4; ++m) a[m] = *(const bf16x8*)(cb + offA[m][ks]);
; #pragma unroll
;             for (int n = 0; n < 4; ++n) b[n] = *(const bf16x8*)(cb + offB[n][ks]);
; #pragma unroll
;             for (int m = 0; m < 4; ++m)
; #pragma unroll
;                 for (int n = 0; n < 4; ++n) acc[m][n] = mfma16(b[n], a[m], acc[m][n]);
;         }
;         asm volatile("s_waitcnt vmcnt(0)" ::: "memory");
;         __syncthreads();
;     }
;     if (nvalid) { const bf16_t* qA = A + (size_t)nrow0 * K; const bf16_t* qB = Bt + (size_t)ncol0 * K; GLDS_STAGE(0, qA, qB, 0); }
.Lgk_tail_998:
	v_mfma_f32_16x16x32_bf16 v[32:35], v[168:171], v[246:249], v[32:35]
	v_mfma_f32_16x16x32_bf16 v[36:39], v[172:175], v[246:249], v[36:39]
	v_mfma_f32_16x16x32_bf16 v[40:43], v[176:179], v[246:249], v[40:43]
	v_mfma_f32_16x16x32_bf16 v[44:47], v[180:183], v[246:249], v[44:47]
	v_mfma_f32_16x16x32_bf16 v[48:51], v[168:171], v[250:253], v[48:51]
	v_mfma_f32_16x16x32_bf16 v[52:55], v[172:175], v[250:253], v[52:55]
	v_mfma_f32_16x16x32_bf16 v[56:59], v[176:179], v[250:253], v[56:59]
	v_mfma_f32_16x16x32_bf16 v[60:63], v[180:183], v[250:253], v[60:63]
	ds_read_b128 v[106:109], v133 offset:49152
	ds_read_b128 v[118:121], v130 offset:32768
	ds_read_b128 v[122:125], v133 offset:49664
	ds_read_b128 v[158:161], v133 offset:53248
	ds_read_b128 v[168:171], v133 offset:53760
	s_add_i32 s16, s16, s58
	s_waitcnt lgkmcnt(3)
	v_mfma_f32_16x16x32_bf16 v[0:3], v[106:109], v[118:121], v[0:3]
	s_cmpk_gt_i32 s16, 0x1fff
	s_cselect_b64 s[6:7], -1, 0
	s_cmpk_lt_i32 s16, 0x2000
	s_waitcnt lgkmcnt(2)
	v_mfma_f32_16x16x32_bf16 v[4:7], v[122:125], v[118:121], v[4:7]
	ds_read_b128 v[184:187], v132 offset:49152
	ds_read_b128 v[188:191], v132 offset:53760
	s_waitcnt lgkmcnt(3)
	v_mfma_f32_16x16x32_bf16 v[8:11], v[158:161], v[118:121], v[8:11]
	s_waitcnt lgkmcnt(2)
	v_mfma_f32_16x16x32_bf16 v[12:15], v[168:171], v[118:121], v[12:15]
	ds_read_b128 v[118:121], v130 offset:34816
	s_waitcnt lgkmcnt(0)
	v_mfma_f32_16x16x32_bf16 v[16:19], v[106:109], v[118:121], v[16:19]
	v_mfma_f32_16x16x32_bf16 v[20:23], v[122:125], v[118:121], v[20:23]
	v_mfma_f32_16x16x32_bf16 v[24:27], v[158:161], v[118:121], v[24:27]
	v_mfma_f32_16x16x32_bf16 v[28:31], v[168:171], v[118:121], v[28:31]
	ds_read_b128 v[118:121], v130 offset:36864
	s_waitcnt lgkmcnt(0)
	v_mfma_f32_16x16x32_bf16 v[172:175], v[106:109], v[118:121], v[32:35]
	s_nop 2
	ds_read_b128 v[32:35], v130 offset:38912
	v_mfma_f32_16x16x32_bf16 v[176:179], v[122:125], v[118:121], v[36:39]
	v_mfma_f32_16x16x32_bf16 v[180:183], v[158:161], v[118:121], v[40:43]
	v_mfma_f32_16x16x32_bf16 v[118:121], v[168:171], v[118:121], v[44:47]
	s_waitcnt lgkmcnt(0)
	v_mfma_f32_16x16x32_bf16 v[106:109], v[106:109], v[32:35], v[48:51]
	v_mfma_f32_16x16x32_bf16 v[122:125], v[122:125], v[32:35], v[52:55]
	v_mfma_f32_16x16x32_bf16 v[158:161], v[158:161], v[32:35], v[56:59]
	v_mfma_f32_16x16x32_bf16 v[168:171], v[168:171], v[32:35], v[60:63]
	ds_read_b128 v[32:35], v131 offset:32768
	s_waitcnt lgkmcnt(0)
	v_mfma_f32_16x16x32_bf16 v[56:59], v[184:187], v[32:35], v[0:3]
	s_nop 2
	ds_read_b128 v[0:3], v132 offset:49664
	s_waitcnt lgkmcnt(0)
	v_mfma_f32_16x16x32_bf16 v[60:63], v[0:3], v[32:35], v[4:7]
	s_nop 2
	ds_read_b128 v[4:7], v132 offset:53248
	s_waitcnt lgkmcnt(0)
	v_mfma_f32_16x16x32_bf16 v[48:51], v[4:7], v[32:35], v[8:11]
	s_nop 2
	ds_read_b128 v[8:11], v131 offset:34816
	v_mfma_f32_16x16x32_bf16 v[52:55], v[188:191], v[32:35], v[12:15]
	s_waitcnt lgkmcnt(0)
	v_mfma_f32_16x16x32_bf16 v[44:47], v[184:187], v[8:11], v[16:19]
	v_mfma_f32_16x16x32_bf16 v[40:43], v[0:3], v[8:11], v[20:23]
	v_mfma_f32_16x16x32_bf16 v[36:39], v[4:7], v[8:11], v[24:27]
	v_mfma_f32_16x16x32_bf16 v[32:35], v[188:191], v[8:11], v[28:31]
	ds_read_b128 v[8:11], v131 offset:36864
	s_waitcnt lgkmcnt(0)
	v_mfma_f32_16x16x32_bf16 v[16:19], v[188:191], v[8:11], v[118:121]
	s_nop 2
	ds_read_b128 v[118:121], v131 offset:38912
	s_waitcnt vmcnt(0)
	v_mfma_f32_16x16x32_bf16 v[28:31], v[184:187], v[8:11], v[172:175]
	s_waitcnt lgkmcnt(0)
	s_barrier
	v_mfma_f32_16x16x32_bf16 v[24:27], v[0:3], v[8:11], v[176:179]
	v_mfma_f32_16x16x32_bf16 v[20:23], v[4:7], v[8:11], v[180:183]
	v_mfma_f32_16x16x32_bf16 v[8:11], v[184:187], v[118:121], v[106:109]
	v_mfma_f32_16x16x32_bf16 v[12:15], v[0:3], v[118:121], v[122:125]
	v_mfma_f32_16x16x32_bf16 v[0:3], v[4:7], v[118:121], v[158:161]
	v_mfma_f32_16x16x32_bf16 v[4:7], v[188:191], v[118:121], v[168:171]
	s_cbranch_scc0 .LBB0_992
	s_ashr_i32 s8, s16, 31
	s_lshr_b32 s8, s8, 27
	s_add_i32 s9, s16, s8
	s_lshl_b32 s8, s9, 2
	s_and_b32 s9, s9, 0x1ffffe0
	s_and_b32 s8, s8, 0xffffff80
	s_sub_i32 s9, s16, s9
	s_lshl_b32 s10, s9, 7
	s_ashr_i32 s9, s8, 31
	s_lshl_b64 s[8:9], s[8:9], 11
	v_readlane_b32 s11, v245, 53
	s_add_u32 s8, s11, s8
	v_readlane_b32 s11, v245, 54
	s_addc_u32 s9, s11, s9
	s_ashr_i32 s11, s10, 31
	s_lshl_b64 s[10:11], s[10:11], 11
	s_add_u32 s10, s14, s10
	v_readfirstlane_b32 s12, v149
	s_addc_u32 s11, s15, s11
	s_mov_b32 m0, s12
	v_readfirstlane_b32 s12, v134
	global_load_lds_dwordx4 v143, s[8:9]
	v_lshl_add_u64 v[106:107], v[64:65], 1, s[10:11]
	s_mov_b32 m0, s12
	v_readfirstlane_b32 s12, v135
	global_load_lds_dwordx4 v[106:107], off
	s_mov_b32 m0, s12
	v_readfirstlane_b32 s12, v136
	global_load_lds_dwordx4 v144, s[8:9]
	v_lshl_add_u64 v[106:107], v[66:67], 1, s[10:11]
	s_mov_b32 m0, s12
	v_readfirstlane_b32 s12, v137
	global_load_lds_dwordx4 v[106:107], off
	s_mov_b32 m0, s12
	v_readfirstlane_b32 s12, v138
	global_load_lds_dwordx4 v145, s[8:9]
	v_lshl_add_u64 v[106:107], v[68:69], 1, s[10:11]
	s_mov_b32 m0, s12
	v_readfirstlane_b32 s12, v139
	global_load_lds_dwordx4 v[106:107], off
	s_mov_b32 m0, s12
	v_lshl_add_u64 v[106:107], v[70:71], 1, s[10:11]
	global_load_lds_dwordx4 v157, s[8:9]
	v_readfirstlane_b32 s8, v140
	s_mov_b32 m0, s8
	s_nop 0
	global_load_lds_dwordx4 v[106:107], off
	s_branch .LBB0_992

; __device__ __forceinline__ f32x4 mfma16(bf16x8 a, bf16x8 b, f32x4 c) { return __builtin_amdgcn_mfma_f32_16x16x32_bf16(a, b, c, 0, 0, 0); }
; template <class Epi>
; __device__ __forceinline__ void gemm_tile(const bf16_t* __restrict__ A, const bf16_t* __restrict__ Bt, int K, int row0, int col0, const Epi& epi, char* smem,
;                                           bool prefetched, bool nvalid, int nrow0, int ncol0) {
;     ...
;     for (int kt = 0; kt < nk; ++kt) {
;         const int cur = kt & 1;
;         if (kt + 1 < nk) GLDS_STAGE(cur ^ 1, pA, pB, kt + 1);
;         const char* cb = smem + cur * 2 * TILE_B;
; #pragma unroll
;         for (int ks = 0; ks < 2; ++ks) {
;             bf16x8 a[4], b[4];
; #pragma unroll
;             for (int m = 0; m < 4; ++m) a[m] = *(const bf16x8*)(cb + offA[m][ks]);
; #pragma unroll
;             for (int n = 0; n < 4; ++n) b[n] = *(const bf16x8*)(cb + offB[n][ks]);
; #pragma unroll
;             for (int m = 0; m < 4; ++m)
; #pragma unroll
;                 for (int n = 0; n < 4; ++n) acc[m][n] = mfma16(b[n], a[m], acc[m][n]);
;         }
;         asm volatile("s_waitcnt vmcnt(0)" ::: "memory");
;         __syncthreads();
;     }
.LBB0_1054:
	v_readfirstlane_b32 s98, v92
	v_readfirstlane_b32 s99, v93
	v_readfirstlane_b32 s6, v94
	v_readfirstlane_b32 s100, v100
	v_readfirstlane_b32 s101, v101
	v_readfirstlane_b32 s10, v149
	s_nop 3
	s_sub_u32 s11, s6, s98
	s_and_b32 s98, s98, 0xffffff80
	s_and_b32 s100, s100, 0xffffff80
	s_nop 1
	v_subrev_u32_e32 v254, s98, v92
	v_subrev_u32_e32 v255, s100, v100
	s_add_i32 s9, s10, 0x8000
	s_mov_b32 m0, s9
	s_nop 1
	global_load_lds_dwordx4 v254, s[98:99]
	s_add_i32 m0, s9, 0x1000
	s_add_u32 s6, s98, s11
	s_addc_u32 s7, s99, 0
	global_load_lds_dwordx4 v254, s[6:7]
	s_add_i32 m0, s9, 0x2000
	s_add_u32 s6, s6, s11
	s_addc_u32 s7, s7, 0
	global_load_lds_dwordx4 v254, s[6:7]
	s_add_i32 m0, s9, 0x3000
	s_add_u32 s6, s6, s11
	s_addc_u32 s7, s7, 0
	global_load_lds_dwordx4 v254, s[6:7]
	s_add_u32 s98, s98, 0x80
	s_addc_u32 s99, s99, 0
	ds_read_b128 v[150:153], v108
	ds_read_b128 v[92:95], v110 offset:16384
	ds_read_b128 v[96:99], v110 offset:16896
	ds_read_b128 v[100:103], v110 offset:20480
	ds_read_b128 v[104:107], v110 offset:20992
	ds_read_b128 v[154:157], v108 offset:2048
	ds_read_b128 v[246:249], v108 offset:4096
	ds_read_b128 v[250:253], v108 offset:6144
.Lgk_loop_1054:
	s_and_b32 s3, s1, 0x8000
	s_xor_b32 s8, s3, 0x8000
	s_add_i32 s9, s8, s10
	v_or_b32_e32 v127, s3, v111
	v_add_u32_e32 v144, s3, v109
	s_add_i32 m0, s9, 0x4000
	s_waitcnt lgkmcnt(6)
	v_mfma_f32_16x16x32_bf16 v[0:3], v[92:95], v[150:153], v[0:3]
	global_load_lds_dwordx4 v255, s[100:101]
	ds_read_b128 v[128:131], v127 offset:16384
	s_add_i32 m0, s9, 0x5000
	s_add_u32 s6, s100, s11
	s_addc_u32 s7, s101, 0
	s_waitcnt lgkmcnt(6)
	v_mfma_f32_16x16x32_bf16 v[4:7], v[96:99], v[150:153], v[4:7]
	global_load_lds_dwordx4 v255, s[6:7]
	ds_read_b128 v[132:135], v127 offset:16896
	s_add_i32 m0, s9, 0x6000
	s_add_u32 s6, s6, s11
	s_addc_u32 s7, s7, 0
	s_waitcnt lgkmcnt(6)
	v_mfma_f32_16x16x32_bf16 v[8:11], v[100:103], v[150:153], v[8:11]
	global_load_lds_dwordx4 v255, s[6:7]
	ds_read_b128 v[136:139], v127 offset:20480
	s_add_i32 m0, s9, 0x7000
	s_add_u32 s6, s6, s11
	s_addc_u32 s7, s7, 0
	s_waitcnt lgkmcnt(6)
	v_mfma_f32_16x16x32_bf16 v[12:15], v[104:107], v[150:153], v[12:15]
	global_load_lds_dwordx4 v255, s[6:7]
	ds_read_b128 v[140:143], v127 offset:20992
	ds_read_b128 v[150:153], v144
	s_add_u32 s100, s100, 0x80
	s_addc_u32 s101, s101, 0
	s_waitcnt lgkmcnt(7)
	v_mfma_f32_16x16x32_bf16 v[16:19], v[92:95], v[154:157], v[16:19]
	v_mfma_f32_16x16x32_bf16 v[20:23], v[96:99], v[154:157], v[20:23]
	v_mfma_f32_16x16x32_bf16 v[24:27], v[100:103], v[154:157], v[24:27]
	v_mfma_f32_16x16x32_bf16 v[28:31], v[104:107], v[154:157], v[28:31]
	ds_read_b128 v[154:157], v144 offset:2048
	s_waitcnt lgkmcnt(7)
	v_mfma_f32_16x16x32_bf16 v[32:35], v[92:95], v[246:249], v[32:35]
	v_mfma_f32_16x16x32_bf16 v[36:39], v[96:99], v[246:249], v[36:39]
	v_mfma_f32_16x16x32_bf16 v[40:43], v[100:103], v[246:249], v[40:43]
	v_mfma_f32_16x16x32_bf16 v[44:47], v[104:107], v[246:249], v[44:47]
	ds_read_b128 v[246:249], v144 offset:4096
	s_waitcnt lgkmcnt(7)
	v_mfma_f32_16x16x32_bf16 v[48:51], v[92:95], v[250:253], v[48:51]
	v_mfma_f32_16x16x32_bf16 v[52:55], v[96:99], v[250:253], v[52:55]
	v_mfma_f32_16x16x32_bf16 v[56:59], v[100:103], v[250:253], v[56:59]
	v_mfma_f32_16x16x32_bf16 v[60:63], v[104:107], v[250:253], v[60:63]
	ds_read_b128 v[250:253], v144 offset:6144
	s_waitcnt lgkmcnt(3)
	v_mfma_f32_16x16x32_bf16 v[0:3], v[128:131], v[150:153], v[0:3]
	v_mfma_f32_16x16x32_bf16 v[4:7], v[132:135], v[150:153], v[4:7]
	v_mfma_f32_16x16x32_bf16 v[8:11], v[136:139], v[150:153], v[8:11]
	v_mfma_f32_16x16x32_bf16 v[12:15], v[140:143], v[150:153], v[12:15]
	s_waitcnt lgkmcnt(2)
	v_mfma_f32_16x16x32_bf16 v[16:19], v[128:131], v[154:157], v[16:19]
	v_mfma_f32_16x16x32_bf16 v[20:23], v[132:135], v[154:157], v[20:23]
	v_mfma_f32_16x16x32_bf16 v[24:27], v[136:139], v[154:157], v[24:27]
	v_mfma_f32_16x16x32_bf16 v[28:31], v[140:143], v[154:157], v[28:31]
	s_waitcnt vmcnt(0)
	s_waitcnt lgkmcnt(0)
	s_barrier
	s_add_i32 s1, s1, 0x8000
	s_cmp_eq_u32 s1, 0x1f8000
	s_cbranch_scc1 .Lgk_tail_1054
	v_or_b32_e32 v127, s8, v110
	v_add_u32_e32 v144, s8, v108
	s_add_i32 s9, s3, s10
	ds_read_b128 v[150:153], v144
	ds_read_b128 v[92:95], v127 offset:16384
	s_mov_b32 m0, s9
	v_mfma_f32_16x16x32_bf16 v[32:35], v[128:131], v[246:249], v[32:35]
	global_load_lds_dwordx4 v254, s[98:99]
	ds_read_b128 v[96:99], v127 offset:16896
	s_add_i32 m0, s9, 0x1000
	s_add_u32 s6, s98, s11
	s_addc_u32 s7, s99, 0
	v_mfma_f32_16x16x32_bf16 v[36:39], v[132:135], v[246:249], v[36:39]
	global_load_lds_dwordx4 v254, s[6:7]
	ds_read_b128 v[100:103], v127 offset:20480
	s_add_i32 m0, s9, 0x2000
	s_add_u32 s6, s6, s11
	s_addc_u32 s7, s7, 0
	v_mfma_f32_16x16x32_bf16 v[40:43], v[136:139], v[246:249], v[40:43]
	global_load_lds_dwordx4 v254, s[6:7]
	ds_read_b128 v[104:107], v127 offset:20992
	s_add_i32 m0, s9, 0x3000
	s_add_u32 s6, s6, s11
	s_addc_u32 s7, s7, 0
	v_mfma_f32_16x16x32_bf16 v[44:47], v[140:143], v[246:249], v[44:47]
	global_load_lds_dwordx4 v254, s[6:7]
	ds_read_b128 v[154:157], v144 offset:2048
	ds_read_b128 v[246:249], v144 offset:4096
	s_add_u32 s98, s98, 0x80
	s_addc_u32 s99, s99, 0
	v_mfma_f32_16x16x32_bf16 v[48:51], v[128:131], v[250:253], v[48:51]
	v_mfma_f32_16x16x32_bf16 v[52:55], v[132:135], v[250:253], v[52:55]
	v_mfma_f32_16x16x32_bf16 v[56:59], v[136:139], v[250:253], v[56:59]
	v_mfma_f32_16x16x32_bf16 v[60:63], v[140:143], v[250:253], v[60:63]
	ds_read_b128 v[250:253], v144 offset:6144
	s_branch .Lgk_loop_1054
; __device__ __forceinline__ f32x4 mfma16(bf16x8 a, bf16x8 b, f32x4 c) { return __builtin_amdgcn_mfma_f32_16x16x32_bf16(a, b, c, 0, 0, 0); }
; template <class Epi>
; __device__ __forceinline__ void gemm_tile(const bf16_t* __restrict__ A, const bf16_t* __restrict__ Bt, int K, int row0, int col0, const Epi& epi, char* smem,
;                                           bool prefetched, bool nvalid, int nrow0, int ncol0) {
;     ...
;     for (int kt = 0; kt < nk; ++kt) {
;         const int cur = kt & 1;
;         if (kt + 1 < nk) GLDS_STAGE(cur ^ 1, pA, pB, kt + 1);
;         const char* cb = smem + cur * 2 * TILE_B;
; #pragma unroll
;         for (int ks = 0; ks < 2; ++ks) {
;             bf16x8 a[4], b[4];
; #pragma unroll
;             for (int m = 0; m < 4; ++m) a[m] = *(const bf16x8*)(cb + offA[m][ks]);
; #pragma unroll
;             for (int n = 0; n < 4; ++n) b[n] = *(const bf16x8*)(cb + offB[n][ks]);
; #pragma unroll
;             for (int m = 0; m < 4; ++m)
; #pragma unroll
;                 for (int n = 0; n < 4; ++n) acc[m][n] = mfma16(b[n], a[m], acc[m][n]);
;         }
;         asm volatile("s_waitcnt vmcnt(0)" ::: "memory");
;         __syncthreads();
;     }
;     if (nvalid) { const bf16_t* qA = A + (size_t)nrow0 * K; const bf16_t* qB = Bt + (size_t)ncol0 * K; GLDS_STAGE(0, qA, qB, 0); }
.Lgk_tail_1054:
	v_mfma_f32_16x16x32_bf16 v[32:35], v[128:131], v[246:249], v[32:35]
	v_mfma_f32_16x16x32_bf16 v[36:39], v[132:135], v[246:249], v[36:39]
	v_mfma_f32_16x16x32_bf16 v[40:43], v[136:139], v[246:249], v[40:43]
	v_mfma_f32_16x16x32_bf16 v[44:47], v[140:143], v[246:249], v[44:47]
	v_mfma_f32_16x16x32_bf16 v[48:51], v[128:131], v[250:253], v[48:51]
	v_mfma_f32_16x16x32_bf16 v[52:55], v[132:135], v[250:253], v[52:55]
	v_mfma_f32_16x16x32_bf16 v[56:59], v[136:139], v[250:253], v[56:59]
	v_mfma_f32_16x16x32_bf16 v[60:63], v[140:143], v[250:253], v[60:63]
	ds_read_b128 v[92:95], v110 offset:49152
	ds_read_b128 v[96:99], v110 offset:49664
	ds_read_b128 v[100:103], v108 offset:32768
	ds_read_b128 v[104:107], v108 offset:34816
	ds_read_b128 v[128:131], v110 offset:53248
	ds_read_b128 v[132:135], v110 offset:53760
	s_add_i32 s16, s16, s58
	s_waitcnt lgkmcnt(3)
	v_mfma_f32_16x16x32_bf16 v[0:3], v[92:95], v[100:103], v[0:3]
	s_cmpk_gt_i32 s16, 0x7ff
	s_cselect_b64 s[4:5], -1, 0
	s_cmpk_lt_i32 s16, 0x800
	v_mfma_f32_16x16x32_bf16 v[4:7], v[96:99], v[100:103], v[4:7]
	s_waitcnt lgkmcnt(1)
	v_mfma_f32_16x16x32_bf16 v[8:11], v[128:131], v[100:103], v[8:11]
	s_waitcnt lgkmcnt(0)
	v_mfma_f32_16x16x32_bf16 v[12:15], v[132:135], v[100:103], v[12:15]
	v_mfma_f32_16x16x32_bf16 v[16:19], v[92:95], v[104:107], v[16:19]
	v_mfma_f32_16x16x32_bf16 v[20:23], v[96:99], v[104:107], v[20:23]
	v_mfma_f32_16x16x32_bf16 v[24:27], v[128:131], v[104:107], v[24:27]
	v_mfma_f32_16x16x32_bf16 v[28:31], v[132:135], v[104:107], v[28:31]
	ds_read_b128 v[100:103], v108 offset:36864
	ds_read_b128 v[104:107], v108 offset:38912
	ds_read_b128 v[154:157], v111 offset:49152
	s_waitcnt lgkmcnt(2)
	v_mfma_f32_16x16x32_bf16 v[136:139], v[92:95], v[100:103], v[32:35]
	v_mfma_f32_16x16x32_bf16 v[140:143], v[96:99], v[100:103], v[36:39]
	v_mfma_f32_16x16x32_bf16 v[150:153], v[128:131], v[100:103], v[40:43]
	v_mfma_f32_16x16x32_bf16 v[100:103], v[132:135], v[100:103], v[44:47]
	s_waitcnt lgkmcnt(1)
	v_mfma_f32_16x16x32_bf16 v[92:95], v[92:95], v[104:107], v[48:51]
	v_mfma_f32_16x16x32_bf16 v[96:99], v[96:99], v[104:107], v[52:55]
	v_mfma_f32_16x16x32_bf16 v[128:131], v[128:131], v[104:107], v[56:59]
	v_mfma_f32_16x16x32_bf16 v[104:107], v[132:135], v[104:107], v[60:63]
	ds_read_b128 v[132:135], v111 offset:49664
	ds_read_b128 v[32:35], v109 offset:32768
	ds_read_b128 v[36:39], v109 offset:34816
	ds_read_b128 v[158:161], v111 offset:53760
	s_waitcnt lgkmcnt(2)
	v_mfma_f32_16x16x32_bf16 v[52:55], v[154:157], v[32:35], v[0:3]
	s_nop 2
	ds_read_b128 v[0:3], v111 offset:53248
	v_mfma_f32_16x16x32_bf16 v[56:59], v[132:135], v[32:35], v[4:7]
	s_nop 2
	ds_read_b128 v[4:7], v109 offset:36864
	ds_read_b128 v[168:171], v109 offset:38912
	s_waitcnt vmcnt(0)
	s_waitcnt lgkmcnt(0)
	v_mfma_f32_16x16x32_bf16 v[60:63], v[0:3], v[32:35], v[8:11]
	s_barrier
	v_mfma_f32_16x16x32_bf16 v[48:51], v[158:161], v[32:35], v[12:15]
	v_mfma_f32_16x16x32_bf16 v[44:47], v[154:157], v[36:39], v[16:19]
	v_mfma_f32_16x16x32_bf16 v[40:43], v[132:135], v[36:39], v[20:23]
	v_mfma_f32_16x16x32_bf16 v[32:35], v[0:3], v[36:39], v[24:27]
	v_mfma_f32_16x16x32_bf16 v[24:27], v[158:161], v[36:39], v[28:31]
	v_mfma_f32_16x16x32_bf16 v[36:39], v[154:157], v[4:7], v[136:139]
	v_mfma_f32_16x16x32_bf16 v[28:31], v[132:135], v[4:7], v[140:143]
	v_mfma_f32_16x16x32_bf16 v[20:23], v[0:3], v[4:7], v[150:153]
	v_mfma_f32_16x16x32_bf16 v[16:19], v[158:161], v[4:7], v[100:103]
	v_mfma_f32_16x16x32_bf16 v[12:15], v[154:157], v[168:171], v[92:95]
	v_mfma_f32_16x16x32_bf16 v[8:11], v[132:135], v[168:171], v[96:99]
	v_mfma_f32_16x16x32_bf16 v[4:7], v[0:3], v[168:171], v[128:131]
	v_mfma_f32_16x16x32_bf16 v[0:3], v[158:161], v[168:171], v[104:107]
	s_cbranch_scc0 .LBB0_1048
	s_ashr_i32 s1, s16, 31
	s_lshr_b32 s1, s1, 29
	s_add_i32 s1, s16, s1
	s_lshl_b32 s3, s1, 4
	s_and_b32 s6, s3, 0xffffff80
	s_and_b32 s1, s1, 0x1fffff8
	s_sub_i32 s1, s16, s1
	s_ashr_i32 s7, s6, 31
	s_lshl_b32 s8, s1, 7
	s_lshl_b64 s[6:7], s[6:7], 13
	v_readlane_b32 s10, v245, 55
	v_readlane_b32 s11, v245, 56
	s_add_u32 s6, s10, s6
	s_addc_u32 s7, s11, s7
	s_ashr_i32 s9, s8, 31
	s_lshl_b64 s[8:9], s[8:9], 13
	s_add_u32 s8, s12, s8
	v_readfirstlane_b32 s1, v149
	s_addc_u32 s9, s13, s9
	s_mov_b32 m0, s1
	v_readfirstlane_b32 s1, v114
	global_load_lds_dwordx4 v123, s[6:7]
	v_lshl_add_u64 v[92:93], v[64:65], 1, s[8:9]
	s_mov_b32 m0, s1
	v_readfirstlane_b32 s1, v116
	global_load_lds_dwordx4 v[92:93], off
	s_mov_b32 m0, s1
	v_readfirstlane_b32 s1, v118
	global_load_lds_dwordx4 v124, s[6:7]
	v_lshl_add_u64 v[92:93], v[66:67], 1, s[8:9]
	s_mov_b32 m0, s1
	v_readfirstlane_b32 s1, v119
	global_load_lds_dwordx4 v[92:93], off
	s_mov_b32 m0, s1
	v_readfirstlane_b32 s1, v120
	global_load_lds_dwordx4 v125, s[6:7]
	v_lshl_add_u64 v[92:93], v[68:69], 1, s[8:9]
	s_mov_b32 m0, s1
	v_readfirstlane_b32 s1, v121
	global_load_lds_dwordx4 v[92:93], off
	s_mov_b32 m0, s1
	v_readfirstlane_b32 s1, v122
	global_load_lds_dwordx4 v126, s[6:7]
	v_lshl_add_u64 v[92:93], v[70:71], 1, s[8:9]
	s_mov_b32 m0, s1
	s_nop 0
	global_load_lds_dwordx4 v[92:93], off
	s_branch .LBB0_1048

; __global__ void __launch_bounds__(256, 2) fwd_megakernel(Params p) {
;     __shared__ __attribute__((aligned(16))) char smem[SMEM_BYTES];
	.amdhsa_kernel _Z14fwd_megakernel6Params
		.amdhsa_group_segment_fixed_size 73744
		.amdhsa_private_segment_fixed_size 0
		.amdhsa_kernarg_size 440
		.amdhsa_user_sgpr_count 2
		.amdhsa_user_sgpr_dispatch_ptr 0
		.amdhsa_user_sgpr_queue_ptr 0
		.amdhsa_user_sgpr_kernarg_segment_ptr 1
		.amdhsa_user_sgpr_dispatch_id 0
		.amdhsa_user_sgpr_kernarg_preload_length 0
		.amdhsa_user_sgpr_kernarg_preload_offset 0
		.amdhsa_user_sgpr_private_segment_size 0
		.amdhsa_uses_dynamic_stack 0
		.amdhsa_enable_private_segment 0
		.amdhsa_system_sgpr_workgroup_id_x 1
		.amdhsa_system_sgpr_workgroup_id_y 0
		.amdhsa_system_sgpr_workgroup_id_z 0
		.amdhsa_system_sgpr_workgroup_info 0
		.amdhsa_system_vgpr_workitem_id 2
		.amdhsa_next_free_vgpr 256
		.amdhsa_next_free_sgpr 102
		.amdhsa_accum_offset 256
		.amdhsa_reserve_vcc 1
		.amdhsa_float_round_mode_32 0
		.amdhsa_float_round_mode_16_64 0
		.amdhsa_float_denorm_mode_32 3
		.amdhsa_float_denorm_mode_16_64 3
		.amdhsa_dx10_clamp 1
		.amdhsa_ieee_mode 1
		.amdhsa_fp16_overflow 0
		.amdhsa_tg_split 0
		.amdhsa_exception_fp_ieee_invalid_op 0
		.amdhsa_exception_fp_denorm_src 0
		.amdhsa_exception_fp_ieee_div_zero 0
		.amdhsa_exception_fp_ieee_overflow 0
		.amdhsa_exception_fp_ieee_underflow 0
		.amdhsa_exception_fp_ieee_inexact 0
		.amdhsa_exception_int_div_zero 0
	.end_amdhsa_kernel

; __global__ void __launch_bounds__(256, 2) fwd_megakernel(Params p) {
;     __shared__ __attribute__((aligned(16))) char smem[SMEM_BYTES];
amdhsa.kernels:
  - .agpr_count:     0
    .args:
      - .offset:         0
        .size:           184
        .value_kind:     by_value
      - .offset:         184
        .size:           4
        .value_kind:     hidden_block_count_x
      - .offset:         188
        .size:           4
        .value_kind:     hidden_block_count_y
      - .offset:         192
        .size:           4
        .value_kind:     hidden_block_count_z
      - .offset:         196
        .size:           2
        .value_kind:     hidden_group_size_x
      - .offset:         198
        .size:           2
        .value_kind:     hidden_group_size_y
      - .offset:         200
        .size:           2
        .value_kind:     hidden_group_size_z
      - .offset:         202
        .size:           2
        .value_kind:     hidden_remainder_x
      - .offset:         204
        .size:           2
        .value_kind:     hidden_remainder_y
      - .offset:         206
        .size:           2
        .value_kind:     hidden_remainder_z
      - .offset:         224
        .size:           8
        .value_kind:     hidden_global_offset_x
      - .offset:         232
        .size:           8
        .value_kind:     hidden_global_offset_y
      - .offset:         240
        .size:           8
        .value_kind:     hidden_global_offset_z
      - .offset:         248
        .size:           2
        .value_kind:     hidden_grid_dims
      - .offset:         272
        .size:           8
        .value_kind:     hidden_multigrid_sync_arg
    .group_segment_fixed_size: 73744
    .kernarg_segment_align: 8
    .kernarg_segment_size: 440
    .language:       OpenCL C
    .language_version:
      - 2
      - 0
    .max_flat_workgroup_size: 256
    .name:           _Z14fwd_megakernel6Params
    .private_segment_fixed_size: 0
    .sgpr_count:     108
    .sgpr_spill_count: 129
    .symbol:         _Z14fwd_megakernel6Params.kd
    .uniform_work_group_size: 1
    .uses_dynamic_stack: false
    .vgpr_count:     256
    .vgpr_spill_count: 0
    .wavefront_size: 64
